# v33 + K-loops: last 4 of the 6 LDS-DMA issues of each SP2 load segment moved into the wave's own following MFMA block (counted wait 8->4)
# speedup vs baseline: 1.0157x; 1.0157x over previous
; #define PG8_STAGE(bufoff, gbase, voff) do { _Pragma("unroll") for (int _i = 0; _i < 2; ++_i) \
;         __builtin_amdgcn_global_load_lds((const unsigned*)((const char*)(gbase) + (voff)[_i]), (PG8_LAS unsigned*)(lds + (bufoff) + ldsw + _i * 8192), 16, 0, 0); } while (0)
; #define PG8_LDA(dst, b, h) do { _Pragma("unroll") for (int m = 0; m < 4; ++m) _Pragma("unroll") for (int k = 0; k < 2; ++k) dst[m][k] = *(const PG8_LAS bf16x8*)(lds + PG8_SA(b, h) + aoff + m * 2048 + k * 1024); } while (0)
; #define PG8_LDB(dst, b, h) do { _Pragma("unroll") for (int n = 0; n < 2; ++n) _Pragma("unroll") for (int k = 0; k < 2; ++k) dst[n][k] = *(const PG8_LAS bf16x8*)(lds + PG8_SB(b, h) + boff + n * 2048 + k * 1024); } while (0)
; #define PG8_MMA(ai, bj, At, Bt) do { __builtin_amdgcn_s_setprio(1); _Pragma("unroll") for (int m = 0; m < 4; ++m) _Pragma("unroll") for (int n = 0; n < 2; ++n) _Pragma("unroll") for (int k = 0; k < 2; ++k) \
;         acc[ai][bj][m][n] = __builtin_amdgcn_mfma_f32_16x16x32_bf16(Bt[n][k], At[m][k], acc[ai][bj][m][n], 0, 0, 0); __builtin_amdgcn_s_setprio(0); } while (0)
; template <class Epi, class Sched, bool ALIGN_EPI = false, bool SP2 = false, bool AGM = false  >
; __device__ __forceinline__ void gemm_phase(PG8_LAS unsigned char* lds, const Gemm g, const Sched& S, const Epi& E) {
;     ...
;         const bool has_next = S.next(ui + 1, nxt);
;         const char* nA = has_next ? (const char*)g.A + (size_t)nxt.pm * tstepA : cA; const char* nB = has_next ? (const char*)g.Bt + (size_t)nxt.pn * tstep : cB;
;         for (int t = 0; t < nt; t += 2) {
;             const bool last = (t == nt - 2);
;             const char* a1 = cA + (size_t)(t + 1) * kstepA;
;             const char* a2 = last ? nA : cA + (size_t)(t + 2) * kstepA; const char* b2 = last ? nB : cB + (size_t)(t + 2) * kstep;
;             const char* a3 = a2 + kstepA; const char* b3 = b2 + kstep;
;             if (last && has_next) S.a_ready(nxt);
;             if constexpr (SP2) {
;             PG8_LDB(B0, 0, 0); PG8_LDB(B1, 0, 1); PG8_SCHED; PG8_LDA(At, 0, 0); PG8_STAGE(PG8_SA(1, 1), a1 + hstepA, voffA);
;             PG8_WAIT_V(8); PG8_WAIT_L(0); PG8_BAR; PG8_MMA(0, 0, At, B0); PG8_MMA(0, 1, At, B1); PG8_BAR; PG8_SCHED;
;             PG8_LDA(At, 0, 1); PG8_STAGE(PG8_SB(0, 0), b2, voffB); PG8_STAGE(PG8_SB(0, 1), b2 + hstep, voffB); PG8_STAGE(PG8_SA(0, 0), a2, voffA);
.LBB0_136:
	s_ashr_i32 s15, s14, 31
	s_lshl_b64 s[16:17], s[14:15], 19
	s_add_u32 s16, s46, s16
	s_addc_u32 s17, s47, s17
	s_and_b64 s[18:19], s[0:1], exec
	s_cselect_b32 s15, s17, s23
	s_cselect_b32 s21, s16, s22
	s_ashr_i32 s13, s12, 31
	s_lshl_b64 s[18:19], s[12:13], 19
	s_add_u32 s18, s3, s18
	s_addc_u32 s19, s28, s19
	s_and_b64 s[26:27], s[0:1], exec
	s_cselect_b32 s13, s19, s25
	s_cselect_b32 s45, s18, s24
	s_add_u32 s22, s22, 0x40080
	s_addc_u32 s23, s23, 0
	s_add_u32 s53, s24, 0x100
	s_addc_u32 s54, s25, 0
	s_mov_b32 s55, -2
	ds_read_b128 v[150:153], v160
	ds_read_b128 v[164:167], v160 offset:1024
	ds_read_b128 v[168:171], v160 offset:2048
	ds_read_b128 v[172:175], v160 offset:3072
	ds_read_b128 v[176:179], v161
	ds_read_b128 v[180:183], v161 offset:1024
	ds_read_b128 v[184:187], v161 offset:2048
	ds_read_b128 v[188:191], v161 offset:3072
	s_add_u32 s24, s22, 0xfffc0080
	s_addc_u32 s25, s23, -1
	s_cmp_eq_u32 s55, 12
	s_cselect_b32 s27, s15, s25
	s_cselect_b32 s26, s21, s24
	s_cselect_b32 s25, s13, s54
	s_cselect_b32 s24, s45, s53
	v_lshl_add_u64 v[224:225], s[22:23], 0, v[142:143]
	s_add_i32 m0, s33, 0xc000
	ds_read_b128 v[192:195], v162
	ds_read_b128 v[196:199], v162 offset:1024
	ds_read_b128 v[200:203], v162 offset:2048
	ds_read_b128 v[204:207], v162 offset:3072
	ds_read_b128 v[208:211], v162 offset:4096
	ds_read_b128 v[212:215], v162 offset:5120
	ds_read_b128 v[216:219], v162 offset:6144
	ds_read_b128 v[220:223], v162 offset:7168
	global_load_lds_dwordx4 v[224:225], off
	v_lshl_add_u64 v[224:225], s[22:23], 0, v[144:145]
	s_add_i32 m0, s33, 0xe000
	s_nop 0
	global_load_lds_dwordx4 v[224:225], off
	s_waitcnt vmcnt(8)
	s_waitcnt lgkmcnt(0)
	s_barrier
	s_setprio 1
	s_waitcnt lgkmcnt(0)
	v_mfma_f32_16x16x32_bf16 v[126:129], v[150:153], v[192:195], 0
	v_mfma_f32_16x16x32_bf16 v[122:125], v[168:171], v[192:195], 0
	v_mfma_f32_16x16x32_bf16 v[114:117], v[150:153], v[200:203], 0
	v_mfma_f32_16x16x32_bf16 v[106:109], v[168:171], v[200:203], 0
	v_mfma_f32_16x16x32_bf16 v[102:105], v[150:153], v[208:211], 0
	v_mfma_f32_16x16x32_bf16 v[94:97], v[168:171], v[208:211], 0
	v_mfma_f32_16x16x32_bf16 v[86:89], v[150:153], v[216:219], 0
	v_mfma_f32_16x16x32_bf16 v[78:81], v[168:171], v[216:219], 0
	v_mfma_f32_16x16x32_bf16 v[126:129], v[164:167], v[196:199], v[126:129]
	v_mfma_f32_16x16x32_bf16 v[122:125], v[172:175], v[196:199], v[122:125]
	v_mfma_f32_16x16x32_bf16 v[114:117], v[164:167], v[204:207], v[114:117]
	v_mfma_f32_16x16x32_bf16 v[106:109], v[172:175], v[204:207], v[106:109]
	v_mfma_f32_16x16x32_bf16 v[102:105], v[164:167], v[212:215], v[102:105]
	v_mfma_f32_16x16x32_bf16 v[94:97], v[172:175], v[212:215], v[94:97]
	v_mfma_f32_16x16x32_bf16 v[86:89], v[164:167], v[220:223], v[86:89]
	v_mfma_f32_16x16x32_bf16 v[78:81], v[172:175], v[220:223], v[78:81]
	s_setprio 0
	s_setprio 1
	v_mfma_f32_16x16x32_bf16 v[118:121], v[176:179], v[192:195], 0
	v_mfma_f32_16x16x32_bf16 v[110:113], v[184:187], v[192:195], 0
	v_mfma_f32_16x16x32_bf16 v[98:101], v[176:179], v[200:203], 0
	v_mfma_f32_16x16x32_bf16 v[90:93], v[184:187], v[200:203], 0
	v_mfma_f32_16x16x32_bf16 v[82:85], v[176:179], v[208:211], 0
	v_mfma_f32_16x16x32_bf16 v[74:77], v[184:187], v[208:211], 0
	v_mfma_f32_16x16x32_bf16 v[70:73], v[176:179], v[216:219], 0
	v_mfma_f32_16x16x32_bf16 v[66:69], v[184:187], v[216:219], 0
	v_mfma_f32_16x16x32_bf16 v[118:121], v[180:183], v[196:199], v[118:121]
	v_mfma_f32_16x16x32_bf16 v[110:113], v[188:191], v[196:199], v[110:113]
	v_mfma_f32_16x16x32_bf16 v[98:101], v[180:183], v[204:207], v[98:101]
	v_mfma_f32_16x16x32_bf16 v[90:93], v[188:191], v[204:207], v[90:93]
	v_mfma_f32_16x16x32_bf16 v[82:85], v[180:183], v[212:215], v[82:85]
	v_mfma_f32_16x16x32_bf16 v[74:77], v[188:191], v[212:215], v[74:77]
	v_mfma_f32_16x16x32_bf16 v[70:73], v[180:183], v[220:223], v[70:73]
	v_mfma_f32_16x16x32_bf16 v[66:69], v[188:191], v[220:223], v[66:69]
	s_setprio 0
	s_barrier
	s_add_i32 s58, s41, s29
	v_lshl_add_u64 v[224:225], s[24:25], 0, v[134:135]
	s_mov_b32 m0, s58
	ds_read_b128 v[192:195], v162 offset:16384
	ds_read_b128 v[196:199], v162 offset:17408
	ds_read_b128 v[200:203], v162 offset:18432
	ds_read_b128 v[204:207], v162 offset:19456
	ds_read_b128 v[208:211], v162 offset:20480
	ds_read_b128 v[212:215], v162 offset:21504
	ds_read_b128 v[216:219], v162 offset:22528
	ds_read_b128 v[220:223], v162 offset:23552
	global_load_lds_dwordx4 v[224:225], off
	s_add_i32 m0, s58, 0x2000
	s_add_u32 s58, s24, 0x40000
	v_lshl_add_u64 v[226:227], s[24:25], 0, v[130:131]
	s_addc_u32 s59, s25, 0
	s_add_i32 s60, s42, s29
	global_load_lds_dwordx4 v[226:227], off
	s_waitcnt vmcnt(4)
	s_waitcnt lgkmcnt(0)
	s_barrier
; #define PG8_STAGE(bufoff, gbase, voff) do { _Pragma("unroll") for (int _i = 0; _i < 2; ++_i) \
;         __builtin_amdgcn_global_load_lds((const unsigned*)((const char*)(gbase) + (voff)[_i]), (PG8_LAS unsigned*)(lds + (bufoff) + ldsw + _i * 8192), 16, 0, 0); } while (0)
; #define PG8_LDA(dst, b, h) do { _Pragma("unroll") for (int m = 0; m < 4; ++m) _Pragma("unroll") for (int k = 0; k < 2; ++k) dst[m][k] = *(const PG8_LAS bf16x8*)(lds + PG8_SA(b, h) + aoff + m * 2048 + k * 1024); } while (0)
; #define PG8_LDB(dst, b, h) do { _Pragma("unroll") for (int n = 0; n < 2; ++n) _Pragma("unroll") for (int k = 0; k < 2; ++k) dst[n][k] = *(const PG8_LAS bf16x8*)(lds + PG8_SB(b, h) + boff + n * 2048 + k * 1024); } while (0)
; #define PG8_MMA(ai, bj, At, Bt) do { __builtin_amdgcn_s_setprio(1); _Pragma("unroll") for (int m = 0; m < 4; ++m) _Pragma("unroll") for (int n = 0; n < 2; ++n) _Pragma("unroll") for (int k = 0; k < 2; ++k) \
;         acc[ai][bj][m][n] = __builtin_amdgcn_mfma_f32_16x16x32_bf16(Bt[n][k], At[m][k], acc[ai][bj][m][n], 0, 0, 0); __builtin_amdgcn_s_setprio(0); } while (0)
; #define PG8_WAIT_V(n) asm volatile("s_waitcnt vmcnt(" #n ")" ::: "memory")
; #define PG8_WAIT_L(n) asm volatile("s_waitcnt lgkmcnt(" #n ")" ::: "memory")
; #define PG8_BAR __builtin_amdgcn_s_barrier()
; #define PG8_SCHED __builtin_amdgcn_sched_barrier(0)
; template <class Epi, class Sched, bool ALIGN_EPI = false, bool SP2 = false, bool AGM = false  >
; __device__ __forceinline__ void gemm_phase(PG8_LAS unsigned char* lds, const Gemm g, const Sched& S, const Epi& E) {
;     ...
;             PG8_LDA(At, 0, 1); PG8_STAGE(PG8_SB(0, 0), b2, voffB); PG8_STAGE(PG8_SB(0, 1), b2 + hstep, voffB); PG8_STAGE(PG8_SA(0, 0), a2, voffA);
;             PG8_WAIT_V(8); PG8_WAIT_L(0); PG8_BAR; PG8_MMA(1, 0, At, B0); PG8_MMA(1, 1, At, B1); PG8_BAR; PG8_SCHED;
;             PG8_LDB(B0, 1, 0); PG8_LDB(B1, 1, 1); PG8_SCHED; PG8_LDA(At, 1, 0); PG8_STAGE(PG8_SA(0, 1), a2 + hstepA, voffA);
;             PG8_WAIT_V(8); PG8_WAIT_L(0); PG8_BAR; PG8_MMA(0, 0, At, B0); PG8_MMA(0, 1, At, B1); PG8_BAR; PG8_SCHED;
	s_setprio 1
	s_waitcnt lgkmcnt(0)
	v_mfma_f32_16x16x32_bf16 v[62:65], v[150:153], v[192:195], 0
	v_mfma_f32_16x16x32_bf16 v[58:61], v[168:171], v[192:195], 0
	v_lshl_add_u64 v[228:229], s[58:59], 0, v[134:135]
	s_mov_b32 m0, s60
	v_lshl_add_u64 v[230:231], s[26:27], 0, v[132:133]
	global_load_lds_dwordx4 v[228:229], off
	v_mfma_f32_16x16x32_bf16 v[54:57], v[150:153], v[200:203], 0
	v_mfma_f32_16x16x32_bf16 v[46:49], v[168:171], v[200:203], 0
	v_mfma_f32_16x16x32_bf16 v[38:41], v[150:153], v[208:211], 0
	v_mfma_f32_16x16x32_bf16 v[30:33], v[168:171], v[208:211], 0
	v_mfma_f32_16x16x32_bf16 v[22:25], v[150:153], v[216:219], 0
	v_mfma_f32_16x16x32_bf16 v[14:17], v[168:171], v[216:219], 0
	v_mfma_f32_16x16x32_bf16 v[62:65], v[164:167], v[196:199], v[62:65]
	v_mfma_f32_16x16x32_bf16 v[58:61], v[172:175], v[196:199], v[58:61]
	v_lshl_add_u64 v[228:229], s[58:59], 0, v[130:131]
	s_add_i32 m0, s60, 0x2000
	s_nop 0
	global_load_lds_dwordx4 v[228:229], off
	v_mfma_f32_16x16x32_bf16 v[54:57], v[164:167], v[204:207], v[54:57]
	v_mfma_f32_16x16x32_bf16 v[46:49], v[172:175], v[204:207], v[46:49]
	v_mfma_f32_16x16x32_bf16 v[38:41], v[164:167], v[212:215], v[38:41]
	v_mfma_f32_16x16x32_bf16 v[30:33], v[172:175], v[212:215], v[30:33]
	v_mfma_f32_16x16x32_bf16 v[22:25], v[164:167], v[220:223], v[22:25]
	v_mfma_f32_16x16x32_bf16 v[14:17], v[172:175], v[220:223], v[14:17]
	s_setprio 0
	s_setprio 1
	v_mfma_f32_16x16x32_bf16 v[50:53], v[176:179], v[192:195], 0
	v_mfma_f32_16x16x32_bf16 v[42:45], v[184:187], v[192:195], 0
	v_lshl_add_u64 v[228:229], s[26:27], 0, v[136:137]
	s_mov_b32 m0, s33
	s_nop 0
	global_load_lds_dwordx4 v[228:229], off
	v_mfma_f32_16x16x32_bf16 v[34:37], v[176:179], v[200:203], 0
	v_mfma_f32_16x16x32_bf16 v[26:29], v[184:187], v[200:203], 0
	v_mfma_f32_16x16x32_bf16 v[18:21], v[176:179], v[208:211], 0
	v_mfma_f32_16x16x32_bf16 v[10:13], v[184:187], v[208:211], 0
	v_mfma_f32_16x16x32_bf16 v[6:9], v[176:179], v[216:219], 0
	v_mfma_f32_16x16x32_bf16 v[2:5], v[184:187], v[216:219], 0
	v_mfma_f32_16x16x32_bf16 v[50:53], v[180:183], v[196:199], v[50:53]
	v_mfma_f32_16x16x32_bf16 v[42:45], v[188:191], v[196:199], v[42:45]
	s_mov_b32 m0, s34
	s_nop 0
	global_load_lds_dwordx4 v[230:231], off
	v_mfma_f32_16x16x32_bf16 v[34:37], v[180:183], v[204:207], v[34:37]
	v_mfma_f32_16x16x32_bf16 v[26:29], v[188:191], v[204:207], v[26:29]
	v_mfma_f32_16x16x32_bf16 v[18:21], v[180:183], v[212:215], v[18:21]
	v_mfma_f32_16x16x32_bf16 v[10:13], v[188:191], v[212:215], v[10:13]
	v_mfma_f32_16x16x32_bf16 v[6:9], v[180:183], v[220:223], v[6:9]
	v_mfma_f32_16x16x32_bf16 v[2:5], v[188:191], v[220:223], v[2:5]
	s_setprio 0
	s_barrier
	s_add_i32 s58, 0, 0x18000
	v_add_u32_e32 v138, s58, v157
	s_add_i32 s59, 0, 0x1c000
	ds_read_b128 v[150:153], v138
	ds_read_b128 v[164:167], v138 offset:1024
	ds_read_b128 v[168:171], v138 offset:2048
	ds_read_b128 v[172:175], v138 offset:3072
	v_add_u32_e32 v138, s59, v157
	ds_read_b128 v[176:179], v138
	ds_read_b128 v[180:183], v138 offset:1024
	ds_read_b128 v[184:187], v138 offset:2048
	ds_read_b128 v[188:191], v138 offset:3072
	s_add_u32 s26, s26, 0x40000
	s_addc_u32 s27, s27, 0
	s_mov_b32 m0, s35
	v_lshl_add_u64 v[232:233], s[26:27], 0, v[136:137]
	ds_read_b128 v[192:195], v162 offset:32768
	ds_read_b128 v[196:199], v162 offset:33792
	ds_read_b128 v[200:203], v162 offset:34816
	ds_read_b128 v[204:207], v162 offset:35840
	ds_read_b128 v[208:211], v162 offset:36864
	ds_read_b128 v[212:215], v162 offset:37888
	ds_read_b128 v[216:219], v162 offset:38912
	ds_read_b128 v[220:223], v162 offset:39936
	global_load_lds_dwordx4 v[232:233], off
	v_lshl_add_u64 v[232:233], s[26:27], 0, v[132:133]
	s_mov_b32 m0, s36
	s_nop 0
	global_load_lds_dwordx4 v[232:233], off
	s_waitcnt vmcnt(8)
	s_waitcnt lgkmcnt(0)
	s_barrier
	s_setprio 1
	s_waitcnt lgkmcnt(0)
	v_mfma_f32_16x16x32_bf16 v[126:129], v[150:153], v[192:195], v[126:129]
	v_mfma_f32_16x16x32_bf16 v[122:125], v[168:171], v[192:195], v[122:125]
	v_mfma_f32_16x16x32_bf16 v[114:117], v[150:153], v[200:203], v[114:117]
	v_mfma_f32_16x16x32_bf16 v[106:109], v[168:171], v[200:203], v[106:109]
	v_mfma_f32_16x16x32_bf16 v[102:105], v[150:153], v[208:211], v[102:105]
	v_mfma_f32_16x16x32_bf16 v[94:97], v[168:171], v[208:211], v[94:97]
	v_mfma_f32_16x16x32_bf16 v[86:89], v[150:153], v[216:219], v[86:89]
	v_mfma_f32_16x16x32_bf16 v[78:81], v[168:171], v[216:219], v[78:81]
	v_mfma_f32_16x16x32_bf16 v[126:129], v[164:167], v[196:199], v[126:129]
	v_mfma_f32_16x16x32_bf16 v[122:125], v[172:175], v[196:199], v[122:125]
	v_mfma_f32_16x16x32_bf16 v[114:117], v[164:167], v[204:207], v[114:117]
	v_mfma_f32_16x16x32_bf16 v[106:109], v[172:175], v[204:207], v[106:109]
	v_mfma_f32_16x16x32_bf16 v[102:105], v[164:167], v[212:215], v[102:105]
	v_mfma_f32_16x16x32_bf16 v[94:97], v[172:175], v[212:215], v[94:97]
	v_mfma_f32_16x16x32_bf16 v[86:89], v[164:167], v[220:223], v[86:89]
	v_mfma_f32_16x16x32_bf16 v[78:81], v[172:175], v[220:223], v[78:81]
	s_setprio 0
	s_setprio 1
	v_mfma_f32_16x16x32_bf16 v[118:121], v[176:179], v[192:195], v[118:121]
	v_mfma_f32_16x16x32_bf16 v[110:113], v[184:187], v[192:195], v[110:113]
	v_mfma_f32_16x16x32_bf16 v[98:101], v[176:179], v[200:203], v[98:101]
	v_mfma_f32_16x16x32_bf16 v[90:93], v[184:187], v[200:203], v[90:93]
	v_mfma_f32_16x16x32_bf16 v[82:85], v[176:179], v[208:211], v[82:85]
	v_mfma_f32_16x16x32_bf16 v[74:77], v[184:187], v[208:211], v[74:77]
	v_mfma_f32_16x16x32_bf16 v[70:73], v[176:179], v[216:219], v[70:73]
	v_mfma_f32_16x16x32_bf16 v[66:69], v[184:187], v[216:219], v[66:69]
	v_mfma_f32_16x16x32_bf16 v[118:121], v[180:183], v[196:199], v[118:121]
	v_mfma_f32_16x16x32_bf16 v[110:113], v[188:191], v[196:199], v[110:113]
	v_mfma_f32_16x16x32_bf16 v[98:101], v[180:183], v[204:207], v[98:101]
	v_mfma_f32_16x16x32_bf16 v[90:93], v[188:191], v[204:207], v[90:93]
	v_mfma_f32_16x16x32_bf16 v[82:85], v[180:183], v[212:215], v[82:85]
	v_mfma_f32_16x16x32_bf16 v[74:77], v[188:191], v[212:215], v[74:77]
	v_mfma_f32_16x16x32_bf16 v[70:73], v[180:183], v[220:223], v[70:73]
	v_mfma_f32_16x16x32_bf16 v[66:69], v[188:191], v[220:223], v[66:69]
	s_setprio 0
	s_barrier
; #define PG8_STAGE(bufoff, gbase, voff) do { _Pragma("unroll") for (int _i = 0; _i < 2; ++_i) \
;         __builtin_amdgcn_global_load_lds((const unsigned*)((const char*)(gbase) + (voff)[_i]), (PG8_LAS unsigned*)(lds + (bufoff) + ldsw + _i * 8192), 16, 0, 0); } while (0)
; #define PG8_LDA(dst, b, h) do { _Pragma("unroll") for (int m = 0; m < 4; ++m) _Pragma("unroll") for (int k = 0; k < 2; ++k) dst[m][k] = *(const PG8_LAS bf16x8*)(lds + PG8_SA(b, h) + aoff + m * 2048 + k * 1024); } while (0)
; #define PG8_LDB(dst, b, h) do { _Pragma("unroll") for (int n = 0; n < 2; ++n) _Pragma("unroll") for (int k = 0; k < 2; ++k) dst[n][k] = *(const PG8_LAS bf16x8*)(lds + PG8_SB(b, h) + boff + n * 2048 + k * 1024); } while (0)
; #define PG8_MMA(ai, bj, At, Bt) do { __builtin_amdgcn_s_setprio(1); _Pragma("unroll") for (int m = 0; m < 4; ++m) _Pragma("unroll") for (int n = 0; n < 2; ++n) _Pragma("unroll") for (int k = 0; k < 2; ++k) \
;         acc[ai][bj][m][n] = __builtin_amdgcn_mfma_f32_16x16x32_bf16(Bt[n][k], At[m][k], acc[ai][bj][m][n], 0, 0, 0); __builtin_amdgcn_s_setprio(0); } while (0)
; #define PG8_BAR __builtin_amdgcn_s_barrier()
; template <class Epi, class Sched, bool ALIGN_EPI = false, bool SP2 = false, bool AGM = false  >
; __device__ __forceinline__ void gemm_phase(PG8_LAS unsigned char* lds, const Gemm g, const Sched& S, const Epi& E) {
;     ...
;             PG8_LDB(B0, 0, 0); PG8_LDB(B1, 0, 1); PG8_SCHED; PG8_LDA(At, 0, 0); PG8_STAGE(PG8_SA(1, 1), a1 + hstepA, voffA);
;             PG8_WAIT_V(8); PG8_WAIT_L(0); PG8_BAR; PG8_MMA(0, 0, At, B0); PG8_MMA(0, 1, At, B1); PG8_BAR; PG8_SCHED;
;             PG8_LDA(At, 0, 1); PG8_STAGE(PG8_SB(0, 0), b2, voffB); PG8_STAGE(PG8_SB(0, 1), b2 + hstep, voffB); PG8_STAGE(PG8_SA(0, 0), a2, voffA);
;             PG8_WAIT_V(8); PG8_WAIT_L(0); PG8_BAR; PG8_MMA(1, 0, At, B0); PG8_MMA(1, 1, At, B1); PG8_BAR; PG8_SCHED;
;             PG8_LDB(B0, 1, 0); PG8_LDB(B1, 1, 1); PG8_SCHED; PG8_LDA(At, 1, 0); PG8_STAGE(PG8_SA(0, 1), a2 + hstepA, voffA);
;             PG8_WAIT_V(8); PG8_WAIT_L(0); PG8_BAR; PG8_MMA(0, 0, At, B0); PG8_MMA(0, 1, At, B1); PG8_BAR; PG8_SCHED;
;             PG8_LDA(At, 1, 1); PG8_STAGE(PG8_SB(1, 0), b3, voffB); PG8_STAGE(PG8_SB(1, 1), b3 + hstep, voffB); PG8_STAGE(PG8_SA(1, 0), a3, voffA);
;             PG8_WAIT_V(8); PG8_WAIT_L(0); PG8_BAR; PG8_MMA(1, 0, At, B0); PG8_MMA(1, 1, At, B1); PG8_BAR; PG8_SCHED;
	s_add_i32 s26, s58, s29
	v_lshl_add_u64 v[224:225], v[224:225], 0, s[10:11]
	s_mov_b32 m0, s26
	ds_read_b128 v[192:195], v162 offset:49152
	ds_read_b128 v[196:199], v162 offset:50176
	ds_read_b128 v[200:203], v162 offset:51200
	ds_read_b128 v[204:207], v162 offset:52224
	ds_read_b128 v[208:211], v162 offset:53248
	ds_read_b128 v[212:215], v162 offset:54272
	ds_read_b128 v[216:219], v162 offset:55296
	ds_read_b128 v[220:223], v162 offset:56320
	global_load_lds_dwordx4 v[224:225], off
	s_add_i32 m0, s26, 0x2000
	s_add_u32 s24, s24, 0x40080
	v_lshl_add_u64 v[224:225], v[226:227], 0, s[10:11]
	s_addc_u32 s25, s25, 0
	s_add_i32 s26, s59, s29
	global_load_lds_dwordx4 v[224:225], off
	s_waitcnt vmcnt(4)
	s_waitcnt lgkmcnt(0)
	s_barrier
	s_setprio 1
	s_waitcnt lgkmcnt(0)
	v_mfma_f32_16x16x32_bf16 v[62:65], v[150:153], v[192:195], v[62:65]
	v_mfma_f32_16x16x32_bf16 v[58:61], v[168:171], v[192:195], v[58:61]
	v_lshl_add_u64 v[224:225], s[24:25], 0, v[134:135]
	s_mov_b32 m0, s26
	s_nop 0
	global_load_lds_dwordx4 v[224:225], off
	v_mfma_f32_16x16x32_bf16 v[54:57], v[150:153], v[200:203], v[54:57]
	v_mfma_f32_16x16x32_bf16 v[46:49], v[168:171], v[200:203], v[46:49]
	v_mfma_f32_16x16x32_bf16 v[38:41], v[150:153], v[208:211], v[38:41]
	v_mfma_f32_16x16x32_bf16 v[30:33], v[168:171], v[208:211], v[30:33]
	v_mfma_f32_16x16x32_bf16 v[22:25], v[150:153], v[216:219], v[22:25]
	v_mfma_f32_16x16x32_bf16 v[14:17], v[168:171], v[216:219], v[14:17]
	v_mfma_f32_16x16x32_bf16 v[62:65], v[164:167], v[196:199], v[62:65]
	v_mfma_f32_16x16x32_bf16 v[58:61], v[172:175], v[196:199], v[58:61]
	v_lshl_add_u64 v[224:225], s[24:25], 0, v[130:131]
	s_add_i32 m0, s26, 0x2000
	s_nop 0
	global_load_lds_dwordx4 v[224:225], off
	v_mfma_f32_16x16x32_bf16 v[54:57], v[164:167], v[204:207], v[54:57]
	v_mfma_f32_16x16x32_bf16 v[46:49], v[172:175], v[204:207], v[46:49]
	v_mfma_f32_16x16x32_bf16 v[38:41], v[164:167], v[212:215], v[38:41]
	v_mfma_f32_16x16x32_bf16 v[30:33], v[172:175], v[212:215], v[30:33]
	v_mfma_f32_16x16x32_bf16 v[22:25], v[164:167], v[220:223], v[22:25]
	v_mfma_f32_16x16x32_bf16 v[14:17], v[172:175], v[220:223], v[14:17]
	s_setprio 0
	s_setprio 1
	v_mfma_f32_16x16x32_bf16 v[50:53], v[176:179], v[192:195], v[50:53]
	v_mfma_f32_16x16x32_bf16 v[42:45], v[184:187], v[192:195], v[42:45]
	v_lshl_add_u64 v[224:225], v[228:229], 0, s[10:11]
	s_mov_b32 m0, s38
	s_nop 0
	global_load_lds_dwordx4 v[224:225], off
	v_mfma_f32_16x16x32_bf16 v[34:37], v[176:179], v[200:203], v[34:37]
	v_mfma_f32_16x16x32_bf16 v[26:29], v[184:187], v[200:203], v[26:29]
	v_mfma_f32_16x16x32_bf16 v[18:21], v[176:179], v[208:211], v[18:21]
	v_mfma_f32_16x16x32_bf16 v[10:13], v[184:187], v[208:211], v[10:13]
	v_mfma_f32_16x16x32_bf16 v[6:9], v[176:179], v[216:219], v[6:9]
	v_mfma_f32_16x16x32_bf16 v[2:5], v[184:187], v[216:219], v[2:5]
	v_mfma_f32_16x16x32_bf16 v[50:53], v[180:183], v[196:199], v[50:53]
	v_mfma_f32_16x16x32_bf16 v[42:45], v[188:191], v[196:199], v[42:45]
	v_lshl_add_u64 v[224:225], v[230:231], 0, s[10:11]
	s_mov_b32 m0, s39
	s_nop 0
	global_load_lds_dwordx4 v[224:225], off
	v_mfma_f32_16x16x32_bf16 v[34:37], v[180:183], v[204:207], v[34:37]
	v_mfma_f32_16x16x32_bf16 v[26:29], v[188:191], v[204:207], v[26:29]
	v_mfma_f32_16x16x32_bf16 v[18:21], v[180:183], v[212:215], v[18:21]
	v_mfma_f32_16x16x32_bf16 v[10:13], v[188:191], v[212:215], v[10:13]
	v_mfma_f32_16x16x32_bf16 v[6:9], v[180:183], v[220:223], v[6:9]
	v_mfma_f32_16x16x32_bf16 v[2:5], v[188:191], v[220:223], v[2:5]
	s_setprio 0
	s_barrier
	s_add_i32 s55, s55, 2
	s_add_u32 s22, s22, 0x100
	s_addc_u32 s23, s23, 0
	s_add_u32 s53, s53, 0x100
	s_addc_u32 s54, s54, 0
	s_cmp_gt_u32 s55, 13
	s_cbranch_scc1 .Lpeel_done_p1
	.p2align	6
.LBB0_137:
	ds_read_b128 v[150:153], v160
	ds_read_b128 v[164:167], v160 offset:1024
	ds_read_b128 v[168:171], v160 offset:2048
	ds_read_b128 v[172:175], v160 offset:3072
	ds_read_b128 v[176:179], v161
	ds_read_b128 v[180:183], v161 offset:1024
	ds_read_b128 v[184:187], v161 offset:2048
	ds_read_b128 v[188:191], v161 offset:3072
	s_add_u32 s24, s22, 0xfffc0080
	s_addc_u32 s25, s23, -1
	s_cmp_eq_u32 s55, 12
	s_cselect_b32 s27, s15, s25
	s_cselect_b32 s26, s21, s24
	s_cselect_b32 s25, s13, s54
	s_cselect_b32 s24, s45, s53
	v_lshl_add_u64 v[224:225], s[22:23], 0, v[142:143]
	s_add_i32 m0, s33, 0xc000
	ds_read_b128 v[192:195], v162
	ds_read_b128 v[196:199], v162 offset:1024
	ds_read_b128 v[200:203], v162 offset:2048
	ds_read_b128 v[204:207], v162 offset:3072
	ds_read_b128 v[208:211], v162 offset:4096
	ds_read_b128 v[212:215], v162 offset:5120
	ds_read_b128 v[216:219], v162 offset:6144
	ds_read_b128 v[220:223], v162 offset:7168
	global_load_lds_dwordx4 v[224:225], off
	v_lshl_add_u64 v[224:225], s[22:23], 0, v[144:145]
	s_add_i32 m0, s33, 0xe000
	s_nop 0
	global_load_lds_dwordx4 v[224:225], off
	s_waitcnt vmcnt(8)
	s_waitcnt lgkmcnt(0)
	s_barrier
; #define PG8_STAGE(bufoff, gbase, voff) do { _Pragma("unroll") for (int _i = 0; _i < 2; ++_i) \
;         __builtin_amdgcn_global_load_lds((const unsigned*)((const char*)(gbase) + (voff)[_i]), (PG8_LAS unsigned*)(lds + (bufoff) + ldsw + _i * 8192), 16, 0, 0); } while (0)
; #define PG8_LDA(dst, b, h) do { _Pragma("unroll") for (int m = 0; m < 4; ++m) _Pragma("unroll") for (int k = 0; k < 2; ++k) dst[m][k] = *(const PG8_LAS bf16x8*)(lds + PG8_SA(b, h) + aoff + m * 2048 + k * 1024); } while (0)
; #define PG8_MMA(ai, bj, At, Bt) do { __builtin_amdgcn_s_setprio(1); _Pragma("unroll") for (int m = 0; m < 4; ++m) _Pragma("unroll") for (int n = 0; n < 2; ++n) _Pragma("unroll") for (int k = 0; k < 2; ++k) \
;         acc[ai][bj][m][n] = __builtin_amdgcn_mfma_f32_16x16x32_bf16(Bt[n][k], At[m][k], acc[ai][bj][m][n], 0, 0, 0); __builtin_amdgcn_s_setprio(0); } while (0)
; #define PG8_WAIT_V(n) asm volatile("s_waitcnt vmcnt(" #n ")" ::: "memory")
; #define PG8_WAIT_L(n) asm volatile("s_waitcnt lgkmcnt(" #n ")" ::: "memory")
; #define PG8_BAR __builtin_amdgcn_s_barrier()
; #define PG8_SCHED __builtin_amdgcn_sched_barrier(0)
; template <class Epi, class Sched, bool ALIGN_EPI = false, bool SP2 = false, bool AGM = false  >
; __device__ __forceinline__ void gemm_phase(PG8_LAS unsigned char* lds, const Gemm g, const Sched& S, const Epi& E) {
;     ...
;             PG8_WAIT_V(8); PG8_WAIT_L(0); PG8_BAR; PG8_MMA(0, 0, At, B0); PG8_MMA(0, 1, At, B1); PG8_BAR; PG8_SCHED;
;             PG8_LDA(At, 0, 1); PG8_STAGE(PG8_SB(0, 0), b2, voffB); PG8_STAGE(PG8_SB(0, 1), b2 + hstep, voffB); PG8_STAGE(PG8_SA(0, 0), a2, voffA);
;             PG8_WAIT_V(8); PG8_WAIT_L(0); PG8_BAR; PG8_MMA(1, 0, At, B0); PG8_MMA(1, 1, At, B1); PG8_BAR; PG8_SCHED;
	s_setprio 1
	s_waitcnt lgkmcnt(0)
	v_mfma_f32_16x16x32_bf16 v[126:129], v[150:153], v[192:195], v[126:129]
	v_mfma_f32_16x16x32_bf16 v[122:125], v[168:171], v[192:195], v[122:125]
	v_mfma_f32_16x16x32_bf16 v[114:117], v[150:153], v[200:203], v[114:117]
	v_mfma_f32_16x16x32_bf16 v[106:109], v[168:171], v[200:203], v[106:109]
	v_mfma_f32_16x16x32_bf16 v[102:105], v[150:153], v[208:211], v[102:105]
	v_mfma_f32_16x16x32_bf16 v[94:97], v[168:171], v[208:211], v[94:97]
	v_mfma_f32_16x16x32_bf16 v[86:89], v[150:153], v[216:219], v[86:89]
	v_mfma_f32_16x16x32_bf16 v[78:81], v[168:171], v[216:219], v[78:81]
	v_mfma_f32_16x16x32_bf16 v[126:129], v[164:167], v[196:199], v[126:129]
	v_mfma_f32_16x16x32_bf16 v[122:125], v[172:175], v[196:199], v[122:125]
	v_mfma_f32_16x16x32_bf16 v[114:117], v[164:167], v[204:207], v[114:117]
	v_mfma_f32_16x16x32_bf16 v[106:109], v[172:175], v[204:207], v[106:109]
	v_mfma_f32_16x16x32_bf16 v[102:105], v[164:167], v[212:215], v[102:105]
	v_mfma_f32_16x16x32_bf16 v[94:97], v[172:175], v[212:215], v[94:97]
	v_mfma_f32_16x16x32_bf16 v[86:89], v[164:167], v[220:223], v[86:89]
	v_mfma_f32_16x16x32_bf16 v[78:81], v[172:175], v[220:223], v[78:81]
	s_setprio 0
	s_setprio 1
	v_mfma_f32_16x16x32_bf16 v[118:121], v[176:179], v[192:195], v[118:121]
	v_mfma_f32_16x16x32_bf16 v[110:113], v[184:187], v[192:195], v[110:113]
	v_mfma_f32_16x16x32_bf16 v[98:101], v[176:179], v[200:203], v[98:101]
	v_mfma_f32_16x16x32_bf16 v[90:93], v[184:187], v[200:203], v[90:93]
	v_mfma_f32_16x16x32_bf16 v[82:85], v[176:179], v[208:211], v[82:85]
	v_mfma_f32_16x16x32_bf16 v[74:77], v[184:187], v[208:211], v[74:77]
	v_mfma_f32_16x16x32_bf16 v[70:73], v[176:179], v[216:219], v[70:73]
	v_mfma_f32_16x16x32_bf16 v[66:69], v[184:187], v[216:219], v[66:69]
	v_mfma_f32_16x16x32_bf16 v[118:121], v[180:183], v[196:199], v[118:121]
	v_mfma_f32_16x16x32_bf16 v[110:113], v[188:191], v[196:199], v[110:113]
	v_mfma_f32_16x16x32_bf16 v[98:101], v[180:183], v[204:207], v[98:101]
	v_mfma_f32_16x16x32_bf16 v[90:93], v[188:191], v[204:207], v[90:93]
	v_mfma_f32_16x16x32_bf16 v[82:85], v[180:183], v[212:215], v[82:85]
	v_mfma_f32_16x16x32_bf16 v[74:77], v[188:191], v[212:215], v[74:77]
	v_mfma_f32_16x16x32_bf16 v[70:73], v[180:183], v[220:223], v[70:73]
	v_mfma_f32_16x16x32_bf16 v[66:69], v[188:191], v[220:223], v[66:69]
	s_setprio 0
	s_barrier
	s_add_i32 s58, s41, s29
	v_lshl_add_u64 v[224:225], s[24:25], 0, v[134:135]
	s_mov_b32 m0, s58
	ds_read_b128 v[192:195], v162 offset:16384
	ds_read_b128 v[196:199], v162 offset:17408
	ds_read_b128 v[200:203], v162 offset:18432
	ds_read_b128 v[204:207], v162 offset:19456
	ds_read_b128 v[208:211], v162 offset:20480
	ds_read_b128 v[212:215], v162 offset:21504
	ds_read_b128 v[216:219], v162 offset:22528
	ds_read_b128 v[220:223], v162 offset:23552
	global_load_lds_dwordx4 v[224:225], off
	s_add_i32 m0, s58, 0x2000
	s_add_u32 s58, s24, 0x40000
	v_lshl_add_u64 v[226:227], s[24:25], 0, v[130:131]
	s_addc_u32 s59, s25, 0
	s_add_i32 s60, s42, s29
	global_load_lds_dwordx4 v[226:227], off
	s_waitcnt vmcnt(4)
	s_waitcnt lgkmcnt(0)
	s_barrier
	s_setprio 1
	s_waitcnt lgkmcnt(0)
	v_mfma_f32_16x16x32_bf16 v[62:65], v[150:153], v[192:195], v[62:65]
	v_mfma_f32_16x16x32_bf16 v[58:61], v[168:171], v[192:195], v[58:61]
	v_lshl_add_u64 v[228:229], s[58:59], 0, v[134:135]
	s_mov_b32 m0, s60
	v_lshl_add_u64 v[230:231], s[26:27], 0, v[132:133]
	global_load_lds_dwordx4 v[228:229], off
	v_mfma_f32_16x16x32_bf16 v[54:57], v[150:153], v[200:203], v[54:57]
	v_mfma_f32_16x16x32_bf16 v[46:49], v[168:171], v[200:203], v[46:49]
	v_mfma_f32_16x16x32_bf16 v[38:41], v[150:153], v[208:211], v[38:41]
	v_mfma_f32_16x16x32_bf16 v[30:33], v[168:171], v[208:211], v[30:33]
	v_mfma_f32_16x16x32_bf16 v[22:25], v[150:153], v[216:219], v[22:25]
	v_mfma_f32_16x16x32_bf16 v[14:17], v[168:171], v[216:219], v[14:17]
	v_mfma_f32_16x16x32_bf16 v[62:65], v[164:167], v[196:199], v[62:65]
	v_mfma_f32_16x16x32_bf16 v[58:61], v[172:175], v[196:199], v[58:61]
	v_lshl_add_u64 v[228:229], s[58:59], 0, v[130:131]
	s_add_i32 m0, s60, 0x2000
	s_nop 0
	global_load_lds_dwordx4 v[228:229], off
	v_mfma_f32_16x16x32_bf16 v[54:57], v[164:167], v[204:207], v[54:57]
	v_mfma_f32_16x16x32_bf16 v[46:49], v[172:175], v[204:207], v[46:49]
	v_mfma_f32_16x16x32_bf16 v[38:41], v[164:167], v[212:215], v[38:41]
	v_mfma_f32_16x16x32_bf16 v[30:33], v[172:175], v[212:215], v[30:33]
	v_mfma_f32_16x16x32_bf16 v[22:25], v[164:167], v[220:223], v[22:25]
	v_mfma_f32_16x16x32_bf16 v[14:17], v[172:175], v[220:223], v[14:17]
	s_setprio 0
	s_setprio 1
	v_mfma_f32_16x16x32_bf16 v[50:53], v[176:179], v[192:195], v[50:53]
	v_mfma_f32_16x16x32_bf16 v[42:45], v[184:187], v[192:195], v[42:45]
	v_lshl_add_u64 v[228:229], s[26:27], 0, v[136:137]
	s_mov_b32 m0, s33
	s_nop 0
	global_load_lds_dwordx4 v[228:229], off
	v_mfma_f32_16x16x32_bf16 v[34:37], v[176:179], v[200:203], v[34:37]
	v_mfma_f32_16x16x32_bf16 v[26:29], v[184:187], v[200:203], v[26:29]
	v_mfma_f32_16x16x32_bf16 v[18:21], v[176:179], v[208:211], v[18:21]
	v_mfma_f32_16x16x32_bf16 v[10:13], v[184:187], v[208:211], v[10:13]
	v_mfma_f32_16x16x32_bf16 v[6:9], v[176:179], v[216:219], v[6:9]
	v_mfma_f32_16x16x32_bf16 v[2:5], v[184:187], v[216:219], v[2:5]
	v_mfma_f32_16x16x32_bf16 v[50:53], v[180:183], v[196:199], v[50:53]
	v_mfma_f32_16x16x32_bf16 v[42:45], v[188:191], v[196:199], v[42:45]
	s_mov_b32 m0, s34
	s_nop 0
	global_load_lds_dwordx4 v[230:231], off
	v_mfma_f32_16x16x32_bf16 v[34:37], v[180:183], v[204:207], v[34:37]
	v_mfma_f32_16x16x32_bf16 v[26:29], v[188:191], v[204:207], v[26:29]
	v_mfma_f32_16x16x32_bf16 v[18:21], v[180:183], v[212:215], v[18:21]
	v_mfma_f32_16x16x32_bf16 v[10:13], v[188:191], v[212:215], v[10:13]
	v_mfma_f32_16x16x32_bf16 v[6:9], v[180:183], v[220:223], v[6:9]
	v_mfma_f32_16x16x32_bf16 v[2:5], v[188:191], v[220:223], v[2:5]
	s_setprio 0
	s_barrier
; #define PG8_STAGE(bufoff, gbase, voff) do { _Pragma("unroll") for (int _i = 0; _i < 2; ++_i) \
;         __builtin_amdgcn_global_load_lds((const unsigned*)((const char*)(gbase) + (voff)[_i]), (PG8_LAS unsigned*)(lds + (bufoff) + ldsw + _i * 8192), 16, 0, 0); } while (0)
; #define PG8_LDA(dst, b, h) do { _Pragma("unroll") for (int m = 0; m < 4; ++m) _Pragma("unroll") for (int k = 0; k < 2; ++k) dst[m][k] = *(const PG8_LAS bf16x8*)(lds + PG8_SA(b, h) + aoff + m * 2048 + k * 1024); } while (0)
; #define PG8_LDB(dst, b, h) do { _Pragma("unroll") for (int n = 0; n < 2; ++n) _Pragma("unroll") for (int k = 0; k < 2; ++k) dst[n][k] = *(const PG8_LAS bf16x8*)(lds + PG8_SB(b, h) + boff + n * 2048 + k * 1024); } while (0)
; #define PG8_MMA(ai, bj, At, Bt) do { __builtin_amdgcn_s_setprio(1); _Pragma("unroll") for (int m = 0; m < 4; ++m) _Pragma("unroll") for (int n = 0; n < 2; ++n) _Pragma("unroll") for (int k = 0; k < 2; ++k) \
;         acc[ai][bj][m][n] = __builtin_amdgcn_mfma_f32_16x16x32_bf16(Bt[n][k], At[m][k], acc[ai][bj][m][n], 0, 0, 0); __builtin_amdgcn_s_setprio(0); } while (0)
; #define PG8_WAIT_V(n) asm volatile("s_waitcnt vmcnt(" #n ")" ::: "memory")
; #define PG8_WAIT_L(n) asm volatile("s_waitcnt lgkmcnt(" #n ")" ::: "memory")
; #define PG8_BAR __builtin_amdgcn_s_barrier()
; #define PG8_SCHED __builtin_amdgcn_sched_barrier(0)
; template <class Epi, class Sched, bool ALIGN_EPI = false, bool SP2 = false, bool AGM = false  >
; __device__ __forceinline__ void gemm_phase(PG8_LAS unsigned char* lds, const Gemm g, const Sched& S, const Epi& E) {
;     ...
;             PG8_LDB(B0, 1, 0); PG8_LDB(B1, 1, 1); PG8_SCHED; PG8_LDA(At, 1, 0); PG8_STAGE(PG8_SA(0, 1), a2 + hstepA, voffA);
;             PG8_WAIT_V(8); PG8_WAIT_L(0); PG8_BAR; PG8_MMA(0, 0, At, B0); PG8_MMA(0, 1, At, B1); PG8_BAR; PG8_SCHED;
	s_add_i32 s58, 0, 0x18000
	v_add_u32_e32 v138, s58, v157
	s_add_i32 s59, 0, 0x1c000
	ds_read_b128 v[150:153], v138
	ds_read_b128 v[164:167], v138 offset:1024
	ds_read_b128 v[168:171], v138 offset:2048
	ds_read_b128 v[172:175], v138 offset:3072
	v_add_u32_e32 v138, s59, v157
	ds_read_b128 v[176:179], v138
	ds_read_b128 v[180:183], v138 offset:1024
	ds_read_b128 v[184:187], v138 offset:2048
	ds_read_b128 v[188:191], v138 offset:3072
	s_add_u32 s26, s26, 0x40000
	s_addc_u32 s27, s27, 0
	s_mov_b32 m0, s35
	v_lshl_add_u64 v[232:233], s[26:27], 0, v[136:137]
	ds_read_b128 v[192:195], v162 offset:32768
	ds_read_b128 v[196:199], v162 offset:33792
	ds_read_b128 v[200:203], v162 offset:34816
	ds_read_b128 v[204:207], v162 offset:35840
	ds_read_b128 v[208:211], v162 offset:36864
	ds_read_b128 v[212:215], v162 offset:37888
	ds_read_b128 v[216:219], v162 offset:38912
	ds_read_b128 v[220:223], v162 offset:39936
	global_load_lds_dwordx4 v[232:233], off
	v_lshl_add_u64 v[232:233], s[26:27], 0, v[132:133]
	s_mov_b32 m0, s36
	s_nop 0
	global_load_lds_dwordx4 v[232:233], off
	s_waitcnt vmcnt(8)
	s_waitcnt lgkmcnt(0)
	s_barrier
	s_setprio 1
	s_waitcnt lgkmcnt(0)
	v_mfma_f32_16x16x32_bf16 v[126:129], v[150:153], v[192:195], v[126:129]
	v_mfma_f32_16x16x32_bf16 v[122:125], v[168:171], v[192:195], v[122:125]
	v_mfma_f32_16x16x32_bf16 v[114:117], v[150:153], v[200:203], v[114:117]
	v_mfma_f32_16x16x32_bf16 v[106:109], v[168:171], v[200:203], v[106:109]
	v_mfma_f32_16x16x32_bf16 v[102:105], v[150:153], v[208:211], v[102:105]
	v_mfma_f32_16x16x32_bf16 v[94:97], v[168:171], v[208:211], v[94:97]
	v_mfma_f32_16x16x32_bf16 v[86:89], v[150:153], v[216:219], v[86:89]
	v_mfma_f32_16x16x32_bf16 v[78:81], v[168:171], v[216:219], v[78:81]
	v_mfma_f32_16x16x32_bf16 v[126:129], v[164:167], v[196:199], v[126:129]
	v_mfma_f32_16x16x32_bf16 v[122:125], v[172:175], v[196:199], v[122:125]
	v_mfma_f32_16x16x32_bf16 v[114:117], v[164:167], v[204:207], v[114:117]
	v_mfma_f32_16x16x32_bf16 v[106:109], v[172:175], v[204:207], v[106:109]
	v_mfma_f32_16x16x32_bf16 v[102:105], v[164:167], v[212:215], v[102:105]
	v_mfma_f32_16x16x32_bf16 v[94:97], v[172:175], v[212:215], v[94:97]
	v_mfma_f32_16x16x32_bf16 v[86:89], v[164:167], v[220:223], v[86:89]
	v_mfma_f32_16x16x32_bf16 v[78:81], v[172:175], v[220:223], v[78:81]
	s_setprio 0
	s_setprio 1
	v_mfma_f32_16x16x32_bf16 v[118:121], v[176:179], v[192:195], v[118:121]
	v_mfma_f32_16x16x32_bf16 v[110:113], v[184:187], v[192:195], v[110:113]
	v_mfma_f32_16x16x32_bf16 v[98:101], v[176:179], v[200:203], v[98:101]
	v_mfma_f32_16x16x32_bf16 v[90:93], v[184:187], v[200:203], v[90:93]
	v_mfma_f32_16x16x32_bf16 v[82:85], v[176:179], v[208:211], v[82:85]
	v_mfma_f32_16x16x32_bf16 v[74:77], v[184:187], v[208:211], v[74:77]
	v_mfma_f32_16x16x32_bf16 v[70:73], v[176:179], v[216:219], v[70:73]
	v_mfma_f32_16x16x32_bf16 v[66:69], v[184:187], v[216:219], v[66:69]
	v_mfma_f32_16x16x32_bf16 v[118:121], v[180:183], v[196:199], v[118:121]
	v_mfma_f32_16x16x32_bf16 v[110:113], v[188:191], v[196:199], v[110:113]
	v_mfma_f32_16x16x32_bf16 v[98:101], v[180:183], v[204:207], v[98:101]
	v_mfma_f32_16x16x32_bf16 v[90:93], v[188:191], v[204:207], v[90:93]
	v_mfma_f32_16x16x32_bf16 v[82:85], v[180:183], v[212:215], v[82:85]
	v_mfma_f32_16x16x32_bf16 v[74:77], v[188:191], v[212:215], v[74:77]
	v_mfma_f32_16x16x32_bf16 v[70:73], v[180:183], v[220:223], v[70:73]
	v_mfma_f32_16x16x32_bf16 v[66:69], v[188:191], v[220:223], v[66:69]
	s_setprio 0
	s_barrier
; #define PG8_STAGE(bufoff, gbase, voff) do { _Pragma("unroll") for (int _i = 0; _i < 2; ++_i) \
;         __builtin_amdgcn_global_load_lds((const unsigned*)((const char*)(gbase) + (voff)[_i]), (PG8_LAS unsigned*)(lds + (bufoff) + ldsw + _i * 8192), 16, 0, 0); } while (0)
; #define PG8_LDA(dst, b, h) do { _Pragma("unroll") for (int m = 0; m < 4; ++m) _Pragma("unroll") for (int k = 0; k < 2; ++k) dst[m][k] = *(const PG8_LAS bf16x8*)(lds + PG8_SA(b, h) + aoff + m * 2048 + k * 1024); } while (0)
; #define PG8_MMA(ai, bj, At, Bt) do { __builtin_amdgcn_s_setprio(1); _Pragma("unroll") for (int m = 0; m < 4; ++m) _Pragma("unroll") for (int n = 0; n < 2; ++n) _Pragma("unroll") for (int k = 0; k < 2; ++k) \
;         acc[ai][bj][m][n] = __builtin_amdgcn_mfma_f32_16x16x32_bf16(Bt[n][k], At[m][k], acc[ai][bj][m][n], 0, 0, 0); __builtin_amdgcn_s_setprio(0); } while (0)
; #define PG8_WAIT_V(n) asm volatile("s_waitcnt vmcnt(" #n ")" ::: "memory")
; #define PG8_WAIT_L(n) asm volatile("s_waitcnt lgkmcnt(" #n ")" ::: "memory")
; #define PG8_BAR __builtin_amdgcn_s_barrier()
; #define PG8_SCHED __builtin_amdgcn_sched_barrier(0)
; template <class Epi, class Sched, bool ALIGN_EPI = false, bool SP2 = false, bool AGM = false  >
; __device__ __forceinline__ void gemm_phase(PG8_LAS unsigned char* lds, const Gemm g, const Sched& S, const Epi& E) {
;     ...
;             PG8_LDA(At, 1, 1); PG8_STAGE(PG8_SB(1, 0), b3, voffB); PG8_STAGE(PG8_SB(1, 1), b3 + hstep, voffB); PG8_STAGE(PG8_SA(1, 0), a3, voffA);
;             PG8_WAIT_V(8); PG8_WAIT_L(0); PG8_BAR; PG8_MMA(1, 0, At, B0); PG8_MMA(1, 1, At, B1); PG8_BAR; PG8_SCHED;
	s_add_i32 s26, s58, s29
	v_lshl_add_u64 v[224:225], v[224:225], 0, s[10:11]
	s_mov_b32 m0, s26
	ds_read_b128 v[192:195], v162 offset:49152
	ds_read_b128 v[196:199], v162 offset:50176
	ds_read_b128 v[200:203], v162 offset:51200
	ds_read_b128 v[204:207], v162 offset:52224
	ds_read_b128 v[208:211], v162 offset:53248
	ds_read_b128 v[212:215], v162 offset:54272
	ds_read_b128 v[216:219], v162 offset:55296
	ds_read_b128 v[220:223], v162 offset:56320
	global_load_lds_dwordx4 v[224:225], off
	s_add_i32 m0, s26, 0x2000
	s_add_u32 s24, s24, 0x40080
	v_lshl_add_u64 v[224:225], v[226:227], 0, s[10:11]
	s_addc_u32 s25, s25, 0
	s_add_i32 s26, s59, s29
	global_load_lds_dwordx4 v[224:225], off
	s_waitcnt vmcnt(4)
	s_waitcnt lgkmcnt(0)
	s_barrier
	s_setprio 1
	s_waitcnt lgkmcnt(0)
	v_mfma_f32_16x16x32_bf16 v[62:65], v[150:153], v[192:195], v[62:65]
	v_mfma_f32_16x16x32_bf16 v[58:61], v[168:171], v[192:195], v[58:61]
	v_lshl_add_u64 v[224:225], s[24:25], 0, v[134:135]
	s_mov_b32 m0, s26
	s_nop 0
	global_load_lds_dwordx4 v[224:225], off
	v_mfma_f32_16x16x32_bf16 v[54:57], v[150:153], v[200:203], v[54:57]
	v_mfma_f32_16x16x32_bf16 v[46:49], v[168:171], v[200:203], v[46:49]
	v_mfma_f32_16x16x32_bf16 v[38:41], v[150:153], v[208:211], v[38:41]
	v_mfma_f32_16x16x32_bf16 v[30:33], v[168:171], v[208:211], v[30:33]
	v_mfma_f32_16x16x32_bf16 v[22:25], v[150:153], v[216:219], v[22:25]
	v_mfma_f32_16x16x32_bf16 v[14:17], v[168:171], v[216:219], v[14:17]
	v_mfma_f32_16x16x32_bf16 v[62:65], v[164:167], v[196:199], v[62:65]
	v_mfma_f32_16x16x32_bf16 v[58:61], v[172:175], v[196:199], v[58:61]
	v_lshl_add_u64 v[224:225], s[24:25], 0, v[130:131]
	s_add_i32 m0, s26, 0x2000
	s_nop 0
	global_load_lds_dwordx4 v[224:225], off
	v_mfma_f32_16x16x32_bf16 v[54:57], v[164:167], v[204:207], v[54:57]
	v_mfma_f32_16x16x32_bf16 v[46:49], v[172:175], v[204:207], v[46:49]
	v_mfma_f32_16x16x32_bf16 v[38:41], v[164:167], v[212:215], v[38:41]
	v_mfma_f32_16x16x32_bf16 v[30:33], v[172:175], v[212:215], v[30:33]
	v_mfma_f32_16x16x32_bf16 v[22:25], v[164:167], v[220:223], v[22:25]
	v_mfma_f32_16x16x32_bf16 v[14:17], v[172:175], v[220:223], v[14:17]
	s_setprio 0
	s_setprio 1
	v_mfma_f32_16x16x32_bf16 v[50:53], v[176:179], v[192:195], v[50:53]
	v_mfma_f32_16x16x32_bf16 v[42:45], v[184:187], v[192:195], v[42:45]
	v_lshl_add_u64 v[224:225], v[228:229], 0, s[10:11]
	s_mov_b32 m0, s38
	s_nop 0
	global_load_lds_dwordx4 v[224:225], off
	v_mfma_f32_16x16x32_bf16 v[34:37], v[176:179], v[200:203], v[34:37]
	v_mfma_f32_16x16x32_bf16 v[26:29], v[184:187], v[200:203], v[26:29]
	v_mfma_f32_16x16x32_bf16 v[18:21], v[176:179], v[208:211], v[18:21]
	v_mfma_f32_16x16x32_bf16 v[10:13], v[184:187], v[208:211], v[10:13]
	v_mfma_f32_16x16x32_bf16 v[6:9], v[176:179], v[216:219], v[6:9]
	v_mfma_f32_16x16x32_bf16 v[2:5], v[184:187], v[216:219], v[2:5]
	v_mfma_f32_16x16x32_bf16 v[50:53], v[180:183], v[196:199], v[50:53]
	v_mfma_f32_16x16x32_bf16 v[42:45], v[188:191], v[196:199], v[42:45]
	v_lshl_add_u64 v[224:225], v[230:231], 0, s[10:11]
	s_mov_b32 m0, s39
	s_nop 0
	global_load_lds_dwordx4 v[224:225], off
	v_mfma_f32_16x16x32_bf16 v[34:37], v[180:183], v[204:207], v[34:37]
	v_mfma_f32_16x16x32_bf16 v[26:29], v[188:191], v[204:207], v[26:29]
	v_mfma_f32_16x16x32_bf16 v[18:21], v[180:183], v[212:215], v[18:21]
	v_mfma_f32_16x16x32_bf16 v[10:13], v[188:191], v[212:215], v[10:13]
	v_mfma_f32_16x16x32_bf16 v[6:9], v[180:183], v[220:223], v[6:9]
	v_mfma_f32_16x16x32_bf16 v[2:5], v[188:191], v[220:223], v[2:5]
	s_setprio 0
	s_barrier
	s_add_i32 s55, s55, 2
	s_add_u32 s22, s22, 0x100
	s_addc_u32 s23, s23, 0
	s_add_u32 s53, s53, 0x100
	s_addc_u32 s54, s54, 0
	s_cmp_gt_u32 s55, 13
	s_cbranch_scc0 .LBB0_137

; #define PG8_STAGE(bufoff, gbase, voff) do { _Pragma("unroll") for (int _i = 0; _i < 2; ++_i) \
;         __builtin_amdgcn_global_load_lds((const unsigned*)((const char*)(gbase) + (voff)[_i]), (PG8_LAS unsigned*)(lds + (bufoff) + ldsw + _i * 8192), 16, 0, 0); } while (0)
; #define PG8_LDA(dst, b, h) do { _Pragma("unroll") for (int m = 0; m < 4; ++m) _Pragma("unroll") for (int k = 0; k < 2; ++k) dst[m][k] = *(const PG8_LAS bf16x8*)(lds + PG8_SA(b, h) + aoff + m * 2048 + k * 1024); } while (0)
; #define PG8_LDB(dst, b, h) do { _Pragma("unroll") for (int n = 0; n < 2; ++n) _Pragma("unroll") for (int k = 0; k < 2; ++k) dst[n][k] = *(const PG8_LAS bf16x8*)(lds + PG8_SB(b, h) + boff + n * 2048 + k * 1024); } while (0)
; #define PG8_MMA(ai, bj, At, Bt) do { __builtin_amdgcn_s_setprio(1); _Pragma("unroll") for (int m = 0; m < 4; ++m) _Pragma("unroll") for (int n = 0; n < 2; ++n) _Pragma("unroll") for (int k = 0; k < 2; ++k) \
;         acc[ai][bj][m][n] = __builtin_amdgcn_mfma_f32_16x16x32_bf16(Bt[n][k], At[m][k], acc[ai][bj][m][n], 0, 0, 0); __builtin_amdgcn_s_setprio(0); } while (0)
; #define PG8_WAIT_V(n) asm volatile("s_waitcnt vmcnt(" #n ")" ::: "memory")
; #define PG8_WAIT_L(n) asm volatile("s_waitcnt lgkmcnt(" #n ")" ::: "memory")
; #define PG8_BAR __builtin_amdgcn_s_barrier()
; #define PG8_SCHED __builtin_amdgcn_sched_barrier(0)
; template <class Epi, class Sched, bool ALIGN_EPI = false, bool SP2 = false, bool AGM = false  >
; __device__ __forceinline__ void gemm_phase(PG8_LAS unsigned char* lds, const Gemm g, const Sched& S, const Epi& E) {
;     ...
;             PG8_LDB(B0, 0, 0); PG8_LDB(B1, 0, 1); PG8_SCHED; PG8_LDA(At, 0, 0); PG8_STAGE(PG8_SA(1, 1), a1 + hstepA, voffA);
;             PG8_WAIT_V(8); PG8_WAIT_L(0); PG8_BAR; PG8_MMA(0, 0, At, B0); PG8_MMA(0, 1, At, B1); PG8_BAR; PG8_SCHED;
;             PG8_LDA(At, 0, 1); PG8_STAGE(PG8_SB(0, 0), b2, voffB); PG8_STAGE(PG8_SB(0, 1), b2 + hstep, voffB); PG8_STAGE(PG8_SA(0, 0), a2, voffA);
.LBB0_677:
	ds_read_b128 v[150:153], v157
	ds_read_b128 v[164:167], v157 offset:1024
	ds_read_b128 v[168:171], v157 offset:2048
	ds_read_b128 v[172:175], v157 offset:3072
	ds_read_b128 v[176:179], v158
	ds_read_b128 v[180:183], v158 offset:1024
	ds_read_b128 v[184:187], v158 offset:2048
	ds_read_b128 v[188:191], v158 offset:3072
	s_add_u32 s26, s24, 0x440000
	s_addc_u32 s27, s25, 0
	s_cmp_eq_u32 s70, 4
	s_cselect_b32 s34, s62, s26
	s_cselect_b32 s35, s19, s27
	s_cselect_b32 s30, s63, s68
	s_cselect_b32 s31, s17, s69
	s_add_u32 s28, s34, 0x220000
	s_addc_u32 s29, s35, 0
	v_lshl_add_u64 v[224:225], s[24:25], 0, v[142:143]
	s_add_i32 m0, s5, 0xc000
	ds_read_b128 v[192:195], v159
	ds_read_b128 v[196:199], v159 offset:1024
	ds_read_b128 v[200:203], v159 offset:2048
	ds_read_b128 v[204:207], v159 offset:3072
	ds_read_b128 v[208:211], v159 offset:4096
	ds_read_b128 v[212:215], v159 offset:5120
	ds_read_b128 v[216:219], v159 offset:6144
	ds_read_b128 v[220:223], v159 offset:7168
	global_load_lds_dwordx4 v[224:225], off
	v_lshl_add_u64 v[224:225], s[24:25], 0, v[144:145]
	s_add_i32 m0, s5, 0xe000
	s_nop 0
	global_load_lds_dwordx4 v[224:225], off
	s_waitcnt vmcnt(8)
	s_waitcnt lgkmcnt(0)
	s_barrier
	s_setprio 1
	s_waitcnt lgkmcnt(0)
	v_mfma_f32_16x16x32_bf16 v[126:129], v[150:153], v[192:195], v[126:129]
	v_mfma_f32_16x16x32_bf16 v[122:125], v[168:171], v[192:195], v[122:125]
	v_mfma_f32_16x16x32_bf16 v[110:113], v[150:153], v[200:203], v[110:113]
	v_mfma_f32_16x16x32_bf16 v[106:109], v[168:171], v[200:203], v[106:109]
	v_mfma_f32_16x16x32_bf16 v[94:97], v[150:153], v[208:211], v[94:97]
	v_mfma_f32_16x16x32_bf16 v[90:93], v[168:171], v[208:211], v[90:93]
	v_mfma_f32_16x16x32_bf16 v[78:81], v[150:153], v[216:219], v[78:81]
	v_mfma_f32_16x16x32_bf16 v[74:77], v[168:171], v[216:219], v[74:77]
	v_mfma_f32_16x16x32_bf16 v[126:129], v[164:167], v[196:199], v[126:129]
	v_mfma_f32_16x16x32_bf16 v[122:125], v[172:175], v[196:199], v[122:125]
	v_mfma_f32_16x16x32_bf16 v[110:113], v[164:167], v[204:207], v[110:113]
	v_mfma_f32_16x16x32_bf16 v[106:109], v[172:175], v[204:207], v[106:109]
	v_mfma_f32_16x16x32_bf16 v[94:97], v[164:167], v[212:215], v[94:97]
	v_mfma_f32_16x16x32_bf16 v[90:93], v[172:175], v[212:215], v[90:93]
	v_mfma_f32_16x16x32_bf16 v[78:81], v[164:167], v[220:223], v[78:81]
	v_mfma_f32_16x16x32_bf16 v[74:77], v[172:175], v[220:223], v[74:77]
	s_setprio 0
	s_setprio 1
	v_mfma_f32_16x16x32_bf16 v[118:121], v[176:179], v[192:195], v[118:121]
	v_mfma_f32_16x16x32_bf16 v[114:117], v[184:187], v[192:195], v[114:117]
	v_mfma_f32_16x16x32_bf16 v[102:105], v[176:179], v[200:203], v[102:105]
	v_mfma_f32_16x16x32_bf16 v[98:101], v[184:187], v[200:203], v[98:101]
	v_mfma_f32_16x16x32_bf16 v[86:89], v[176:179], v[208:211], v[86:89]
	v_mfma_f32_16x16x32_bf16 v[82:85], v[184:187], v[208:211], v[82:85]
	v_mfma_f32_16x16x32_bf16 v[70:73], v[176:179], v[216:219], v[70:73]
	v_mfma_f32_16x16x32_bf16 v[66:69], v[184:187], v[216:219], v[66:69]
	v_mfma_f32_16x16x32_bf16 v[118:121], v[180:183], v[196:199], v[118:121]
	v_mfma_f32_16x16x32_bf16 v[114:117], v[188:191], v[196:199], v[114:117]
	v_mfma_f32_16x16x32_bf16 v[102:105], v[180:183], v[204:207], v[102:105]
	v_mfma_f32_16x16x32_bf16 v[98:101], v[188:191], v[204:207], v[98:101]
	v_mfma_f32_16x16x32_bf16 v[86:89], v[180:183], v[212:215], v[86:89]
	v_mfma_f32_16x16x32_bf16 v[82:85], v[188:191], v[212:215], v[82:85]
	v_mfma_f32_16x16x32_bf16 v[70:73], v[180:183], v[220:223], v[70:73]
	v_mfma_f32_16x16x32_bf16 v[66:69], v[188:191], v[220:223], v[66:69]
	s_setprio 0
	s_barrier
	s_add_i32 s24, s54, s37
	v_lshl_add_u64 v[224:225], s[30:31], 0, v[134:135]
	s_mov_b32 m0, s24
	ds_read_b128 v[192:195], v159 offset:16384
	ds_read_b128 v[196:199], v159 offset:17408
	ds_read_b128 v[200:203], v159 offset:18432
	ds_read_b128 v[204:207], v159 offset:19456
	ds_read_b128 v[208:211], v159 offset:20480
	ds_read_b128 v[212:215], v159 offset:21504
	ds_read_b128 v[216:219], v159 offset:22528
	ds_read_b128 v[220:223], v159 offset:23552
	global_load_lds_dwordx4 v[224:225], off
	s_add_i32 m0, s24, 0x2000
	s_add_u32 s24, s30, 0x20000
	v_lshl_add_u64 v[226:227], s[30:31], 0, v[130:131]
	s_addc_u32 s25, s31, 0
	s_add_i32 s71, s55, s37
	global_load_lds_dwordx4 v[226:227], off
	s_waitcnt vmcnt(4)
	s_waitcnt lgkmcnt(0)
	s_barrier
; #define PG8_STAGE(bufoff, gbase, voff) do { _Pragma("unroll") for (int _i = 0; _i < 2; ++_i) \
;         __builtin_amdgcn_global_load_lds((const unsigned*)((const char*)(gbase) + (voff)[_i]), (PG8_LAS unsigned*)(lds + (bufoff) + ldsw + _i * 8192), 16, 0, 0); } while (0)
; #define PG8_LDA(dst, b, h) do { _Pragma("unroll") for (int m = 0; m < 4; ++m) _Pragma("unroll") for (int k = 0; k < 2; ++k) dst[m][k] = *(const PG8_LAS bf16x8*)(lds + PG8_SA(b, h) + aoff + m * 2048 + k * 1024); } while (0)
; #define PG8_LDB(dst, b, h) do { _Pragma("unroll") for (int n = 0; n < 2; ++n) _Pragma("unroll") for (int k = 0; k < 2; ++k) dst[n][k] = *(const PG8_LAS bf16x8*)(lds + PG8_SB(b, h) + boff + n * 2048 + k * 1024); } while (0)
; #define PG8_MMA(ai, bj, At, Bt) do { __builtin_amdgcn_s_setprio(1); _Pragma("unroll") for (int m = 0; m < 4; ++m) _Pragma("unroll") for (int n = 0; n < 2; ++n) _Pragma("unroll") for (int k = 0; k < 2; ++k) \
;         acc[ai][bj][m][n] = __builtin_amdgcn_mfma_f32_16x16x32_bf16(Bt[n][k], At[m][k], acc[ai][bj][m][n], 0, 0, 0); __builtin_amdgcn_s_setprio(0); } while (0)
; #define PG8_WAIT_V(n) asm volatile("s_waitcnt vmcnt(" #n ")" ::: "memory")
; #define PG8_WAIT_L(n) asm volatile("s_waitcnt lgkmcnt(" #n ")" ::: "memory")
; #define PG8_BAR __builtin_amdgcn_s_barrier()
; #define PG8_SCHED __builtin_amdgcn_sched_barrier(0)
; template <class Epi, class Sched, bool ALIGN_EPI = false, bool SP2 = false, bool AGM = false  >
; __device__ __forceinline__ void gemm_phase(PG8_LAS unsigned char* lds, const Gemm g, const Sched& S, const Epi& E) {
;     ...
;             PG8_LDA(At, 0, 1); PG8_STAGE(PG8_SB(0, 0), b2, voffB); PG8_STAGE(PG8_SB(0, 1), b2 + hstep, voffB); PG8_STAGE(PG8_SA(0, 0), a2, voffA);
;             PG8_WAIT_V(8); PG8_WAIT_L(0); PG8_BAR; PG8_MMA(1, 0, At, B0); PG8_MMA(1, 1, At, B1); PG8_BAR; PG8_SCHED;
;             PG8_LDB(B0, 1, 0); PG8_LDB(B1, 1, 1); PG8_SCHED; PG8_LDA(At, 1, 0); PG8_STAGE(PG8_SA(0, 1), a2 + hstepA, voffA);
;             PG8_WAIT_V(8); PG8_WAIT_L(0); PG8_BAR; PG8_MMA(0, 0, At, B0); PG8_MMA(0, 1, At, B1); PG8_BAR; PG8_SCHED;
	s_setprio 1
	s_waitcnt lgkmcnt(0)
	v_mfma_f32_16x16x32_bf16 v[62:65], v[150:153], v[192:195], v[62:65]
	v_mfma_f32_16x16x32_bf16 v[58:61], v[168:171], v[192:195], v[58:61]
	v_lshl_add_u64 v[228:229], s[24:25], 0, v[134:135]
	s_mov_b32 m0, s71
	s_nop 0
	global_load_lds_dwordx4 v[228:229], off
	v_mfma_f32_16x16x32_bf16 v[46:49], v[150:153], v[200:203], v[46:49]
	v_mfma_f32_16x16x32_bf16 v[42:45], v[168:171], v[200:203], v[42:45]
	v_mfma_f32_16x16x32_bf16 v[30:33], v[150:153], v[208:211], v[30:33]
	v_mfma_f32_16x16x32_bf16 v[26:29], v[168:171], v[208:211], v[26:29]
	v_mfma_f32_16x16x32_bf16 v[14:17], v[150:153], v[216:219], v[14:17]
	v_mfma_f32_16x16x32_bf16 v[10:13], v[168:171], v[216:219], v[10:13]
	v_mfma_f32_16x16x32_bf16 v[62:65], v[164:167], v[196:199], v[62:65]
	v_mfma_f32_16x16x32_bf16 v[58:61], v[172:175], v[196:199], v[58:61]
	v_lshl_add_u64 v[228:229], s[24:25], 0, v[130:131]
	s_add_i32 m0, s71, 0x2000
	s_nop 0
	global_load_lds_dwordx4 v[228:229], off
	v_mfma_f32_16x16x32_bf16 v[46:49], v[164:167], v[204:207], v[46:49]
	v_mfma_f32_16x16x32_bf16 v[42:45], v[172:175], v[204:207], v[42:45]
	v_mfma_f32_16x16x32_bf16 v[30:33], v[164:167], v[212:215], v[30:33]
	v_mfma_f32_16x16x32_bf16 v[26:29], v[172:175], v[212:215], v[26:29]
	v_mfma_f32_16x16x32_bf16 v[14:17], v[164:167], v[220:223], v[14:17]
	v_mfma_f32_16x16x32_bf16 v[10:13], v[172:175], v[220:223], v[10:13]
	s_setprio 0
	s_setprio 1
	v_mfma_f32_16x16x32_bf16 v[54:57], v[176:179], v[192:195], v[54:57]
	v_mfma_f32_16x16x32_bf16 v[50:53], v[184:187], v[192:195], v[50:53]
	v_lshl_add_u64 v[228:229], s[34:35], 0, v[136:137]
	s_mov_b32 m0, s5
	s_nop 0
	global_load_lds_dwordx4 v[228:229], off
	v_mfma_f32_16x16x32_bf16 v[38:41], v[176:179], v[200:203], v[38:41]
	v_mfma_f32_16x16x32_bf16 v[34:37], v[184:187], v[200:203], v[34:37]
	v_mfma_f32_16x16x32_bf16 v[22:25], v[176:179], v[208:211], v[22:25]
	v_mfma_f32_16x16x32_bf16 v[18:21], v[184:187], v[208:211], v[18:21]
	v_mfma_f32_16x16x32_bf16 v[6:9], v[176:179], v[216:219], v[6:9]
	v_mfma_f32_16x16x32_bf16 v[2:5], v[184:187], v[216:219], v[2:5]
	v_mfma_f32_16x16x32_bf16 v[54:57], v[180:183], v[196:199], v[54:57]
	v_mfma_f32_16x16x32_bf16 v[50:53], v[188:191], v[196:199], v[50:53]
	v_lshl_add_u64 v[228:229], s[34:35], 0, v[132:133]
	s_mov_b32 m0, s39
	s_nop 0
	global_load_lds_dwordx4 v[228:229], off
	v_mfma_f32_16x16x32_bf16 v[38:41], v[180:183], v[204:207], v[38:41]
	v_mfma_f32_16x16x32_bf16 v[34:37], v[188:191], v[204:207], v[34:37]
	v_mfma_f32_16x16x32_bf16 v[22:25], v[180:183], v[212:215], v[22:25]
	v_mfma_f32_16x16x32_bf16 v[18:21], v[188:191], v[212:215], v[18:21]
	v_mfma_f32_16x16x32_bf16 v[6:9], v[180:183], v[220:223], v[6:9]
	v_mfma_f32_16x16x32_bf16 v[2:5], v[188:191], v[220:223], v[2:5]
	s_setprio 0
	s_barrier
	s_add_i32 s71, 0, 0x18000
	v_add_u32_e32 v163, s71, v155
	s_add_i32 s72, 0, 0x1c000
	ds_read_b128 v[150:153], v163
	ds_read_b128 v[164:167], v163 offset:1024
	ds_read_b128 v[168:171], v163 offset:2048
	ds_read_b128 v[172:175], v163 offset:3072
	v_add_u32_e32 v163, s72, v155
	ds_read_b128 v[176:179], v163
	ds_read_b128 v[180:183], v163 offset:1024
	ds_read_b128 v[184:187], v163 offset:2048
	ds_read_b128 v[188:191], v163 offset:3072
	s_add_u32 s24, s34, 0x1000
	s_addc_u32 s25, s35, 0
	s_mov_b32 m0, s40
	v_lshl_add_u64 v[228:229], s[24:25], 0, v[136:137]
	ds_read_b128 v[192:195], v159 offset:32768
	ds_read_b128 v[196:199], v159 offset:33792
	ds_read_b128 v[200:203], v159 offset:34816
	ds_read_b128 v[204:207], v159 offset:35840
	ds_read_b128 v[208:211], v159 offset:36864
	ds_read_b128 v[212:215], v159 offset:37888
	ds_read_b128 v[216:219], v159 offset:38912
	ds_read_b128 v[220:223], v159 offset:39936
	global_load_lds_dwordx4 v[228:229], off
	v_lshl_add_u64 v[228:229], s[24:25], 0, v[132:133]
	s_mov_b32 m0, s41
	s_nop 0
	global_load_lds_dwordx4 v[228:229], off
	s_waitcnt vmcnt(8)
	s_waitcnt lgkmcnt(0)
	s_barrier
; #define PG8_STAGE(bufoff, gbase, voff) do { _Pragma("unroll") for (int _i = 0; _i < 2; ++_i) \
;         __builtin_amdgcn_global_load_lds((const unsigned*)((const char*)(gbase) + (voff)[_i]), (PG8_LAS unsigned*)(lds + (bufoff) + ldsw + _i * 8192), 16, 0, 0); } while (0)
; #define PG8_LDA(dst, b, h) do { _Pragma("unroll") for (int m = 0; m < 4; ++m) _Pragma("unroll") for (int k = 0; k < 2; ++k) dst[m][k] = *(const PG8_LAS bf16x8*)(lds + PG8_SA(b, h) + aoff + m * 2048 + k * 1024); } while (0)
; #define PG8_LDB(dst, b, h) do { _Pragma("unroll") for (int n = 0; n < 2; ++n) _Pragma("unroll") for (int k = 0; k < 2; ++k) dst[n][k] = *(const PG8_LAS bf16x8*)(lds + PG8_SB(b, h) + boff + n * 2048 + k * 1024); } while (0)
; #define PG8_MMA(ai, bj, At, Bt) do { __builtin_amdgcn_s_setprio(1); _Pragma("unroll") for (int m = 0; m < 4; ++m) _Pragma("unroll") for (int n = 0; n < 2; ++n) _Pragma("unroll") for (int k = 0; k < 2; ++k) \
;         acc[ai][bj][m][n] = __builtin_amdgcn_mfma_f32_16x16x32_bf16(Bt[n][k], At[m][k], acc[ai][bj][m][n], 0, 0, 0); __builtin_amdgcn_s_setprio(0); } while (0)
; #define PG8_WAIT_V(n) asm volatile("s_waitcnt vmcnt(" #n ")" ::: "memory")
; #define PG8_WAIT_L(n) asm volatile("s_waitcnt lgkmcnt(" #n ")" ::: "memory")
; #define PG8_BAR __builtin_amdgcn_s_barrier()
; #define PG8_SCHED __builtin_amdgcn_sched_barrier(0)
; template <class Epi, class Sched, bool ALIGN_EPI = false, bool SP2 = false, bool AGM = false  >
; __device__ __forceinline__ void gemm_phase(PG8_LAS unsigned char* lds, const Gemm g, const Sched& S, const Epi& E) {
;     ...
;             PG8_LDB(B0, 1, 0); PG8_LDB(B1, 1, 1); PG8_SCHED; PG8_LDA(At, 1, 0); PG8_STAGE(PG8_SA(0, 1), a2 + hstepA, voffA);
;             PG8_WAIT_V(8); PG8_WAIT_L(0); PG8_BAR; PG8_MMA(0, 0, At, B0); PG8_MMA(0, 1, At, B1); PG8_BAR; PG8_SCHED;
;             PG8_LDA(At, 1, 1); PG8_STAGE(PG8_SB(1, 0), b3, voffB); PG8_STAGE(PG8_SB(1, 1), b3 + hstep, voffB); PG8_STAGE(PG8_SA(1, 0), a3, voffA);
;             PG8_WAIT_V(8); PG8_WAIT_L(0); PG8_BAR; PG8_MMA(1, 0, At, B0); PG8_MMA(1, 1, At, B1); PG8_BAR; PG8_SCHED;
;     ...
;         if constexpr (ALIGN_EPI) { if (wr == 0) PG8_BAR; }
	s_setprio 1
	s_waitcnt lgkmcnt(0)
	v_mfma_f32_16x16x32_bf16 v[126:129], v[150:153], v[192:195], v[126:129]
	v_mfma_f32_16x16x32_bf16 v[122:125], v[168:171], v[192:195], v[122:125]
	v_mfma_f32_16x16x32_bf16 v[110:113], v[150:153], v[200:203], v[110:113]
	v_mfma_f32_16x16x32_bf16 v[106:109], v[168:171], v[200:203], v[106:109]
	v_mfma_f32_16x16x32_bf16 v[94:97], v[150:153], v[208:211], v[94:97]
	v_mfma_f32_16x16x32_bf16 v[90:93], v[168:171], v[208:211], v[90:93]
	v_mfma_f32_16x16x32_bf16 v[78:81], v[150:153], v[216:219], v[78:81]
	v_mfma_f32_16x16x32_bf16 v[74:77], v[168:171], v[216:219], v[74:77]
	v_mfma_f32_16x16x32_bf16 v[126:129], v[164:167], v[196:199], v[126:129]
	v_mfma_f32_16x16x32_bf16 v[122:125], v[172:175], v[196:199], v[122:125]
	v_mfma_f32_16x16x32_bf16 v[110:113], v[164:167], v[204:207], v[110:113]
	v_mfma_f32_16x16x32_bf16 v[106:109], v[172:175], v[204:207], v[106:109]
	v_mfma_f32_16x16x32_bf16 v[94:97], v[164:167], v[212:215], v[94:97]
	v_mfma_f32_16x16x32_bf16 v[90:93], v[172:175], v[212:215], v[90:93]
	v_mfma_f32_16x16x32_bf16 v[78:81], v[164:167], v[220:223], v[78:81]
	v_mfma_f32_16x16x32_bf16 v[74:77], v[172:175], v[220:223], v[74:77]
	s_setprio 0
	s_setprio 1
	v_mfma_f32_16x16x32_bf16 v[118:121], v[176:179], v[192:195], v[118:121]
	v_mfma_f32_16x16x32_bf16 v[114:117], v[184:187], v[192:195], v[114:117]
	v_mfma_f32_16x16x32_bf16 v[102:105], v[176:179], v[200:203], v[102:105]
	v_mfma_f32_16x16x32_bf16 v[98:101], v[184:187], v[200:203], v[98:101]
	v_mfma_f32_16x16x32_bf16 v[86:89], v[176:179], v[208:211], v[86:89]
	v_mfma_f32_16x16x32_bf16 v[82:85], v[184:187], v[208:211], v[82:85]
	v_mfma_f32_16x16x32_bf16 v[70:73], v[176:179], v[216:219], v[70:73]
	v_mfma_f32_16x16x32_bf16 v[66:69], v[184:187], v[216:219], v[66:69]
	v_mfma_f32_16x16x32_bf16 v[118:121], v[180:183], v[196:199], v[118:121]
	v_mfma_f32_16x16x32_bf16 v[114:117], v[188:191], v[196:199], v[114:117]
	v_mfma_f32_16x16x32_bf16 v[102:105], v[180:183], v[204:207], v[102:105]
	v_mfma_f32_16x16x32_bf16 v[98:101], v[188:191], v[204:207], v[98:101]
	v_mfma_f32_16x16x32_bf16 v[86:89], v[180:183], v[212:215], v[86:89]
	v_mfma_f32_16x16x32_bf16 v[82:85], v[188:191], v[212:215], v[82:85]
	v_mfma_f32_16x16x32_bf16 v[70:73], v[180:183], v[220:223], v[70:73]
	v_mfma_f32_16x16x32_bf16 v[66:69], v[188:191], v[220:223], v[66:69]
	s_setprio 0
	s_barrier
	s_add_i32 s24, s71, s37
	v_lshl_add_u64 v[224:225], v[224:225], 0, s[12:13]
	s_mov_b32 m0, s24
	ds_read_b128 v[192:195], v159 offset:49152
	ds_read_b128 v[196:199], v159 offset:50176
	ds_read_b128 v[200:203], v159 offset:51200
	ds_read_b128 v[204:207], v159 offset:52224
	ds_read_b128 v[208:211], v159 offset:53248
	ds_read_b128 v[212:215], v159 offset:54272
	ds_read_b128 v[216:219], v159 offset:55296
	ds_read_b128 v[220:223], v159 offset:56320
	global_load_lds_dwordx4 v[224:225], off
	s_add_i32 m0, s24, 0x2000
	s_add_u32 s24, s30, 0x20080
	v_lshl_add_u64 v[224:225], v[226:227], 0, s[12:13]
	s_addc_u32 s25, s31, 0
	s_add_i32 s30, s72, s37
	global_load_lds_dwordx4 v[224:225], off
	s_waitcnt vmcnt(4)
	s_waitcnt lgkmcnt(0)
	s_barrier
	s_setprio 1
	s_waitcnt lgkmcnt(0)
	v_mfma_f32_16x16x32_bf16 v[62:65], v[150:153], v[192:195], v[62:65]
	v_mfma_f32_16x16x32_bf16 v[58:61], v[168:171], v[192:195], v[58:61]
	v_lshl_add_u64 v[224:225], s[24:25], 0, v[134:135]
	s_mov_b32 m0, s30
	s_nop 0
	global_load_lds_dwordx4 v[224:225], off
	v_mfma_f32_16x16x32_bf16 v[46:49], v[150:153], v[200:203], v[46:49]
	v_mfma_f32_16x16x32_bf16 v[42:45], v[168:171], v[200:203], v[42:45]
	v_mfma_f32_16x16x32_bf16 v[30:33], v[150:153], v[208:211], v[30:33]
	v_mfma_f32_16x16x32_bf16 v[26:29], v[168:171], v[208:211], v[26:29]
	v_mfma_f32_16x16x32_bf16 v[14:17], v[150:153], v[216:219], v[14:17]
	v_mfma_f32_16x16x32_bf16 v[10:13], v[168:171], v[216:219], v[10:13]
	v_mfma_f32_16x16x32_bf16 v[62:65], v[164:167], v[196:199], v[62:65]
	v_mfma_f32_16x16x32_bf16 v[58:61], v[172:175], v[196:199], v[58:61]
	v_lshl_add_u64 v[224:225], s[24:25], 0, v[130:131]
	s_add_i32 m0, s30, 0x2000
	s_nop 0
	global_load_lds_dwordx4 v[224:225], off
	v_mfma_f32_16x16x32_bf16 v[46:49], v[164:167], v[204:207], v[46:49]
	v_mfma_f32_16x16x32_bf16 v[42:45], v[172:175], v[204:207], v[42:45]
	v_mfma_f32_16x16x32_bf16 v[30:33], v[164:167], v[212:215], v[30:33]
	v_mfma_f32_16x16x32_bf16 v[26:29], v[172:175], v[212:215], v[26:29]
	v_mfma_f32_16x16x32_bf16 v[14:17], v[164:167], v[220:223], v[14:17]
	v_mfma_f32_16x16x32_bf16 v[10:13], v[172:175], v[220:223], v[10:13]
	s_setprio 0
	s_setprio 1
	v_mfma_f32_16x16x32_bf16 v[54:57], v[176:179], v[192:195], v[54:57]
	v_mfma_f32_16x16x32_bf16 v[50:53], v[184:187], v[192:195], v[50:53]
	v_lshl_add_u64 v[224:225], s[28:29], 0, v[136:137]
	s_mov_b32 m0, s44
	s_nop 0
	global_load_lds_dwordx4 v[224:225], off
	v_mfma_f32_16x16x32_bf16 v[38:41], v[176:179], v[200:203], v[38:41]
	v_mfma_f32_16x16x32_bf16 v[34:37], v[184:187], v[200:203], v[34:37]
	v_mfma_f32_16x16x32_bf16 v[22:25], v[176:179], v[208:211], v[22:25]
	v_mfma_f32_16x16x32_bf16 v[18:21], v[184:187], v[208:211], v[18:21]
	v_mfma_f32_16x16x32_bf16 v[6:9], v[176:179], v[216:219], v[6:9]
	v_mfma_f32_16x16x32_bf16 v[2:5], v[184:187], v[216:219], v[2:5]
	v_mfma_f32_16x16x32_bf16 v[54:57], v[180:183], v[196:199], v[54:57]
	v_mfma_f32_16x16x32_bf16 v[50:53], v[188:191], v[196:199], v[50:53]
	v_lshl_add_u64 v[224:225], s[28:29], 0, v[132:133]
	s_mov_b32 m0, s45
	s_nop 0
	global_load_lds_dwordx4 v[224:225], off
	v_mfma_f32_16x16x32_bf16 v[38:41], v[180:183], v[204:207], v[38:41]
	v_mfma_f32_16x16x32_bf16 v[34:37], v[188:191], v[204:207], v[34:37]
	v_mfma_f32_16x16x32_bf16 v[22:25], v[180:183], v[212:215], v[22:25]
	v_mfma_f32_16x16x32_bf16 v[18:21], v[188:191], v[212:215], v[18:21]
	v_mfma_f32_16x16x32_bf16 v[6:9], v[180:183], v[220:223], v[6:9]
	v_mfma_f32_16x16x32_bf16 v[2:5], v[188:191], v[220:223], v[2:5]
	s_setprio 0
	s_barrier
	s_add_i32 s70, s70, 2
	s_add_u32 s68, s68, 0x100
	s_addc_u32 s69, s69, 0
	s_cmp_gt_u32 s70, 5
	s_mov_b64 s[24:25], s[26:27]
	s_cbranch_scc0 .LBB0_677
	s_and_b64 vcc, exec, s[14:15]
	s_cbranch_vccz .LBB0_680
	s_barrier

; #define PG8_STAGE(bufoff, gbase, voff) do { _Pragma("unroll") for (int _i = 0; _i < 2; ++_i) \
;         __builtin_amdgcn_global_load_lds((const unsigned*)((const char*)(gbase) + (voff)[_i]), (PG8_LAS unsigned*)(lds + (bufoff) + ldsw + _i * 8192), 16, 0, 0); } while (0)
; #define PG8_LDA(dst, b, h) do { _Pragma("unroll") for (int m = 0; m < 4; ++m) _Pragma("unroll") for (int k = 0; k < 2; ++k) dst[m][k] = *(const PG8_LAS bf16x8*)(lds + PG8_SA(b, h) + aoff + m * 2048 + k * 1024); } while (0)
; #define PG8_LDB(dst, b, h) do { _Pragma("unroll") for (int n = 0; n < 2; ++n) _Pragma("unroll") for (int k = 0; k < 2; ++k) dst[n][k] = *(const PG8_LAS bf16x8*)(lds + PG8_SB(b, h) + boff + n * 2048 + k * 1024); } while (0)
; #define PG8_MMA(ai, bj, At, Bt) do { __builtin_amdgcn_s_setprio(1); _Pragma("unroll") for (int m = 0; m < 4; ++m) _Pragma("unroll") for (int n = 0; n < 2; ++n) _Pragma("unroll") for (int k = 0; k < 2; ++k) \
;         acc[ai][bj][m][n] = __builtin_amdgcn_mfma_f32_16x16x32_bf16(Bt[n][k], At[m][k], acc[ai][bj][m][n], 0, 0, 0); __builtin_amdgcn_s_setprio(0); } while (0)
; #define PG8_WAIT_V(n) asm volatile("s_waitcnt vmcnt(" #n ")" ::: "memory")
; #define PG8_WAIT_L(n) asm volatile("s_waitcnt lgkmcnt(" #n ")" ::: "memory")
; #define PG8_BAR __builtin_amdgcn_s_barrier()
; #define PG8_SCHED __builtin_amdgcn_sched_barrier(0)
; template <class Epi, class Sched, bool ALIGN_EPI = false, bool SP2 = false, bool AGM = false  >
; __device__ __forceinline__ void gemm_phase(PG8_LAS unsigned char* lds, const Gemm g, const Sched& S, const Epi& E) {
;     ...
;             PG8_LDB(B0, 0, 0); PG8_LDB(B1, 0, 1); PG8_SCHED; PG8_LDA(At, 0, 0); PG8_STAGE(PG8_SA(1, 1), a1 + hstepA, voffA);
;             PG8_WAIT_V(8); PG8_WAIT_L(0); PG8_BAR; PG8_MMA(0, 0, At, B0); PG8_MMA(0, 1, At, B1); PG8_BAR; PG8_SCHED;
;             PG8_LDA(At, 0, 1); PG8_STAGE(PG8_SB(0, 0), b2, voffB); PG8_STAGE(PG8_SB(0, 1), b2 + hstep, voffB); PG8_STAGE(PG8_SA(0, 0), a2, voffA);
;             PG8_WAIT_V(8); PG8_WAIT_L(0); PG8_BAR; PG8_MMA(1, 0, At, B0); PG8_MMA(1, 1, At, B1); PG8_BAR; PG8_SCHED;
.LBB0_783:
	ds_read_b128 v[130:133], v186
	ds_read_b128 v[134:137], v186 offset:1024
	ds_read_b128 v[138:141], v186 offset:2048
	ds_read_b128 v[142:145], v186 offset:3072
	ds_read_b128 v[146:149], v187
	ds_read_b128 v[150:153], v187 offset:1024
	ds_read_b128 v[178:181], v187 offset:2048
	ds_read_b128 v[194:197], v187 offset:3072
	s_add_u32 s40, s38, 0xfffc0080
	s_addc_u32 s41, s39, -1
	s_cmp_eq_u32 s75, 12
	s_cselect_b32 s43, s5, s41
	s_cselect_b32 s42, s31, s40
	s_cselect_b32 s41, s29, s74
	s_cselect_b32 s40, s33, s62
	v_lshl_add_u64 v[182:183], s[38:39], 0, v[170:171]
	s_add_i32 m0, s44, 0xc000
	ds_read_b128 v[198:201], v188
	ds_read_b128 v[202:205], v188 offset:1024
	ds_read_b128 v[206:209], v188 offset:2048
	ds_read_b128 v[210:213], v188 offset:3072
	ds_read_b128 v[214:217], v188 offset:4096
	ds_read_b128 v[218:221], v188 offset:5120
	ds_read_b128 v[222:225], v188 offset:6144
	ds_read_b128 v[226:229], v188 offset:7168
	global_load_lds_dwordx4 v[182:183], off
	v_lshl_add_u64 v[182:183], s[38:39], 0, v[172:173]
	s_add_i32 m0, s44, 0xe000
	s_nop 0
	global_load_lds_dwordx4 v[182:183], off
	s_waitcnt vmcnt(8)
	s_waitcnt lgkmcnt(0)
	s_barrier
	s_setprio 1
	s_waitcnt lgkmcnt(0)
	v_mfma_f32_16x16x32_bf16 v[126:129], v[130:133], v[198:201], v[126:129]
	v_mfma_f32_16x16x32_bf16 v[122:125], v[138:141], v[198:201], v[122:125]
	v_mfma_f32_16x16x32_bf16 v[110:113], v[130:133], v[206:209], v[110:113]
	v_mfma_f32_16x16x32_bf16 v[106:109], v[138:141], v[206:209], v[106:109]
	v_mfma_f32_16x16x32_bf16 v[94:97], v[130:133], v[214:217], v[94:97]
	v_mfma_f32_16x16x32_bf16 v[90:93], v[138:141], v[214:217], v[90:93]
	v_mfma_f32_16x16x32_bf16 v[78:81], v[130:133], v[222:225], v[78:81]
	v_mfma_f32_16x16x32_bf16 v[74:77], v[138:141], v[222:225], v[74:77]
	v_mfma_f32_16x16x32_bf16 v[126:129], v[134:137], v[202:205], v[126:129]
	v_mfma_f32_16x16x32_bf16 v[122:125], v[142:145], v[202:205], v[122:125]
	v_mfma_f32_16x16x32_bf16 v[110:113], v[134:137], v[210:213], v[110:113]
	v_mfma_f32_16x16x32_bf16 v[106:109], v[142:145], v[210:213], v[106:109]
	v_mfma_f32_16x16x32_bf16 v[94:97], v[134:137], v[218:221], v[94:97]
	v_mfma_f32_16x16x32_bf16 v[90:93], v[142:145], v[218:221], v[90:93]
	v_mfma_f32_16x16x32_bf16 v[78:81], v[134:137], v[226:229], v[78:81]
	v_mfma_f32_16x16x32_bf16 v[74:77], v[142:145], v[226:229], v[74:77]
	s_setprio 0
	s_setprio 1
	v_mfma_f32_16x16x32_bf16 v[118:121], v[146:149], v[198:201], v[118:121]
	v_mfma_f32_16x16x32_bf16 v[114:117], v[178:181], v[198:201], v[114:117]
	v_mfma_f32_16x16x32_bf16 v[102:105], v[146:149], v[206:209], v[102:105]
	v_mfma_f32_16x16x32_bf16 v[98:101], v[178:181], v[206:209], v[98:101]
	v_mfma_f32_16x16x32_bf16 v[86:89], v[146:149], v[214:217], v[86:89]
	v_mfma_f32_16x16x32_bf16 v[82:85], v[178:181], v[214:217], v[82:85]
	v_mfma_f32_16x16x32_bf16 v[70:73], v[146:149], v[222:225], v[70:73]
	v_mfma_f32_16x16x32_bf16 v[66:69], v[178:181], v[222:225], v[66:69]
	v_mfma_f32_16x16x32_bf16 v[118:121], v[150:153], v[202:205], v[118:121]
	v_mfma_f32_16x16x32_bf16 v[114:117], v[194:197], v[202:205], v[114:117]
	v_mfma_f32_16x16x32_bf16 v[102:105], v[150:153], v[210:213], v[102:105]
	v_mfma_f32_16x16x32_bf16 v[98:101], v[194:197], v[210:213], v[98:101]
	v_mfma_f32_16x16x32_bf16 v[86:89], v[150:153], v[218:221], v[86:89]
	v_mfma_f32_16x16x32_bf16 v[82:85], v[194:197], v[218:221], v[82:85]
	v_mfma_f32_16x16x32_bf16 v[70:73], v[150:153], v[226:229], v[70:73]
	v_mfma_f32_16x16x32_bf16 v[66:69], v[194:197], v[226:229], v[66:69]
	s_setprio 0
	s_barrier
	s_add_i32 s76, s71, s3
	v_lshl_add_u64 v[182:183], s[40:41], 0, v[158:159]
	s_mov_b32 m0, s76
	ds_read_b128 v[198:201], v188 offset:16384
	ds_read_b128 v[202:205], v188 offset:17408
	ds_read_b128 v[206:209], v188 offset:18432
	ds_read_b128 v[210:213], v188 offset:19456
	ds_read_b128 v[214:217], v188 offset:20480
	ds_read_b128 v[218:221], v188 offset:21504
	ds_read_b128 v[222:225], v188 offset:22528
	ds_read_b128 v[226:229], v188 offset:23552
	global_load_lds_dwordx4 v[182:183], off
	s_add_i32 m0, s76, 0x2000
	s_add_u32 s76, s40, 0x40000
	v_lshl_add_u64 v[230:231], s[40:41], 0, v[162:163]
	s_addc_u32 s77, s41, 0
	s_add_i32 s78, s72, s3
	global_load_lds_dwordx4 v[230:231], off
	s_waitcnt vmcnt(4)
	s_waitcnt lgkmcnt(0)
	s_barrier
	s_setprio 1
	s_waitcnt lgkmcnt(0)
	v_mfma_f32_16x16x32_bf16 v[62:65], v[130:133], v[198:201], v[62:65]
	v_mfma_f32_16x16x32_bf16 v[58:61], v[138:141], v[198:201], v[58:61]
	v_lshl_add_u64 v[232:233], s[76:77], 0, v[158:159]
	s_mov_b32 m0, s78
	v_lshl_add_u64 v[234:235], s[42:43], 0, v[160:161]
	global_load_lds_dwordx4 v[232:233], off
	v_mfma_f32_16x16x32_bf16 v[46:49], v[130:133], v[206:209], v[46:49]
	v_mfma_f32_16x16x32_bf16 v[42:45], v[138:141], v[206:209], v[42:45]
	v_mfma_f32_16x16x32_bf16 v[30:33], v[130:133], v[214:217], v[30:33]
	v_mfma_f32_16x16x32_bf16 v[26:29], v[138:141], v[214:217], v[26:29]
	v_mfma_f32_16x16x32_bf16 v[14:17], v[130:133], v[222:225], v[14:17]
	v_mfma_f32_16x16x32_bf16 v[10:13], v[138:141], v[222:225], v[10:13]
	v_mfma_f32_16x16x32_bf16 v[62:65], v[134:137], v[202:205], v[62:65]
	v_mfma_f32_16x16x32_bf16 v[58:61], v[142:145], v[202:205], v[58:61]
	v_lshl_add_u64 v[232:233], s[76:77], 0, v[162:163]
	s_add_i32 m0, s78, 0x2000
	s_nop 0
	global_load_lds_dwordx4 v[232:233], off
	v_mfma_f32_16x16x32_bf16 v[46:49], v[134:137], v[210:213], v[46:49]
	v_mfma_f32_16x16x32_bf16 v[42:45], v[142:145], v[210:213], v[42:45]
	v_mfma_f32_16x16x32_bf16 v[30:33], v[134:137], v[218:221], v[30:33]
	v_mfma_f32_16x16x32_bf16 v[26:29], v[142:145], v[218:221], v[26:29]
	v_mfma_f32_16x16x32_bf16 v[14:17], v[134:137], v[226:229], v[14:17]
	v_mfma_f32_16x16x32_bf16 v[10:13], v[142:145], v[226:229], v[10:13]
	s_setprio 0
	s_setprio 1
	v_mfma_f32_16x16x32_bf16 v[54:57], v[146:149], v[198:201], v[54:57]
	v_mfma_f32_16x16x32_bf16 v[50:53], v[178:181], v[198:201], v[50:53]
	v_lshl_add_u64 v[232:233], s[42:43], 0, v[156:157]
	s_mov_b32 m0, s44
	s_nop 0
	global_load_lds_dwordx4 v[232:233], off
	v_mfma_f32_16x16x32_bf16 v[38:41], v[146:149], v[206:209], v[38:41]
	v_mfma_f32_16x16x32_bf16 v[34:37], v[178:181], v[206:209], v[34:37]
	v_mfma_f32_16x16x32_bf16 v[22:25], v[146:149], v[214:217], v[22:25]
	v_mfma_f32_16x16x32_bf16 v[18:21], v[178:181], v[214:217], v[18:21]
	v_mfma_f32_16x16x32_bf16 v[6:9], v[146:149], v[222:225], v[6:9]
	v_mfma_f32_16x16x32_bf16 v[2:5], v[178:181], v[222:225], v[2:5]
	v_mfma_f32_16x16x32_bf16 v[54:57], v[150:153], v[202:205], v[54:57]
	v_mfma_f32_16x16x32_bf16 v[50:53], v[194:197], v[202:205], v[50:53]
	s_mov_b32 m0, s45
	s_nop 0
	global_load_lds_dwordx4 v[234:235], off
	v_mfma_f32_16x16x32_bf16 v[38:41], v[150:153], v[210:213], v[38:41]
	v_mfma_f32_16x16x32_bf16 v[34:37], v[194:197], v[210:213], v[34:37]
	v_mfma_f32_16x16x32_bf16 v[22:25], v[150:153], v[218:221], v[22:25]
	v_mfma_f32_16x16x32_bf16 v[18:21], v[194:197], v[218:221], v[18:21]
	v_mfma_f32_16x16x32_bf16 v[6:9], v[150:153], v[226:229], v[6:9]
	v_mfma_f32_16x16x32_bf16 v[2:5], v[194:197], v[226:229], v[2:5]
	s_setprio 0
	s_barrier
; #define PG8_STAGE(bufoff, gbase, voff) do { _Pragma("unroll") for (int _i = 0; _i < 2; ++_i) \
;         __builtin_amdgcn_global_load_lds((const unsigned*)((const char*)(gbase) + (voff)[_i]), (PG8_LAS unsigned*)(lds + (bufoff) + ldsw + _i * 8192), 16, 0, 0); } while (0)
; #define PG8_LDA(dst, b, h) do { _Pragma("unroll") for (int m = 0; m < 4; ++m) _Pragma("unroll") for (int k = 0; k < 2; ++k) dst[m][k] = *(const PG8_LAS bf16x8*)(lds + PG8_SA(b, h) + aoff + m * 2048 + k * 1024); } while (0)
; #define PG8_LDB(dst, b, h) do { _Pragma("unroll") for (int n = 0; n < 2; ++n) _Pragma("unroll") for (int k = 0; k < 2; ++k) dst[n][k] = *(const PG8_LAS bf16x8*)(lds + PG8_SB(b, h) + boff + n * 2048 + k * 1024); } while (0)
; #define PG8_MMA(ai, bj, At, Bt) do { __builtin_amdgcn_s_setprio(1); _Pragma("unroll") for (int m = 0; m < 4; ++m) _Pragma("unroll") for (int n = 0; n < 2; ++n) _Pragma("unroll") for (int k = 0; k < 2; ++k) \
;         acc[ai][bj][m][n] = __builtin_amdgcn_mfma_f32_16x16x32_bf16(Bt[n][k], At[m][k], acc[ai][bj][m][n], 0, 0, 0); __builtin_amdgcn_s_setprio(0); } while (0)
; #define PG8_WAIT_V(n) asm volatile("s_waitcnt vmcnt(" #n ")" ::: "memory")
; #define PG8_WAIT_L(n) asm volatile("s_waitcnt lgkmcnt(" #n ")" ::: "memory")
; #define PG8_BAR __builtin_amdgcn_s_barrier()
; #define PG8_SCHED __builtin_amdgcn_sched_barrier(0)
; template <class Epi, class Sched, bool ALIGN_EPI = false, bool SP2 = false, bool AGM = false  >
; __device__ __forceinline__ void gemm_phase(PG8_LAS unsigned char* lds, const Gemm g, const Sched& S, const Epi& E) {
;     ...
;             PG8_LDB(B0, 1, 0); PG8_LDB(B1, 1, 1); PG8_SCHED; PG8_LDA(At, 1, 0); PG8_STAGE(PG8_SA(0, 1), a2 + hstepA, voffA);
;             PG8_WAIT_V(8); PG8_WAIT_L(0); PG8_BAR; PG8_MMA(0, 0, At, B0); PG8_MMA(0, 1, At, B1); PG8_BAR; PG8_SCHED;
	s_add_i32 s76, 0, 0x18000
	s_add_i32 s77, 0, 0x1c000
	v_add_u32_e32 v142, s76, v184
	v_add_u32_e32 v164, s77, v184
	ds_read_b128 v[130:133], v142
	ds_read_b128 v[134:137], v142 offset:1024
	ds_read_b128 v[138:141], v142 offset:2048
	ds_read_b128 v[142:145], v142 offset:3072
	ds_read_b128 v[146:149], v164
	ds_read_b128 v[150:153], v164 offset:1024
	ds_read_b128 v[178:181], v164 offset:2048
	ds_read_b128 v[194:197], v164 offset:3072
	s_add_u32 s42, s42, 0x40000
	s_addc_u32 s43, s43, 0
	s_mov_b32 m0, s53
	v_lshl_add_u64 v[236:237], s[42:43], 0, v[156:157]
	ds_read_b128 v[198:201], v188 offset:32768
	ds_read_b128 v[202:205], v188 offset:33792
	ds_read_b128 v[206:209], v188 offset:34816
	ds_read_b128 v[210:213], v188 offset:35840
	ds_read_b128 v[214:217], v188 offset:36864
	ds_read_b128 v[218:221], v188 offset:37888
	ds_read_b128 v[222:225], v188 offset:38912
	ds_read_b128 v[226:229], v188 offset:39936
	global_load_lds_dwordx4 v[236:237], off
	v_lshl_add_u64 v[236:237], s[42:43], 0, v[160:161]
	s_mov_b32 m0, s54
	s_nop 0
	global_load_lds_dwordx4 v[236:237], off
	s_waitcnt vmcnt(8)
	s_waitcnt lgkmcnt(0)
	s_barrier
	s_setprio 1
	s_waitcnt lgkmcnt(0)
	v_mfma_f32_16x16x32_bf16 v[126:129], v[130:133], v[198:201], v[126:129]
	v_mfma_f32_16x16x32_bf16 v[122:125], v[138:141], v[198:201], v[122:125]
	v_mfma_f32_16x16x32_bf16 v[110:113], v[130:133], v[206:209], v[110:113]
	v_mfma_f32_16x16x32_bf16 v[106:109], v[138:141], v[206:209], v[106:109]
	v_mfma_f32_16x16x32_bf16 v[94:97], v[130:133], v[214:217], v[94:97]
	v_mfma_f32_16x16x32_bf16 v[90:93], v[138:141], v[214:217], v[90:93]
	v_mfma_f32_16x16x32_bf16 v[78:81], v[130:133], v[222:225], v[78:81]
	v_mfma_f32_16x16x32_bf16 v[74:77], v[138:141], v[222:225], v[74:77]
	v_mfma_f32_16x16x32_bf16 v[126:129], v[134:137], v[202:205], v[126:129]
	v_mfma_f32_16x16x32_bf16 v[122:125], v[142:145], v[202:205], v[122:125]
	v_mfma_f32_16x16x32_bf16 v[110:113], v[134:137], v[210:213], v[110:113]
	v_mfma_f32_16x16x32_bf16 v[106:109], v[142:145], v[210:213], v[106:109]
	v_mfma_f32_16x16x32_bf16 v[94:97], v[134:137], v[218:221], v[94:97]
	v_mfma_f32_16x16x32_bf16 v[90:93], v[142:145], v[218:221], v[90:93]
	v_mfma_f32_16x16x32_bf16 v[78:81], v[134:137], v[226:229], v[78:81]
	v_mfma_f32_16x16x32_bf16 v[74:77], v[142:145], v[226:229], v[74:77]
	s_setprio 0
	s_setprio 1
	v_mfma_f32_16x16x32_bf16 v[118:121], v[146:149], v[198:201], v[118:121]
	v_mfma_f32_16x16x32_bf16 v[114:117], v[178:181], v[198:201], v[114:117]
	v_mfma_f32_16x16x32_bf16 v[102:105], v[146:149], v[206:209], v[102:105]
	v_mfma_f32_16x16x32_bf16 v[98:101], v[178:181], v[206:209], v[98:101]
	v_mfma_f32_16x16x32_bf16 v[86:89], v[146:149], v[214:217], v[86:89]
	v_mfma_f32_16x16x32_bf16 v[82:85], v[178:181], v[214:217], v[82:85]
	v_mfma_f32_16x16x32_bf16 v[70:73], v[146:149], v[222:225], v[70:73]
	v_mfma_f32_16x16x32_bf16 v[66:69], v[178:181], v[222:225], v[66:69]
	v_mfma_f32_16x16x32_bf16 v[118:121], v[150:153], v[202:205], v[118:121]
	v_mfma_f32_16x16x32_bf16 v[114:117], v[194:197], v[202:205], v[114:117]
	v_mfma_f32_16x16x32_bf16 v[102:105], v[150:153], v[210:213], v[102:105]
	v_mfma_f32_16x16x32_bf16 v[98:101], v[194:197], v[210:213], v[98:101]
	v_mfma_f32_16x16x32_bf16 v[86:89], v[150:153], v[218:221], v[86:89]
	v_mfma_f32_16x16x32_bf16 v[82:85], v[194:197], v[218:221], v[82:85]
	v_mfma_f32_16x16x32_bf16 v[70:73], v[150:153], v[226:229], v[70:73]
	v_mfma_f32_16x16x32_bf16 v[66:69], v[194:197], v[226:229], v[66:69]
	s_setprio 0
	s_barrier
; #define PG8_STAGE(bufoff, gbase, voff) do { _Pragma("unroll") for (int _i = 0; _i < 2; ++_i) \
;         __builtin_amdgcn_global_load_lds((const unsigned*)((const char*)(gbase) + (voff)[_i]), (PG8_LAS unsigned*)(lds + (bufoff) + ldsw + _i * 8192), 16, 0, 0); } while (0)
; #define PG8_LDA(dst, b, h) do { _Pragma("unroll") for (int m = 0; m < 4; ++m) _Pragma("unroll") for (int k = 0; k < 2; ++k) dst[m][k] = *(const PG8_LAS bf16x8*)(lds + PG8_SA(b, h) + aoff + m * 2048 + k * 1024); } while (0)
; #define PG8_MMA(ai, bj, At, Bt) do { __builtin_amdgcn_s_setprio(1); _Pragma("unroll") for (int m = 0; m < 4; ++m) _Pragma("unroll") for (int n = 0; n < 2; ++n) _Pragma("unroll") for (int k = 0; k < 2; ++k) \
;         acc[ai][bj][m][n] = __builtin_amdgcn_mfma_f32_16x16x32_bf16(Bt[n][k], At[m][k], acc[ai][bj][m][n], 0, 0, 0); __builtin_amdgcn_s_setprio(0); } while (0)
; #define PG8_WAIT_V(n) asm volatile("s_waitcnt vmcnt(" #n ")" ::: "memory")
; #define PG8_WAIT_L(n) asm volatile("s_waitcnt lgkmcnt(" #n ")" ::: "memory")
; #define PG8_BAR __builtin_amdgcn_s_barrier()
; #define PG8_SCHED __builtin_amdgcn_sched_barrier(0)
; template <class Epi, class Sched, bool ALIGN_EPI = false, bool SP2 = false, bool AGM = false  >
; __device__ __forceinline__ void gemm_phase(PG8_LAS unsigned char* lds, const Gemm g, const Sched& S, const Epi& E) {
;     ...
;             PG8_LDA(At, 1, 1); PG8_STAGE(PG8_SB(1, 0), b3, voffB); PG8_STAGE(PG8_SB(1, 1), b3 + hstep, voffB); PG8_STAGE(PG8_SA(1, 0), a3, voffA);
;             PG8_WAIT_V(8); PG8_WAIT_L(0); PG8_BAR; PG8_MMA(1, 0, At, B0); PG8_MMA(1, 1, At, B1); PG8_BAR; PG8_SCHED;
;     ...
;         if constexpr (ALIGN_EPI) { if (wr == 0) PG8_BAR; }
	s_add_i32 s42, s76, s3
	v_lshl_add_u64 v[182:183], v[182:183], 0, s[24:25]
	s_mov_b32 m0, s42
	ds_read_b128 v[198:201], v188 offset:49152
	ds_read_b128 v[202:205], v188 offset:50176
	ds_read_b128 v[206:209], v188 offset:51200
	ds_read_b128 v[210:213], v188 offset:52224
	ds_read_b128 v[214:217], v188 offset:53248
	ds_read_b128 v[218:221], v188 offset:54272
	ds_read_b128 v[222:225], v188 offset:55296
	ds_read_b128 v[226:229], v188 offset:56320
	global_load_lds_dwordx4 v[182:183], off
	s_add_i32 m0, s42, 0x2000
	s_add_u32 s40, s40, 0x40080
	v_lshl_add_u64 v[182:183], v[230:231], 0, s[24:25]
	s_addc_u32 s41, s41, 0
	s_add_i32 s42, s77, s3
	global_load_lds_dwordx4 v[182:183], off
	s_waitcnt vmcnt(4)
	s_waitcnt lgkmcnt(0)
	s_barrier
	s_setprio 1
	s_waitcnt lgkmcnt(0)
	v_mfma_f32_16x16x32_bf16 v[62:65], v[130:133], v[198:201], v[62:65]
	v_mfma_f32_16x16x32_bf16 v[58:61], v[138:141], v[198:201], v[58:61]
	v_lshl_add_u64 v[182:183], s[40:41], 0, v[158:159]
	s_mov_b32 m0, s42
	s_nop 0
	global_load_lds_dwordx4 v[182:183], off
	v_mfma_f32_16x16x32_bf16 v[46:49], v[130:133], v[206:209], v[46:49]
	v_mfma_f32_16x16x32_bf16 v[42:45], v[138:141], v[206:209], v[42:45]
	v_mfma_f32_16x16x32_bf16 v[30:33], v[130:133], v[214:217], v[30:33]
	v_mfma_f32_16x16x32_bf16 v[26:29], v[138:141], v[214:217], v[26:29]
	v_mfma_f32_16x16x32_bf16 v[14:17], v[130:133], v[222:225], v[14:17]
	v_mfma_f32_16x16x32_bf16 v[10:13], v[138:141], v[222:225], v[10:13]
	v_mfma_f32_16x16x32_bf16 v[62:65], v[134:137], v[202:205], v[62:65]
	v_mfma_f32_16x16x32_bf16 v[58:61], v[142:145], v[202:205], v[58:61]
	v_lshl_add_u64 v[182:183], s[40:41], 0, v[162:163]
	s_add_i32 m0, s42, 0x2000
	s_nop 0
	global_load_lds_dwordx4 v[182:183], off
	v_mfma_f32_16x16x32_bf16 v[46:49], v[134:137], v[210:213], v[46:49]
	v_mfma_f32_16x16x32_bf16 v[42:45], v[142:145], v[210:213], v[42:45]
	v_mfma_f32_16x16x32_bf16 v[30:33], v[134:137], v[218:221], v[30:33]
	v_mfma_f32_16x16x32_bf16 v[26:29], v[142:145], v[218:221], v[26:29]
	v_mfma_f32_16x16x32_bf16 v[14:17], v[134:137], v[226:229], v[14:17]
	v_mfma_f32_16x16x32_bf16 v[10:13], v[142:145], v[226:229], v[10:13]
	s_setprio 0
	s_setprio 1
	v_mfma_f32_16x16x32_bf16 v[54:57], v[146:149], v[198:201], v[54:57]
	v_mfma_f32_16x16x32_bf16 v[50:53], v[178:181], v[198:201], v[50:53]
	v_lshl_add_u64 v[182:183], v[232:233], 0, s[24:25]
	s_mov_b32 m0, s60
	s_nop 0
	global_load_lds_dwordx4 v[182:183], off
	v_mfma_f32_16x16x32_bf16 v[38:41], v[146:149], v[206:209], v[38:41]
	v_mfma_f32_16x16x32_bf16 v[34:37], v[178:181], v[206:209], v[34:37]
	v_mfma_f32_16x16x32_bf16 v[22:25], v[146:149], v[214:217], v[22:25]
	v_mfma_f32_16x16x32_bf16 v[18:21], v[178:181], v[214:217], v[18:21]
	v_mfma_f32_16x16x32_bf16 v[6:9], v[146:149], v[222:225], v[6:9]
	v_mfma_f32_16x16x32_bf16 v[2:5], v[178:181], v[222:225], v[2:5]
	v_mfma_f32_16x16x32_bf16 v[54:57], v[150:153], v[202:205], v[54:57]
	v_mfma_f32_16x16x32_bf16 v[50:53], v[194:197], v[202:205], v[50:53]
	v_lshl_add_u64 v[182:183], v[234:235], 0, s[24:25]
	s_mov_b32 m0, s61
	s_nop 0
	global_load_lds_dwordx4 v[182:183], off
	v_mfma_f32_16x16x32_bf16 v[38:41], v[150:153], v[210:213], v[38:41]
	v_mfma_f32_16x16x32_bf16 v[34:37], v[194:197], v[210:213], v[34:37]
	v_mfma_f32_16x16x32_bf16 v[22:25], v[150:153], v[218:221], v[22:25]
	v_mfma_f32_16x16x32_bf16 v[18:21], v[194:197], v[218:221], v[18:21]
	v_mfma_f32_16x16x32_bf16 v[6:9], v[150:153], v[226:229], v[6:9]
	v_mfma_f32_16x16x32_bf16 v[2:5], v[194:197], v[226:229], v[2:5]
	s_setprio 0
	s_barrier
	s_add_i32 s75, s75, 2
	s_add_u32 s38, s38, 0x100
	s_addc_u32 s39, s39, 0
	s_add_u32 s62, s62, 0x100
	s_addc_u32 s74, s74, 0
	s_cmp_gt_u32 s75, 13
	s_cbranch_scc0 .LBB0_783
	s_and_b64 vcc, exec, s[26:27]
	s_cbranch_vccz .LBB0_786
	s_barrier

; #define PG8_STAGE(bufoff, gbase, voff) do { _Pragma("unroll") for (int _i = 0; _i < 2; ++_i) \
;         __builtin_amdgcn_global_load_lds((const unsigned*)((const char*)(gbase) + (voff)[_i]), (PG8_LAS unsigned*)(lds + (bufoff) + ldsw + _i * 8192), 16, 0, 0); } while (0)
; #define PG8_LDA(dst, b, h) do { _Pragma("unroll") for (int m = 0; m < 4; ++m) _Pragma("unroll") for (int k = 0; k < 2; ++k) dst[m][k] = *(const PG8_LAS bf16x8*)(lds + PG8_SA(b, h) + aoff + m * 2048 + k * 1024); } while (0)
; #define PG8_LDB(dst, b, h) do { _Pragma("unroll") for (int n = 0; n < 2; ++n) _Pragma("unroll") for (int k = 0; k < 2; ++k) dst[n][k] = *(const PG8_LAS bf16x8*)(lds + PG8_SB(b, h) + boff + n * 2048 + k * 1024); } while (0)
; #define PG8_MMA(ai, bj, At, Bt) do { __builtin_amdgcn_s_setprio(1); _Pragma("unroll") for (int m = 0; m < 4; ++m) _Pragma("unroll") for (int n = 0; n < 2; ++n) _Pragma("unroll") for (int k = 0; k < 2; ++k) \
;         acc[ai][bj][m][n] = __builtin_amdgcn_mfma_f32_16x16x32_bf16(Bt[n][k], At[m][k], acc[ai][bj][m][n], 0, 0, 0); __builtin_amdgcn_s_setprio(0); } while (0)
; template <class Epi, class Sched, bool ALIGN_EPI = false, bool SP2 = false, bool AGM = false  >
; __device__ __forceinline__ void gemm_phase(PG8_LAS unsigned char* lds, const Gemm g, const Sched& S, const Epi& E) {
;     ...
;         const bool has_next = S.next(ui + 1, nxt);
;         const char* nA = has_next ? (const char*)g.A + (size_t)nxt.pm * tstepA : cA; const char* nB = has_next ? (const char*)g.Bt + (size_t)nxt.pn * tstep : cB;
;         for (int t = 0; t < nt; t += 2) {
;             const bool last = (t == nt - 2);
;             const char* a1 = cA + (size_t)(t + 1) * kstepA;
;             const char* a2 = last ? nA : cA + (size_t)(t + 2) * kstepA; const char* b2 = last ? nB : cB + (size_t)(t + 2) * kstep;
;             const char* a3 = a2 + kstepA; const char* b3 = b2 + kstep;
;             if (last && has_next) S.a_ready(nxt);
;             if constexpr (SP2) {
;             PG8_LDB(B0, 0, 0); PG8_LDB(B1, 0, 1); PG8_SCHED; PG8_LDA(At, 0, 0); PG8_STAGE(PG8_SA(1, 1), a1 + hstepA, voffA);
;             PG8_WAIT_V(8); PG8_WAIT_L(0); PG8_BAR; PG8_MMA(0, 0, At, B0); PG8_MMA(0, 1, At, B1); PG8_BAR; PG8_SCHED;
;             PG8_LDA(At, 0, 1); PG8_STAGE(PG8_SB(0, 0), b2, voffB); PG8_STAGE(PG8_SB(0, 1), b2 + hstep, voffB); PG8_STAGE(PG8_SA(0, 0), a2, voffA);
.LBB0_876:
	s_ashr_i32 s23, s22, 31
	s_lshl_b64 s[24:25], s[22:23], 19
	s_add_u32 s24, s46, s24
	s_addc_u32 s25, s47, s25
	s_and_b64 s[26:27], s[0:1], exec
	s_cselect_b32 s23, s25, s29
	s_cselect_b32 s64, s24, s28
	s_ashr_i32 s21, s20, 31
	s_lshl_b64 s[26:27], s[20:21], 19
	s_add_u32 s26, s10, s26
	s_addc_u32 s27, s11, s27
	s_and_b64 s[34:35], s[0:1], exec
	s_cselect_b32 s21, s27, s31
	s_cselect_b32 s65, s26, s30
	s_add_u32 s28, s28, 0x40080
	s_addc_u32 s29, s29, 0
	s_add_u32 s66, s30, 0x100
	s_addc_u32 s67, s31, 0
	s_mov_b32 s68, -2
	s_waitcnt vmcnt(0)
	s_waitcnt lgkmcnt(0)
	ds_read_b128 v[148:151], v156
	ds_read_b128 v[164:167], v156 offset:1024
	ds_read_b128 v[168:171], v156 offset:2048
	ds_read_b128 v[172:175], v156 offset:3072
	ds_read_b128 v[176:179], v157
	ds_read_b128 v[180:183], v157 offset:1024
	ds_read_b128 v[184:187], v157 offset:2048
	ds_read_b128 v[188:191], v157 offset:3072
	s_add_u32 s30, s28, 0xfffc0080
	s_addc_u32 s31, s29, -1
	s_cmp_eq_u32 s68, 12
	s_cselect_b32 s35, s23, s31
	s_cselect_b32 s34, s64, s30
	s_cselect_b32 s31, s21, s67
	s_cselect_b32 s30, s65, s66
	v_lshl_add_u64 v[224:225], s[28:29], 0, v[140:141]
	s_add_i32 m0, s37, 0xc000
	ds_read_b128 v[192:195], v158
	ds_read_b128 v[196:199], v158 offset:1024
	ds_read_b128 v[200:203], v158 offset:2048
	ds_read_b128 v[204:207], v158 offset:3072
	ds_read_b128 v[208:211], v158 offset:4096
	ds_read_b128 v[212:215], v158 offset:5120
	ds_read_b128 v[216:219], v158 offset:6144
	ds_read_b128 v[220:223], v158 offset:7168
	global_load_lds_dwordx4 v[224:225], off
	v_lshl_add_u64 v[224:225], s[28:29], 0, v[142:143]
	s_add_i32 m0, s37, 0xe000
	s_nop 0
	global_load_lds_dwordx4 v[224:225], off
	s_waitcnt vmcnt(8)
	s_waitcnt lgkmcnt(0)
	s_barrier
	s_setprio 1
	s_waitcnt lgkmcnt(0)
	v_mfma_f32_16x16x32_bf16 v[126:129], v[148:151], v[192:195], 0
	v_mfma_f32_16x16x32_bf16 v[122:125], v[168:171], v[192:195], 0
	v_mfma_f32_16x16x32_bf16 v[110:113], v[148:151], v[200:203], 0
	v_mfma_f32_16x16x32_bf16 v[106:109], v[168:171], v[200:203], 0
	v_mfma_f32_16x16x32_bf16 v[94:97], v[148:151], v[208:211], 0
	v_mfma_f32_16x16x32_bf16 v[90:93], v[168:171], v[208:211], 0
	v_mfma_f32_16x16x32_bf16 v[78:81], v[148:151], v[216:219], 0
	v_mfma_f32_16x16x32_bf16 v[74:77], v[168:171], v[216:219], 0
	v_mfma_f32_16x16x32_bf16 v[126:129], v[164:167], v[196:199], v[126:129]
	v_mfma_f32_16x16x32_bf16 v[122:125], v[172:175], v[196:199], v[122:125]
	v_mfma_f32_16x16x32_bf16 v[110:113], v[164:167], v[204:207], v[110:113]
	v_mfma_f32_16x16x32_bf16 v[106:109], v[172:175], v[204:207], v[106:109]
	v_mfma_f32_16x16x32_bf16 v[94:97], v[164:167], v[212:215], v[94:97]
	v_mfma_f32_16x16x32_bf16 v[90:93], v[172:175], v[212:215], v[90:93]
	v_mfma_f32_16x16x32_bf16 v[78:81], v[164:167], v[220:223], v[78:81]
	v_mfma_f32_16x16x32_bf16 v[74:77], v[172:175], v[220:223], v[74:77]
	s_setprio 0
	s_setprio 1
	v_mfma_f32_16x16x32_bf16 v[118:121], v[176:179], v[192:195], 0
	v_mfma_f32_16x16x32_bf16 v[114:117], v[184:187], v[192:195], 0
	v_mfma_f32_16x16x32_bf16 v[102:105], v[176:179], v[200:203], 0
	v_mfma_f32_16x16x32_bf16 v[98:101], v[184:187], v[200:203], 0
	v_mfma_f32_16x16x32_bf16 v[86:89], v[176:179], v[208:211], 0
	v_mfma_f32_16x16x32_bf16 v[82:85], v[184:187], v[208:211], 0
	v_mfma_f32_16x16x32_bf16 v[70:73], v[176:179], v[216:219], 0
	v_mfma_f32_16x16x32_bf16 v[66:69], v[184:187], v[216:219], 0
	v_mfma_f32_16x16x32_bf16 v[118:121], v[180:183], v[196:199], v[118:121]
	v_mfma_f32_16x16x32_bf16 v[114:117], v[188:191], v[196:199], v[114:117]
	v_mfma_f32_16x16x32_bf16 v[102:105], v[180:183], v[204:207], v[102:105]
	v_mfma_f32_16x16x32_bf16 v[98:101], v[188:191], v[204:207], v[98:101]
	v_mfma_f32_16x16x32_bf16 v[86:89], v[180:183], v[212:215], v[86:89]
	v_mfma_f32_16x16x32_bf16 v[82:85], v[188:191], v[212:215], v[82:85]
	v_mfma_f32_16x16x32_bf16 v[70:73], v[180:183], v[220:223], v[70:73]
	v_mfma_f32_16x16x32_bf16 v[66:69], v[188:191], v[220:223], v[66:69]
	s_setprio 0
	s_barrier
	s_add_i32 s69, s53, s3
	v_lshl_add_u64 v[224:225], s[30:31], 0, v[134:135]
	s_mov_b32 m0, s69
	ds_read_b128 v[192:195], v158 offset:16384
	ds_read_b128 v[196:199], v158 offset:17408
	ds_read_b128 v[200:203], v158 offset:18432
	ds_read_b128 v[204:207], v158 offset:19456
	ds_read_b128 v[208:211], v158 offset:20480
	ds_read_b128 v[212:215], v158 offset:21504
	ds_read_b128 v[216:219], v158 offset:22528
	ds_read_b128 v[220:223], v158 offset:23552
	global_load_lds_dwordx4 v[224:225], off
	s_add_i32 m0, s69, 0x2000
	s_add_u32 s70, s30, 0x40000
	v_lshl_add_u64 v[226:227], s[30:31], 0, v[130:131]
	s_addc_u32 s71, s31, 0
	s_add_i32 s69, s54, s3
	global_load_lds_dwordx4 v[226:227], off
	s_waitcnt vmcnt(4)
	s_waitcnt lgkmcnt(0)
	s_barrier
; #define PG8_STAGE(bufoff, gbase, voff) do { _Pragma("unroll") for (int _i = 0; _i < 2; ++_i) \
;         __builtin_amdgcn_global_load_lds((const unsigned*)((const char*)(gbase) + (voff)[_i]), (PG8_LAS unsigned*)(lds + (bufoff) + ldsw + _i * 8192), 16, 0, 0); } while (0)
; #define PG8_LDA(dst, b, h) do { _Pragma("unroll") for (int m = 0; m < 4; ++m) _Pragma("unroll") for (int k = 0; k < 2; ++k) dst[m][k] = *(const PG8_LAS bf16x8*)(lds + PG8_SA(b, h) + aoff + m * 2048 + k * 1024); } while (0)
; #define PG8_LDB(dst, b, h) do { _Pragma("unroll") for (int n = 0; n < 2; ++n) _Pragma("unroll") for (int k = 0; k < 2; ++k) dst[n][k] = *(const PG8_LAS bf16x8*)(lds + PG8_SB(b, h) + boff + n * 2048 + k * 1024); } while (0)
; #define PG8_MMA(ai, bj, At, Bt) do { __builtin_amdgcn_s_setprio(1); _Pragma("unroll") for (int m = 0; m < 4; ++m) _Pragma("unroll") for (int n = 0; n < 2; ++n) _Pragma("unroll") for (int k = 0; k < 2; ++k) \
;         acc[ai][bj][m][n] = __builtin_amdgcn_mfma_f32_16x16x32_bf16(Bt[n][k], At[m][k], acc[ai][bj][m][n], 0, 0, 0); __builtin_amdgcn_s_setprio(0); } while (0)
; #define PG8_WAIT_V(n) asm volatile("s_waitcnt vmcnt(" #n ")" ::: "memory")
; #define PG8_WAIT_L(n) asm volatile("s_waitcnt lgkmcnt(" #n ")" ::: "memory")
; #define PG8_BAR __builtin_amdgcn_s_barrier()
; #define PG8_SCHED __builtin_amdgcn_sched_barrier(0)
; template <class Epi, class Sched, bool ALIGN_EPI = false, bool SP2 = false, bool AGM = false  >
; __device__ __forceinline__ void gemm_phase(PG8_LAS unsigned char* lds, const Gemm g, const Sched& S, const Epi& E) {
;     ...
;             PG8_LDA(At, 0, 1); PG8_STAGE(PG8_SB(0, 0), b2, voffB); PG8_STAGE(PG8_SB(0, 1), b2 + hstep, voffB); PG8_STAGE(PG8_SA(0, 0), a2, voffA);
;             PG8_WAIT_V(8); PG8_WAIT_L(0); PG8_BAR; PG8_MMA(1, 0, At, B0); PG8_MMA(1, 1, At, B1); PG8_BAR; PG8_SCHED;
;             PG8_LDB(B0, 1, 0); PG8_LDB(B1, 1, 1); PG8_SCHED; PG8_LDA(At, 1, 0); PG8_STAGE(PG8_SA(0, 1), a2 + hstepA, voffA);
;             PG8_WAIT_V(8); PG8_WAIT_L(0); PG8_BAR; PG8_MMA(0, 0, At, B0); PG8_MMA(0, 1, At, B1); PG8_BAR; PG8_SCHED;
	s_setprio 1
	s_waitcnt lgkmcnt(0)
	v_mfma_f32_16x16x32_bf16 v[62:65], v[148:151], v[192:195], 0
	v_mfma_f32_16x16x32_bf16 v[58:61], v[168:171], v[192:195], 0
	v_lshl_add_u64 v[228:229], s[70:71], 0, v[134:135]
	s_mov_b32 m0, s69
	v_lshl_add_u64 v[230:231], s[34:35], 0, v[132:133]
	global_load_lds_dwordx4 v[228:229], off
	v_mfma_f32_16x16x32_bf16 v[46:49], v[148:151], v[200:203], 0
	v_mfma_f32_16x16x32_bf16 v[42:45], v[168:171], v[200:203], 0
	v_mfma_f32_16x16x32_bf16 v[30:33], v[148:151], v[208:211], 0
	v_mfma_f32_16x16x32_bf16 v[26:29], v[168:171], v[208:211], 0
	v_mfma_f32_16x16x32_bf16 v[14:17], v[148:151], v[216:219], 0
	v_mfma_f32_16x16x32_bf16 v[10:13], v[168:171], v[216:219], 0
	v_mfma_f32_16x16x32_bf16 v[62:65], v[164:167], v[196:199], v[62:65]
	v_mfma_f32_16x16x32_bf16 v[58:61], v[172:175], v[196:199], v[58:61]
	v_lshl_add_u64 v[228:229], s[70:71], 0, v[130:131]
	s_add_i32 m0, s69, 0x2000
	s_nop 0
	global_load_lds_dwordx4 v[228:229], off
	v_mfma_f32_16x16x32_bf16 v[46:49], v[164:167], v[204:207], v[46:49]
	v_mfma_f32_16x16x32_bf16 v[42:45], v[172:175], v[204:207], v[42:45]
	v_mfma_f32_16x16x32_bf16 v[30:33], v[164:167], v[212:215], v[30:33]
	v_mfma_f32_16x16x32_bf16 v[26:29], v[172:175], v[212:215], v[26:29]
	v_mfma_f32_16x16x32_bf16 v[14:17], v[164:167], v[220:223], v[14:17]
	v_mfma_f32_16x16x32_bf16 v[10:13], v[172:175], v[220:223], v[10:13]
	s_setprio 0
	s_setprio 1
	v_mfma_f32_16x16x32_bf16 v[54:57], v[176:179], v[192:195], 0
	v_mfma_f32_16x16x32_bf16 v[50:53], v[184:187], v[192:195], 0
	v_lshl_add_u64 v[228:229], s[34:35], 0, v[136:137]
	s_mov_b32 m0, s37
	s_nop 0
	global_load_lds_dwordx4 v[228:229], off
	v_mfma_f32_16x16x32_bf16 v[38:41], v[176:179], v[200:203], 0
	v_mfma_f32_16x16x32_bf16 v[34:37], v[184:187], v[200:203], 0
	v_mfma_f32_16x16x32_bf16 v[22:25], v[176:179], v[208:211], 0
	v_mfma_f32_16x16x32_bf16 v[18:21], v[184:187], v[208:211], 0
	v_mfma_f32_16x16x32_bf16 v[6:9], v[176:179], v[216:219], 0
	v_mfma_f32_16x16x32_bf16 v[2:5], v[184:187], v[216:219], 0
	v_mfma_f32_16x16x32_bf16 v[54:57], v[180:183], v[196:199], v[54:57]
	v_mfma_f32_16x16x32_bf16 v[50:53], v[188:191], v[196:199], v[50:53]
	s_mov_b32 m0, s38
	s_nop 0
	global_load_lds_dwordx4 v[230:231], off
	v_mfma_f32_16x16x32_bf16 v[38:41], v[180:183], v[204:207], v[38:41]
	v_mfma_f32_16x16x32_bf16 v[34:37], v[188:191], v[204:207], v[34:37]
	v_mfma_f32_16x16x32_bf16 v[22:25], v[180:183], v[212:215], v[22:25]
	v_mfma_f32_16x16x32_bf16 v[18:21], v[188:191], v[212:215], v[18:21]
	v_mfma_f32_16x16x32_bf16 v[6:9], v[180:183], v[220:223], v[6:9]
	v_mfma_f32_16x16x32_bf16 v[2:5], v[188:191], v[220:223], v[2:5]
	s_setprio 0
	s_barrier
	s_add_i32 s69, 0, 0x18000
	s_add_i32 s70, 0, 0x1c000
	v_add_u32_e32 v172, s69, v155
	v_add_u32_e32 v188, s70, v155
	ds_read_b128 v[148:151], v172
	ds_read_b128 v[164:167], v172 offset:1024
	ds_read_b128 v[168:171], v172 offset:2048
	ds_read_b128 v[172:175], v172 offset:3072
	ds_read_b128 v[176:179], v188
	ds_read_b128 v[180:183], v188 offset:1024
	ds_read_b128 v[184:187], v188 offset:2048
	ds_read_b128 v[188:191], v188 offset:3072
	s_add_u32 s34, s34, 0x40000
	s_addc_u32 s35, s35, 0
	s_mov_b32 m0, s39
	v_lshl_add_u64 v[232:233], s[34:35], 0, v[136:137]
	ds_read_b128 v[192:195], v158 offset:32768
	ds_read_b128 v[196:199], v158 offset:33792
	ds_read_b128 v[200:203], v158 offset:34816
	ds_read_b128 v[204:207], v158 offset:35840
	ds_read_b128 v[208:211], v158 offset:36864
	ds_read_b128 v[212:215], v158 offset:37888
	ds_read_b128 v[216:219], v158 offset:38912
	ds_read_b128 v[220:223], v158 offset:39936
	global_load_lds_dwordx4 v[232:233], off
	v_lshl_add_u64 v[232:233], s[34:35], 0, v[132:133]
	s_mov_b32 m0, s40
	s_nop 0
	global_load_lds_dwordx4 v[232:233], off
	s_waitcnt vmcnt(8)
	s_waitcnt lgkmcnt(0)
	s_barrier
	s_setprio 1
	s_waitcnt lgkmcnt(0)
	v_mfma_f32_16x16x32_bf16 v[126:129], v[148:151], v[192:195], v[126:129]
	v_mfma_f32_16x16x32_bf16 v[122:125], v[168:171], v[192:195], v[122:125]
	v_mfma_f32_16x16x32_bf16 v[110:113], v[148:151], v[200:203], v[110:113]
	v_mfma_f32_16x16x32_bf16 v[106:109], v[168:171], v[200:203], v[106:109]
	v_mfma_f32_16x16x32_bf16 v[94:97], v[148:151], v[208:211], v[94:97]
	v_mfma_f32_16x16x32_bf16 v[90:93], v[168:171], v[208:211], v[90:93]
	v_mfma_f32_16x16x32_bf16 v[78:81], v[148:151], v[216:219], v[78:81]
	v_mfma_f32_16x16x32_bf16 v[74:77], v[168:171], v[216:219], v[74:77]
	v_mfma_f32_16x16x32_bf16 v[126:129], v[164:167], v[196:199], v[126:129]
	v_mfma_f32_16x16x32_bf16 v[122:125], v[172:175], v[196:199], v[122:125]
	v_mfma_f32_16x16x32_bf16 v[110:113], v[164:167], v[204:207], v[110:113]
	v_mfma_f32_16x16x32_bf16 v[106:109], v[172:175], v[204:207], v[106:109]
	v_mfma_f32_16x16x32_bf16 v[94:97], v[164:167], v[212:215], v[94:97]
	v_mfma_f32_16x16x32_bf16 v[90:93], v[172:175], v[212:215], v[90:93]
	v_mfma_f32_16x16x32_bf16 v[78:81], v[164:167], v[220:223], v[78:81]
	v_mfma_f32_16x16x32_bf16 v[74:77], v[172:175], v[220:223], v[74:77]
	s_setprio 0
	s_setprio 1
	v_mfma_f32_16x16x32_bf16 v[118:121], v[176:179], v[192:195], v[118:121]
	v_mfma_f32_16x16x32_bf16 v[114:117], v[184:187], v[192:195], v[114:117]
	v_mfma_f32_16x16x32_bf16 v[102:105], v[176:179], v[200:203], v[102:105]
	v_mfma_f32_16x16x32_bf16 v[98:101], v[184:187], v[200:203], v[98:101]
	v_mfma_f32_16x16x32_bf16 v[86:89], v[176:179], v[208:211], v[86:89]
	v_mfma_f32_16x16x32_bf16 v[82:85], v[184:187], v[208:211], v[82:85]
	v_mfma_f32_16x16x32_bf16 v[70:73], v[176:179], v[216:219], v[70:73]
	v_mfma_f32_16x16x32_bf16 v[66:69], v[184:187], v[216:219], v[66:69]
	v_mfma_f32_16x16x32_bf16 v[118:121], v[180:183], v[196:199], v[118:121]
	v_mfma_f32_16x16x32_bf16 v[114:117], v[188:191], v[196:199], v[114:117]
	v_mfma_f32_16x16x32_bf16 v[102:105], v[180:183], v[204:207], v[102:105]
	v_mfma_f32_16x16x32_bf16 v[98:101], v[188:191], v[204:207], v[98:101]
	v_mfma_f32_16x16x32_bf16 v[86:89], v[180:183], v[212:215], v[86:89]
	v_mfma_f32_16x16x32_bf16 v[82:85], v[188:191], v[212:215], v[82:85]
	v_mfma_f32_16x16x32_bf16 v[70:73], v[180:183], v[220:223], v[70:73]
	v_mfma_f32_16x16x32_bf16 v[66:69], v[188:191], v[220:223], v[66:69]
	s_setprio 0
	s_barrier
; #define PG8_STAGE(bufoff, gbase, voff) do { _Pragma("unroll") for (int _i = 0; _i < 2; ++_i) \
;         __builtin_amdgcn_global_load_lds((const unsigned*)((const char*)(gbase) + (voff)[_i]), (PG8_LAS unsigned*)(lds + (bufoff) + ldsw + _i * 8192), 16, 0, 0); } while (0)
; #define PG8_LDA(dst, b, h) do { _Pragma("unroll") for (int m = 0; m < 4; ++m) _Pragma("unroll") for (int k = 0; k < 2; ++k) dst[m][k] = *(const PG8_LAS bf16x8*)(lds + PG8_SA(b, h) + aoff + m * 2048 + k * 1024); } while (0)
; #define PG8_LDB(dst, b, h) do { _Pragma("unroll") for (int n = 0; n < 2; ++n) _Pragma("unroll") for (int k = 0; k < 2; ++k) dst[n][k] = *(const PG8_LAS bf16x8*)(lds + PG8_SB(b, h) + boff + n * 2048 + k * 1024); } while (0)
; #define PG8_MMA(ai, bj, At, Bt) do { __builtin_amdgcn_s_setprio(1); _Pragma("unroll") for (int m = 0; m < 4; ++m) _Pragma("unroll") for (int n = 0; n < 2; ++n) _Pragma("unroll") for (int k = 0; k < 2; ++k) \
;         acc[ai][bj][m][n] = __builtin_amdgcn_mfma_f32_16x16x32_bf16(Bt[n][k], At[m][k], acc[ai][bj][m][n], 0, 0, 0); __builtin_amdgcn_s_setprio(0); } while (0)
; #define PG8_BAR __builtin_amdgcn_s_barrier()
; template <class Epi, class Sched, bool ALIGN_EPI = false, bool SP2 = false, bool AGM = false  >
; __device__ __forceinline__ void gemm_phase(PG8_LAS unsigned char* lds, const Gemm g, const Sched& S, const Epi& E) {
;     ...
;             PG8_LDB(B0, 0, 0); PG8_LDB(B1, 0, 1); PG8_SCHED; PG8_LDA(At, 0, 0); PG8_STAGE(PG8_SA(1, 1), a1 + hstepA, voffA);
;             PG8_WAIT_V(8); PG8_WAIT_L(0); PG8_BAR; PG8_MMA(0, 0, At, B0); PG8_MMA(0, 1, At, B1); PG8_BAR; PG8_SCHED;
;             PG8_LDA(At, 0, 1); PG8_STAGE(PG8_SB(0, 0), b2, voffB); PG8_STAGE(PG8_SB(0, 1), b2 + hstep, voffB); PG8_STAGE(PG8_SA(0, 0), a2, voffA);
;             PG8_WAIT_V(8); PG8_WAIT_L(0); PG8_BAR; PG8_MMA(1, 0, At, B0); PG8_MMA(1, 1, At, B1); PG8_BAR; PG8_SCHED;
;             PG8_LDB(B0, 1, 0); PG8_LDB(B1, 1, 1); PG8_SCHED; PG8_LDA(At, 1, 0); PG8_STAGE(PG8_SA(0, 1), a2 + hstepA, voffA);
;             PG8_WAIT_V(8); PG8_WAIT_L(0); PG8_BAR; PG8_MMA(0, 0, At, B0); PG8_MMA(0, 1, At, B1); PG8_BAR; PG8_SCHED;
;             PG8_LDA(At, 1, 1); PG8_STAGE(PG8_SB(1, 0), b3, voffB); PG8_STAGE(PG8_SB(1, 1), b3 + hstep, voffB); PG8_STAGE(PG8_SA(1, 0), a3, voffA);
;             PG8_WAIT_V(8); PG8_WAIT_L(0); PG8_BAR; PG8_MMA(1, 0, At, B0); PG8_MMA(1, 1, At, B1); PG8_BAR; PG8_SCHED;
	s_add_i32 s34, s69, s3
	v_lshl_add_u64 v[224:225], v[224:225], 0, s[16:17]
	s_mov_b32 m0, s34
	ds_read_b128 v[192:195], v158 offset:49152
	ds_read_b128 v[196:199], v158 offset:50176
	ds_read_b128 v[200:203], v158 offset:51200
	ds_read_b128 v[204:207], v158 offset:52224
	ds_read_b128 v[208:211], v158 offset:53248
	ds_read_b128 v[212:215], v158 offset:54272
	ds_read_b128 v[216:219], v158 offset:55296
	ds_read_b128 v[220:223], v158 offset:56320
	global_load_lds_dwordx4 v[224:225], off
	s_add_i32 m0, s34, 0x2000
	s_add_u32 s30, s30, 0x40080
	v_lshl_add_u64 v[224:225], v[226:227], 0, s[16:17]
	s_addc_u32 s31, s31, 0
	s_add_i32 s34, s70, s3
	global_load_lds_dwordx4 v[224:225], off
	s_waitcnt vmcnt(4)
	s_waitcnt lgkmcnt(0)
	s_barrier
	s_setprio 1
	s_waitcnt lgkmcnt(0)
	v_mfma_f32_16x16x32_bf16 v[62:65], v[148:151], v[192:195], v[62:65]
	v_mfma_f32_16x16x32_bf16 v[58:61], v[168:171], v[192:195], v[58:61]
	v_lshl_add_u64 v[224:225], s[30:31], 0, v[134:135]
	s_mov_b32 m0, s34
	s_nop 0
	global_load_lds_dwordx4 v[224:225], off
	v_mfma_f32_16x16x32_bf16 v[46:49], v[148:151], v[200:203], v[46:49]
	v_mfma_f32_16x16x32_bf16 v[42:45], v[168:171], v[200:203], v[42:45]
	v_mfma_f32_16x16x32_bf16 v[30:33], v[148:151], v[208:211], v[30:33]
	v_mfma_f32_16x16x32_bf16 v[26:29], v[168:171], v[208:211], v[26:29]
	v_mfma_f32_16x16x32_bf16 v[14:17], v[148:151], v[216:219], v[14:17]
	v_mfma_f32_16x16x32_bf16 v[10:13], v[168:171], v[216:219], v[10:13]
	v_mfma_f32_16x16x32_bf16 v[62:65], v[164:167], v[196:199], v[62:65]
	v_mfma_f32_16x16x32_bf16 v[58:61], v[172:175], v[196:199], v[58:61]
	v_lshl_add_u64 v[224:225], s[30:31], 0, v[130:131]
	s_add_i32 m0, s34, 0x2000
	s_nop 0
	global_load_lds_dwordx4 v[224:225], off
	v_mfma_f32_16x16x32_bf16 v[46:49], v[164:167], v[204:207], v[46:49]
	v_mfma_f32_16x16x32_bf16 v[42:45], v[172:175], v[204:207], v[42:45]
	v_mfma_f32_16x16x32_bf16 v[30:33], v[164:167], v[212:215], v[30:33]
	v_mfma_f32_16x16x32_bf16 v[26:29], v[172:175], v[212:215], v[26:29]
	v_mfma_f32_16x16x32_bf16 v[14:17], v[164:167], v[220:223], v[14:17]
	v_mfma_f32_16x16x32_bf16 v[10:13], v[172:175], v[220:223], v[10:13]
	s_setprio 0
	s_setprio 1
	v_mfma_f32_16x16x32_bf16 v[54:57], v[176:179], v[192:195], v[54:57]
	v_mfma_f32_16x16x32_bf16 v[50:53], v[184:187], v[192:195], v[50:53]
	v_lshl_add_u64 v[224:225], v[228:229], 0, s[16:17]
	s_mov_b32 m0, s43
	s_nop 0
	global_load_lds_dwordx4 v[224:225], off
	v_mfma_f32_16x16x32_bf16 v[38:41], v[176:179], v[200:203], v[38:41]
	v_mfma_f32_16x16x32_bf16 v[34:37], v[184:187], v[200:203], v[34:37]
	v_mfma_f32_16x16x32_bf16 v[22:25], v[176:179], v[208:211], v[22:25]
	v_mfma_f32_16x16x32_bf16 v[18:21], v[184:187], v[208:211], v[18:21]
	v_mfma_f32_16x16x32_bf16 v[6:9], v[176:179], v[216:219], v[6:9]
	v_mfma_f32_16x16x32_bf16 v[2:5], v[184:187], v[216:219], v[2:5]
	v_mfma_f32_16x16x32_bf16 v[54:57], v[180:183], v[196:199], v[54:57]
	v_mfma_f32_16x16x32_bf16 v[50:53], v[188:191], v[196:199], v[50:53]
	v_lshl_add_u64 v[224:225], v[230:231], 0, s[16:17]
	s_mov_b32 m0, s44
	s_nop 0
	global_load_lds_dwordx4 v[224:225], off
	v_mfma_f32_16x16x32_bf16 v[38:41], v[180:183], v[204:207], v[38:41]
	v_mfma_f32_16x16x32_bf16 v[34:37], v[188:191], v[204:207], v[34:37]
	v_mfma_f32_16x16x32_bf16 v[22:25], v[180:183], v[212:215], v[22:25]
	v_mfma_f32_16x16x32_bf16 v[18:21], v[188:191], v[212:215], v[18:21]
	v_mfma_f32_16x16x32_bf16 v[6:9], v[180:183], v[220:223], v[6:9]
	v_mfma_f32_16x16x32_bf16 v[2:5], v[188:191], v[220:223], v[2:5]
	s_setprio 0
	s_barrier
	s_add_i32 s68, s68, 2
	s_add_u32 s28, s28, 0x100
	s_addc_u32 s29, s29, 0
	s_add_u32 s66, s66, 0x100
	s_addc_u32 s67, s67, 0
	s_cmp_gt_u32 s68, 13
	s_cbranch_scc1 .Lpeel_done_p6
	.p2align	6
.LBB0_877:
	ds_read_b128 v[148:151], v156
	ds_read_b128 v[164:167], v156 offset:1024
	ds_read_b128 v[168:171], v156 offset:2048
	ds_read_b128 v[172:175], v156 offset:3072
	ds_read_b128 v[176:179], v157
	ds_read_b128 v[180:183], v157 offset:1024
	ds_read_b128 v[184:187], v157 offset:2048
	ds_read_b128 v[188:191], v157 offset:3072
	s_add_u32 s30, s28, 0xfffc0080
	s_addc_u32 s31, s29, -1
	s_cmp_eq_u32 s68, 12
	s_cselect_b32 s35, s23, s31
	s_cselect_b32 s34, s64, s30
	s_cselect_b32 s31, s21, s67
	s_cselect_b32 s30, s65, s66
	v_lshl_add_u64 v[224:225], s[28:29], 0, v[140:141]
	s_add_i32 m0, s37, 0xc000
	ds_read_b128 v[192:195], v158
	ds_read_b128 v[196:199], v158 offset:1024
	ds_read_b128 v[200:203], v158 offset:2048
	ds_read_b128 v[204:207], v158 offset:3072
	ds_read_b128 v[208:211], v158 offset:4096
	ds_read_b128 v[212:215], v158 offset:5120
	ds_read_b128 v[216:219], v158 offset:6144
	ds_read_b128 v[220:223], v158 offset:7168
	global_load_lds_dwordx4 v[224:225], off
	v_lshl_add_u64 v[224:225], s[28:29], 0, v[142:143]
	s_add_i32 m0, s37, 0xe000
	s_nop 0
	global_load_lds_dwordx4 v[224:225], off
	s_waitcnt vmcnt(8)
	s_waitcnt lgkmcnt(0)
	s_barrier
; #define PG8_STAGE(bufoff, gbase, voff) do { _Pragma("unroll") for (int _i = 0; _i < 2; ++_i) \
;         __builtin_amdgcn_global_load_lds((const unsigned*)((const char*)(gbase) + (voff)[_i]), (PG8_LAS unsigned*)(lds + (bufoff) + ldsw + _i * 8192), 16, 0, 0); } while (0)
; #define PG8_LDA(dst, b, h) do { _Pragma("unroll") for (int m = 0; m < 4; ++m) _Pragma("unroll") for (int k = 0; k < 2; ++k) dst[m][k] = *(const PG8_LAS bf16x8*)(lds + PG8_SA(b, h) + aoff + m * 2048 + k * 1024); } while (0)
; #define PG8_MMA(ai, bj, At, Bt) do { __builtin_amdgcn_s_setprio(1); _Pragma("unroll") for (int m = 0; m < 4; ++m) _Pragma("unroll") for (int n = 0; n < 2; ++n) _Pragma("unroll") for (int k = 0; k < 2; ++k) \
;         acc[ai][bj][m][n] = __builtin_amdgcn_mfma_f32_16x16x32_bf16(Bt[n][k], At[m][k], acc[ai][bj][m][n], 0, 0, 0); __builtin_amdgcn_s_setprio(0); } while (0)
; #define PG8_WAIT_V(n) asm volatile("s_waitcnt vmcnt(" #n ")" ::: "memory")
; #define PG8_WAIT_L(n) asm volatile("s_waitcnt lgkmcnt(" #n ")" ::: "memory")
; #define PG8_BAR __builtin_amdgcn_s_barrier()
; #define PG8_SCHED __builtin_amdgcn_sched_barrier(0)
; template <class Epi, class Sched, bool ALIGN_EPI = false, bool SP2 = false, bool AGM = false  >
; __device__ __forceinline__ void gemm_phase(PG8_LAS unsigned char* lds, const Gemm g, const Sched& S, const Epi& E) {
;     ...
;             PG8_WAIT_V(8); PG8_WAIT_L(0); PG8_BAR; PG8_MMA(0, 0, At, B0); PG8_MMA(0, 1, At, B1); PG8_BAR; PG8_SCHED;
;             PG8_LDA(At, 0, 1); PG8_STAGE(PG8_SB(0, 0), b2, voffB); PG8_STAGE(PG8_SB(0, 1), b2 + hstep, voffB); PG8_STAGE(PG8_SA(0, 0), a2, voffA);
;             PG8_WAIT_V(8); PG8_WAIT_L(0); PG8_BAR; PG8_MMA(1, 0, At, B0); PG8_MMA(1, 1, At, B1); PG8_BAR; PG8_SCHED;
	s_setprio 1
	s_waitcnt lgkmcnt(0)
	v_mfma_f32_16x16x32_bf16 v[126:129], v[148:151], v[192:195], v[126:129]
	v_mfma_f32_16x16x32_bf16 v[122:125], v[168:171], v[192:195], v[122:125]
	v_mfma_f32_16x16x32_bf16 v[110:113], v[148:151], v[200:203], v[110:113]
	v_mfma_f32_16x16x32_bf16 v[106:109], v[168:171], v[200:203], v[106:109]
	v_mfma_f32_16x16x32_bf16 v[94:97], v[148:151], v[208:211], v[94:97]
	v_mfma_f32_16x16x32_bf16 v[90:93], v[168:171], v[208:211], v[90:93]
	v_mfma_f32_16x16x32_bf16 v[78:81], v[148:151], v[216:219], v[78:81]
	v_mfma_f32_16x16x32_bf16 v[74:77], v[168:171], v[216:219], v[74:77]
	v_mfma_f32_16x16x32_bf16 v[126:129], v[164:167], v[196:199], v[126:129]
	v_mfma_f32_16x16x32_bf16 v[122:125], v[172:175], v[196:199], v[122:125]
	v_mfma_f32_16x16x32_bf16 v[110:113], v[164:167], v[204:207], v[110:113]
	v_mfma_f32_16x16x32_bf16 v[106:109], v[172:175], v[204:207], v[106:109]
	v_mfma_f32_16x16x32_bf16 v[94:97], v[164:167], v[212:215], v[94:97]
	v_mfma_f32_16x16x32_bf16 v[90:93], v[172:175], v[212:215], v[90:93]
	v_mfma_f32_16x16x32_bf16 v[78:81], v[164:167], v[220:223], v[78:81]
	v_mfma_f32_16x16x32_bf16 v[74:77], v[172:175], v[220:223], v[74:77]
	s_setprio 0
	s_setprio 1
	v_mfma_f32_16x16x32_bf16 v[118:121], v[176:179], v[192:195], v[118:121]
	v_mfma_f32_16x16x32_bf16 v[114:117], v[184:187], v[192:195], v[114:117]
	v_mfma_f32_16x16x32_bf16 v[102:105], v[176:179], v[200:203], v[102:105]
	v_mfma_f32_16x16x32_bf16 v[98:101], v[184:187], v[200:203], v[98:101]
	v_mfma_f32_16x16x32_bf16 v[86:89], v[176:179], v[208:211], v[86:89]
	v_mfma_f32_16x16x32_bf16 v[82:85], v[184:187], v[208:211], v[82:85]
	v_mfma_f32_16x16x32_bf16 v[70:73], v[176:179], v[216:219], v[70:73]
	v_mfma_f32_16x16x32_bf16 v[66:69], v[184:187], v[216:219], v[66:69]
	v_mfma_f32_16x16x32_bf16 v[118:121], v[180:183], v[196:199], v[118:121]
	v_mfma_f32_16x16x32_bf16 v[114:117], v[188:191], v[196:199], v[114:117]
	v_mfma_f32_16x16x32_bf16 v[102:105], v[180:183], v[204:207], v[102:105]
	v_mfma_f32_16x16x32_bf16 v[98:101], v[188:191], v[204:207], v[98:101]
	v_mfma_f32_16x16x32_bf16 v[86:89], v[180:183], v[212:215], v[86:89]
	v_mfma_f32_16x16x32_bf16 v[82:85], v[188:191], v[212:215], v[82:85]
	v_mfma_f32_16x16x32_bf16 v[70:73], v[180:183], v[220:223], v[70:73]
	v_mfma_f32_16x16x32_bf16 v[66:69], v[188:191], v[220:223], v[66:69]
	s_setprio 0
	s_barrier
	s_add_i32 s69, s53, s3
	v_lshl_add_u64 v[224:225], s[30:31], 0, v[134:135]
	s_mov_b32 m0, s69
	ds_read_b128 v[192:195], v158 offset:16384
	ds_read_b128 v[196:199], v158 offset:17408
	ds_read_b128 v[200:203], v158 offset:18432
	ds_read_b128 v[204:207], v158 offset:19456
	ds_read_b128 v[208:211], v158 offset:20480
	ds_read_b128 v[212:215], v158 offset:21504
	ds_read_b128 v[216:219], v158 offset:22528
	ds_read_b128 v[220:223], v158 offset:23552
	global_load_lds_dwordx4 v[224:225], off
	s_add_i32 m0, s69, 0x2000
	s_add_u32 s70, s30, 0x40000
	v_lshl_add_u64 v[226:227], s[30:31], 0, v[130:131]
	s_addc_u32 s71, s31, 0
	s_add_i32 s69, s54, s3
	global_load_lds_dwordx4 v[226:227], off
	s_waitcnt vmcnt(4)
	s_waitcnt lgkmcnt(0)
	s_barrier
	s_setprio 1
	s_waitcnt lgkmcnt(0)
	v_mfma_f32_16x16x32_bf16 v[62:65], v[148:151], v[192:195], v[62:65]
	v_mfma_f32_16x16x32_bf16 v[58:61], v[168:171], v[192:195], v[58:61]
	v_lshl_add_u64 v[228:229], s[70:71], 0, v[134:135]
	s_mov_b32 m0, s69
	v_lshl_add_u64 v[230:231], s[34:35], 0, v[132:133]
	global_load_lds_dwordx4 v[228:229], off
	v_mfma_f32_16x16x32_bf16 v[46:49], v[148:151], v[200:203], v[46:49]
	v_mfma_f32_16x16x32_bf16 v[42:45], v[168:171], v[200:203], v[42:45]
	v_mfma_f32_16x16x32_bf16 v[30:33], v[148:151], v[208:211], v[30:33]
	v_mfma_f32_16x16x32_bf16 v[26:29], v[168:171], v[208:211], v[26:29]
	v_mfma_f32_16x16x32_bf16 v[14:17], v[148:151], v[216:219], v[14:17]
	v_mfma_f32_16x16x32_bf16 v[10:13], v[168:171], v[216:219], v[10:13]
	v_mfma_f32_16x16x32_bf16 v[62:65], v[164:167], v[196:199], v[62:65]
	v_mfma_f32_16x16x32_bf16 v[58:61], v[172:175], v[196:199], v[58:61]
	v_lshl_add_u64 v[228:229], s[70:71], 0, v[130:131]
	s_add_i32 m0, s69, 0x2000
	s_nop 0
	global_load_lds_dwordx4 v[228:229], off
	v_mfma_f32_16x16x32_bf16 v[46:49], v[164:167], v[204:207], v[46:49]
	v_mfma_f32_16x16x32_bf16 v[42:45], v[172:175], v[204:207], v[42:45]
	v_mfma_f32_16x16x32_bf16 v[30:33], v[164:167], v[212:215], v[30:33]
	v_mfma_f32_16x16x32_bf16 v[26:29], v[172:175], v[212:215], v[26:29]
	v_mfma_f32_16x16x32_bf16 v[14:17], v[164:167], v[220:223], v[14:17]
	v_mfma_f32_16x16x32_bf16 v[10:13], v[172:175], v[220:223], v[10:13]
	s_setprio 0
	s_setprio 1
	v_mfma_f32_16x16x32_bf16 v[54:57], v[176:179], v[192:195], v[54:57]
	v_mfma_f32_16x16x32_bf16 v[50:53], v[184:187], v[192:195], v[50:53]
	v_lshl_add_u64 v[228:229], s[34:35], 0, v[136:137]
	s_mov_b32 m0, s37
	s_nop 0
	global_load_lds_dwordx4 v[228:229], off
	v_mfma_f32_16x16x32_bf16 v[38:41], v[176:179], v[200:203], v[38:41]
	v_mfma_f32_16x16x32_bf16 v[34:37], v[184:187], v[200:203], v[34:37]
	v_mfma_f32_16x16x32_bf16 v[22:25], v[176:179], v[208:211], v[22:25]
	v_mfma_f32_16x16x32_bf16 v[18:21], v[184:187], v[208:211], v[18:21]
	v_mfma_f32_16x16x32_bf16 v[6:9], v[176:179], v[216:219], v[6:9]
	v_mfma_f32_16x16x32_bf16 v[2:5], v[184:187], v[216:219], v[2:5]
	v_mfma_f32_16x16x32_bf16 v[54:57], v[180:183], v[196:199], v[54:57]
	v_mfma_f32_16x16x32_bf16 v[50:53], v[188:191], v[196:199], v[50:53]
	s_mov_b32 m0, s38
	s_nop 0
	global_load_lds_dwordx4 v[230:231], off
	v_mfma_f32_16x16x32_bf16 v[38:41], v[180:183], v[204:207], v[38:41]
	v_mfma_f32_16x16x32_bf16 v[34:37], v[188:191], v[204:207], v[34:37]
	v_mfma_f32_16x16x32_bf16 v[22:25], v[180:183], v[212:215], v[22:25]
	v_mfma_f32_16x16x32_bf16 v[18:21], v[188:191], v[212:215], v[18:21]
	v_mfma_f32_16x16x32_bf16 v[6:9], v[180:183], v[220:223], v[6:9]
	v_mfma_f32_16x16x32_bf16 v[2:5], v[188:191], v[220:223], v[2:5]
	s_setprio 0
	s_barrier
; #define PG8_STAGE(bufoff, gbase, voff) do { _Pragma("unroll") for (int _i = 0; _i < 2; ++_i) \
;         __builtin_amdgcn_global_load_lds((const unsigned*)((const char*)(gbase) + (voff)[_i]), (PG8_LAS unsigned*)(lds + (bufoff) + ldsw + _i * 8192), 16, 0, 0); } while (0)
; #define PG8_LDA(dst, b, h) do { _Pragma("unroll") for (int m = 0; m < 4; ++m) _Pragma("unroll") for (int k = 0; k < 2; ++k) dst[m][k] = *(const PG8_LAS bf16x8*)(lds + PG8_SA(b, h) + aoff + m * 2048 + k * 1024); } while (0)
; #define PG8_LDB(dst, b, h) do { _Pragma("unroll") for (int n = 0; n < 2; ++n) _Pragma("unroll") for (int k = 0; k < 2; ++k) dst[n][k] = *(const PG8_LAS bf16x8*)(lds + PG8_SB(b, h) + boff + n * 2048 + k * 1024); } while (0)
; #define PG8_MMA(ai, bj, At, Bt) do { __builtin_amdgcn_s_setprio(1); _Pragma("unroll") for (int m = 0; m < 4; ++m) _Pragma("unroll") for (int n = 0; n < 2; ++n) _Pragma("unroll") for (int k = 0; k < 2; ++k) \
;         acc[ai][bj][m][n] = __builtin_amdgcn_mfma_f32_16x16x32_bf16(Bt[n][k], At[m][k], acc[ai][bj][m][n], 0, 0, 0); __builtin_amdgcn_s_setprio(0); } while (0)
; #define PG8_WAIT_V(n) asm volatile("s_waitcnt vmcnt(" #n ")" ::: "memory")
; #define PG8_WAIT_L(n) asm volatile("s_waitcnt lgkmcnt(" #n ")" ::: "memory")
; #define PG8_BAR __builtin_amdgcn_s_barrier()
; #define PG8_SCHED __builtin_amdgcn_sched_barrier(0)
; template <class Epi, class Sched, bool ALIGN_EPI = false, bool SP2 = false, bool AGM = false  >
; __device__ __forceinline__ void gemm_phase(PG8_LAS unsigned char* lds, const Gemm g, const Sched& S, const Epi& E) {
;     ...
;             PG8_LDB(B0, 1, 0); PG8_LDB(B1, 1, 1); PG8_SCHED; PG8_LDA(At, 1, 0); PG8_STAGE(PG8_SA(0, 1), a2 + hstepA, voffA);
;             PG8_WAIT_V(8); PG8_WAIT_L(0); PG8_BAR; PG8_MMA(0, 0, At, B0); PG8_MMA(0, 1, At, B1); PG8_BAR; PG8_SCHED;
	s_add_i32 s69, 0, 0x18000
	s_add_i32 s70, 0, 0x1c000
	v_add_u32_e32 v172, s69, v155
	v_add_u32_e32 v188, s70, v155
	ds_read_b128 v[148:151], v172
	ds_read_b128 v[164:167], v172 offset:1024
	ds_read_b128 v[168:171], v172 offset:2048
	ds_read_b128 v[172:175], v172 offset:3072
	ds_read_b128 v[176:179], v188
	ds_read_b128 v[180:183], v188 offset:1024
	ds_read_b128 v[184:187], v188 offset:2048
	ds_read_b128 v[188:191], v188 offset:3072
	s_add_u32 s34, s34, 0x40000
	s_addc_u32 s35, s35, 0
	s_mov_b32 m0, s39
	v_lshl_add_u64 v[232:233], s[34:35], 0, v[136:137]
	ds_read_b128 v[192:195], v158 offset:32768
	ds_read_b128 v[196:199], v158 offset:33792
	ds_read_b128 v[200:203], v158 offset:34816
	ds_read_b128 v[204:207], v158 offset:35840
	ds_read_b128 v[208:211], v158 offset:36864
	ds_read_b128 v[212:215], v158 offset:37888
	ds_read_b128 v[216:219], v158 offset:38912
	ds_read_b128 v[220:223], v158 offset:39936
	global_load_lds_dwordx4 v[232:233], off
	v_lshl_add_u64 v[232:233], s[34:35], 0, v[132:133]
	s_mov_b32 m0, s40
	s_nop 0
	global_load_lds_dwordx4 v[232:233], off
	s_waitcnt vmcnt(8)
	s_waitcnt lgkmcnt(0)
	s_barrier
	s_setprio 1
	s_waitcnt lgkmcnt(0)
	v_mfma_f32_16x16x32_bf16 v[126:129], v[148:151], v[192:195], v[126:129]
	v_mfma_f32_16x16x32_bf16 v[122:125], v[168:171], v[192:195], v[122:125]
	v_mfma_f32_16x16x32_bf16 v[110:113], v[148:151], v[200:203], v[110:113]
	v_mfma_f32_16x16x32_bf16 v[106:109], v[168:171], v[200:203], v[106:109]
	v_mfma_f32_16x16x32_bf16 v[94:97], v[148:151], v[208:211], v[94:97]
	v_mfma_f32_16x16x32_bf16 v[90:93], v[168:171], v[208:211], v[90:93]
	v_mfma_f32_16x16x32_bf16 v[78:81], v[148:151], v[216:219], v[78:81]
	v_mfma_f32_16x16x32_bf16 v[74:77], v[168:171], v[216:219], v[74:77]
	v_mfma_f32_16x16x32_bf16 v[126:129], v[164:167], v[196:199], v[126:129]
	v_mfma_f32_16x16x32_bf16 v[122:125], v[172:175], v[196:199], v[122:125]
	v_mfma_f32_16x16x32_bf16 v[110:113], v[164:167], v[204:207], v[110:113]
	v_mfma_f32_16x16x32_bf16 v[106:109], v[172:175], v[204:207], v[106:109]
	v_mfma_f32_16x16x32_bf16 v[94:97], v[164:167], v[212:215], v[94:97]
	v_mfma_f32_16x16x32_bf16 v[90:93], v[172:175], v[212:215], v[90:93]
	v_mfma_f32_16x16x32_bf16 v[78:81], v[164:167], v[220:223], v[78:81]
	v_mfma_f32_16x16x32_bf16 v[74:77], v[172:175], v[220:223], v[74:77]
	s_setprio 0
	s_setprio 1
	v_mfma_f32_16x16x32_bf16 v[118:121], v[176:179], v[192:195], v[118:121]
	v_mfma_f32_16x16x32_bf16 v[114:117], v[184:187], v[192:195], v[114:117]
	v_mfma_f32_16x16x32_bf16 v[102:105], v[176:179], v[200:203], v[102:105]
	v_mfma_f32_16x16x32_bf16 v[98:101], v[184:187], v[200:203], v[98:101]
	v_mfma_f32_16x16x32_bf16 v[86:89], v[176:179], v[208:211], v[86:89]
	v_mfma_f32_16x16x32_bf16 v[82:85], v[184:187], v[208:211], v[82:85]
	v_mfma_f32_16x16x32_bf16 v[70:73], v[176:179], v[216:219], v[70:73]
	v_mfma_f32_16x16x32_bf16 v[66:69], v[184:187], v[216:219], v[66:69]
	v_mfma_f32_16x16x32_bf16 v[118:121], v[180:183], v[196:199], v[118:121]
	v_mfma_f32_16x16x32_bf16 v[114:117], v[188:191], v[196:199], v[114:117]
	v_mfma_f32_16x16x32_bf16 v[102:105], v[180:183], v[204:207], v[102:105]
	v_mfma_f32_16x16x32_bf16 v[98:101], v[188:191], v[204:207], v[98:101]
	v_mfma_f32_16x16x32_bf16 v[86:89], v[180:183], v[212:215], v[86:89]
	v_mfma_f32_16x16x32_bf16 v[82:85], v[188:191], v[212:215], v[82:85]
	v_mfma_f32_16x16x32_bf16 v[70:73], v[180:183], v[220:223], v[70:73]
	v_mfma_f32_16x16x32_bf16 v[66:69], v[188:191], v[220:223], v[66:69]
	s_setprio 0
	s_barrier
; #define PG8_STAGE(bufoff, gbase, voff) do { _Pragma("unroll") for (int _i = 0; _i < 2; ++_i) \
;         __builtin_amdgcn_global_load_lds((const unsigned*)((const char*)(gbase) + (voff)[_i]), (PG8_LAS unsigned*)(lds + (bufoff) + ldsw + _i * 8192), 16, 0, 0); } while (0)
; #define PG8_LDA(dst, b, h) do { _Pragma("unroll") for (int m = 0; m < 4; ++m) _Pragma("unroll") for (int k = 0; k < 2; ++k) dst[m][k] = *(const PG8_LAS bf16x8*)(lds + PG8_SA(b, h) + aoff + m * 2048 + k * 1024); } while (0)
; #define PG8_MMA(ai, bj, At, Bt) do { __builtin_amdgcn_s_setprio(1); _Pragma("unroll") for (int m = 0; m < 4; ++m) _Pragma("unroll") for (int n = 0; n < 2; ++n) _Pragma("unroll") for (int k = 0; k < 2; ++k) \
;         acc[ai][bj][m][n] = __builtin_amdgcn_mfma_f32_16x16x32_bf16(Bt[n][k], At[m][k], acc[ai][bj][m][n], 0, 0, 0); __builtin_amdgcn_s_setprio(0); } while (0)
; #define PG8_WAIT_V(n) asm volatile("s_waitcnt vmcnt(" #n ")" ::: "memory")
; #define PG8_WAIT_L(n) asm volatile("s_waitcnt lgkmcnt(" #n ")" ::: "memory")
; #define PG8_BAR __builtin_amdgcn_s_barrier()
; #define PG8_SCHED __builtin_amdgcn_sched_barrier(0)
; template <class Epi, class Sched, bool ALIGN_EPI = false, bool SP2 = false, bool AGM = false  >
; __device__ __forceinline__ void gemm_phase(PG8_LAS unsigned char* lds, const Gemm g, const Sched& S, const Epi& E) {
;     ...
;             PG8_LDA(At, 1, 1); PG8_STAGE(PG8_SB(1, 0), b3, voffB); PG8_STAGE(PG8_SB(1, 1), b3 + hstep, voffB); PG8_STAGE(PG8_SA(1, 0), a3, voffA);
;             PG8_WAIT_V(8); PG8_WAIT_L(0); PG8_BAR; PG8_MMA(1, 0, At, B0); PG8_MMA(1, 1, At, B1); PG8_BAR; PG8_SCHED;
	s_add_i32 s34, s69, s3
	v_lshl_add_u64 v[224:225], v[224:225], 0, s[16:17]
	s_mov_b32 m0, s34
	ds_read_b128 v[192:195], v158 offset:49152
	ds_read_b128 v[196:199], v158 offset:50176
	ds_read_b128 v[200:203], v158 offset:51200
	ds_read_b128 v[204:207], v158 offset:52224
	ds_read_b128 v[208:211], v158 offset:53248
	ds_read_b128 v[212:215], v158 offset:54272
	ds_read_b128 v[216:219], v158 offset:55296
	ds_read_b128 v[220:223], v158 offset:56320
	global_load_lds_dwordx4 v[224:225], off
	s_add_i32 m0, s34, 0x2000
	s_add_u32 s30, s30, 0x40080
	v_lshl_add_u64 v[224:225], v[226:227], 0, s[16:17]
	s_addc_u32 s31, s31, 0
	s_add_i32 s34, s70, s3
	global_load_lds_dwordx4 v[224:225], off
	s_waitcnt vmcnt(4)
	s_waitcnt lgkmcnt(0)
	s_barrier
	s_setprio 1
	s_waitcnt lgkmcnt(0)
	v_mfma_f32_16x16x32_bf16 v[62:65], v[148:151], v[192:195], v[62:65]
	v_mfma_f32_16x16x32_bf16 v[58:61], v[168:171], v[192:195], v[58:61]
	v_lshl_add_u64 v[224:225], s[30:31], 0, v[134:135]
	s_mov_b32 m0, s34
	s_nop 0
	global_load_lds_dwordx4 v[224:225], off
	v_mfma_f32_16x16x32_bf16 v[46:49], v[148:151], v[200:203], v[46:49]
	v_mfma_f32_16x16x32_bf16 v[42:45], v[168:171], v[200:203], v[42:45]
	v_mfma_f32_16x16x32_bf16 v[30:33], v[148:151], v[208:211], v[30:33]
	v_mfma_f32_16x16x32_bf16 v[26:29], v[168:171], v[208:211], v[26:29]
	v_mfma_f32_16x16x32_bf16 v[14:17], v[148:151], v[216:219], v[14:17]
	v_mfma_f32_16x16x32_bf16 v[10:13], v[168:171], v[216:219], v[10:13]
	v_mfma_f32_16x16x32_bf16 v[62:65], v[164:167], v[196:199], v[62:65]
	v_mfma_f32_16x16x32_bf16 v[58:61], v[172:175], v[196:199], v[58:61]
	v_lshl_add_u64 v[224:225], s[30:31], 0, v[130:131]
	s_add_i32 m0, s34, 0x2000
	s_nop 0
	global_load_lds_dwordx4 v[224:225], off
	v_mfma_f32_16x16x32_bf16 v[46:49], v[164:167], v[204:207], v[46:49]
	v_mfma_f32_16x16x32_bf16 v[42:45], v[172:175], v[204:207], v[42:45]
	v_mfma_f32_16x16x32_bf16 v[30:33], v[164:167], v[212:215], v[30:33]
	v_mfma_f32_16x16x32_bf16 v[26:29], v[172:175], v[212:215], v[26:29]
	v_mfma_f32_16x16x32_bf16 v[14:17], v[164:167], v[220:223], v[14:17]
	v_mfma_f32_16x16x32_bf16 v[10:13], v[172:175], v[220:223], v[10:13]
	s_setprio 0
	s_setprio 1
	v_mfma_f32_16x16x32_bf16 v[54:57], v[176:179], v[192:195], v[54:57]
	v_mfma_f32_16x16x32_bf16 v[50:53], v[184:187], v[192:195], v[50:53]
	v_lshl_add_u64 v[224:225], v[228:229], 0, s[16:17]
	s_mov_b32 m0, s43
	s_nop 0
	global_load_lds_dwordx4 v[224:225], off
	v_mfma_f32_16x16x32_bf16 v[38:41], v[176:179], v[200:203], v[38:41]
	v_mfma_f32_16x16x32_bf16 v[34:37], v[184:187], v[200:203], v[34:37]
	v_mfma_f32_16x16x32_bf16 v[22:25], v[176:179], v[208:211], v[22:25]
	v_mfma_f32_16x16x32_bf16 v[18:21], v[184:187], v[208:211], v[18:21]
	v_mfma_f32_16x16x32_bf16 v[6:9], v[176:179], v[216:219], v[6:9]
	v_mfma_f32_16x16x32_bf16 v[2:5], v[184:187], v[216:219], v[2:5]
	v_mfma_f32_16x16x32_bf16 v[54:57], v[180:183], v[196:199], v[54:57]
	v_mfma_f32_16x16x32_bf16 v[50:53], v[188:191], v[196:199], v[50:53]
	v_lshl_add_u64 v[224:225], v[230:231], 0, s[16:17]
	s_mov_b32 m0, s44
	s_nop 0
	global_load_lds_dwordx4 v[224:225], off
	v_mfma_f32_16x16x32_bf16 v[38:41], v[180:183], v[204:207], v[38:41]
	v_mfma_f32_16x16x32_bf16 v[34:37], v[188:191], v[204:207], v[34:37]
	v_mfma_f32_16x16x32_bf16 v[22:25], v[180:183], v[212:215], v[22:25]
	v_mfma_f32_16x16x32_bf16 v[18:21], v[188:191], v[212:215], v[18:21]
	v_mfma_f32_16x16x32_bf16 v[6:9], v[180:183], v[220:223], v[6:9]
	v_mfma_f32_16x16x32_bf16 v[2:5], v[188:191], v[220:223], v[2:5]
	s_setprio 0
	s_barrier
	s_add_i32 s68, s68, 2
	s_add_u32 s28, s28, 0x100
	s_addc_u32 s29, s29, 0
	s_add_u32 s66, s66, 0x100
	s_addc_u32 s67, s67, 0
	s_cmp_gt_u32 s68, 13
	s_cbranch_scc0 .LBB0_877

; #define PG8_STAGE(bufoff, gbase, voff) do { _Pragma("unroll") for (int _i = 0; _i < 2; ++_i) \
;         __builtin_amdgcn_global_load_lds((const unsigned*)((const char*)(gbase) + (voff)[_i]), (PG8_LAS unsigned*)(lds + (bufoff) + ldsw + _i * 8192), 16, 0, 0); } while (0)
; #define PG8_LDA(dst, b, h) do { _Pragma("unroll") for (int m = 0; m < 4; ++m) _Pragma("unroll") for (int k = 0; k < 2; ++k) dst[m][k] = *(const PG8_LAS bf16x8*)(lds + PG8_SA(b, h) + aoff + m * 2048 + k * 1024); } while (0)
; #define PG8_LDB(dst, b, h) do { _Pragma("unroll") for (int n = 0; n < 2; ++n) _Pragma("unroll") for (int k = 0; k < 2; ++k) dst[n][k] = *(const PG8_LAS bf16x8*)(lds + PG8_SB(b, h) + boff + n * 2048 + k * 1024); } while (0)
; #define PG8_MMA(ai, bj, At, Bt) do { __builtin_amdgcn_s_setprio(1); _Pragma("unroll") for (int m = 0; m < 4; ++m) _Pragma("unroll") for (int n = 0; n < 2; ++n) _Pragma("unroll") for (int k = 0; k < 2; ++k) \
;         acc[ai][bj][m][n] = __builtin_amdgcn_mfma_f32_16x16x32_bf16(Bt[n][k], At[m][k], acc[ai][bj][m][n], 0, 0, 0); __builtin_amdgcn_s_setprio(0); } while (0)
; #define PG8_WAIT_V(n) asm volatile("s_waitcnt vmcnt(" #n ")" ::: "memory")
; #define PG8_WAIT_L(n) asm volatile("s_waitcnt lgkmcnt(" #n ")" ::: "memory")
; template <class Epi, class Sched, bool ALIGN_EPI = false, bool SP2 = false, bool AGM = false  >
; __device__ __forceinline__ void gemm_phase(PG8_LAS unsigned char* lds, const Gemm g, const Sched& S, const Epi& E) {
;     ...
;             const bool last = (t == nt - 2);
;             const char* a1 = cA + (size_t)(t + 1) * kstepA;
;             const char* a2 = last ? nA : cA + (size_t)(t + 2) * kstepA; const char* b2 = last ? nB : cB + (size_t)(t + 2) * kstep;
;             const char* a3 = a2 + kstepA; const char* b3 = b2 + kstep;
;             if (last && has_next) S.a_ready(nxt);
;             if constexpr (SP2) {
;             PG8_LDB(B0, 0, 0); PG8_LDB(B1, 0, 1); PG8_SCHED; PG8_LDA(At, 0, 0); PG8_STAGE(PG8_SA(1, 1), a1 + hstepA, voffA);
;             PG8_WAIT_V(8); PG8_WAIT_L(0); PG8_BAR; PG8_MMA(0, 0, At, B0); PG8_MMA(0, 1, At, B1); PG8_BAR; PG8_SCHED;
;             PG8_LDA(At, 0, 1); PG8_STAGE(PG8_SB(0, 0), b2, voffB); PG8_STAGE(PG8_SB(0, 1), b2 + hstep, voffB); PG8_STAGE(PG8_SA(0, 0), a2, voffA);
;             PG8_WAIT_V(8); PG8_WAIT_L(0); PG8_BAR; PG8_MMA(1, 0, At, B0); PG8_MMA(1, 1, At, B1); PG8_BAR; PG8_SCHED;
.LBB0_1068:
	ds_read_b128 v[150:153], v167
	ds_read_b128 v[156:159], v167 offset:1024
	ds_read_b128 v[160:163], v167 offset:2048
	ds_read_b128 v[176:179], v167 offset:3072
	ds_read_b128 v[180:183], v168
	ds_read_b128 v[184:187], v168 offset:1024
	ds_read_b128 v[188:191], v168 offset:2048
	ds_read_b128 v[192:195], v168 offset:3072
	s_add_u32 s34, s30, 0xfff50080
	s_addc_u32 s35, s31, -1
	s_cmp_eq_u32 s65, 40
	s_cselect_b32 s37, s13, s35
	s_cselect_b32 s36, s12, s34
	s_cselect_b32 s35, s29, s33
	s_cselect_b32 s34, s28, s5
	v_lshl_add_u64 v[164:165], s[30:31], 0, v[142:143]
	s_add_i32 m0, s39, 0xc000
	ds_read_b128 v[196:199], v169
	ds_read_b128 v[200:203], v169 offset:1024
	ds_read_b128 v[204:207], v169 offset:2048
	ds_read_b128 v[208:211], v169 offset:3072
	ds_read_b128 v[212:215], v169 offset:4096
	ds_read_b128 v[216:219], v169 offset:5120
	ds_read_b128 v[220:223], v169 offset:6144
	ds_read_b128 v[224:227], v169 offset:7168
	global_load_lds_dwordx4 v[164:165], off
	v_lshl_add_u64 v[164:165], s[30:31], 0, v[144:145]
	s_add_i32 m0, s39, 0xe000
	s_nop 0
	global_load_lds_dwordx4 v[164:165], off
	s_waitcnt vmcnt(8)
	s_waitcnt lgkmcnt(0)
	s_barrier
	s_setprio 1
	s_waitcnt lgkmcnt(0)
	v_mfma_f32_16x16x32_bf16 v[126:129], v[150:153], v[196:199], v[126:129]
	v_mfma_f32_16x16x32_bf16 v[122:125], v[160:163], v[196:199], v[122:125]
	v_mfma_f32_16x16x32_bf16 v[110:113], v[150:153], v[204:207], v[110:113]
	v_mfma_f32_16x16x32_bf16 v[106:109], v[160:163], v[204:207], v[106:109]
	v_mfma_f32_16x16x32_bf16 v[94:97], v[150:153], v[212:215], v[94:97]
	v_mfma_f32_16x16x32_bf16 v[90:93], v[160:163], v[212:215], v[90:93]
	v_mfma_f32_16x16x32_bf16 v[78:81], v[150:153], v[220:223], v[78:81]
	v_mfma_f32_16x16x32_bf16 v[74:77], v[160:163], v[220:223], v[74:77]
	v_mfma_f32_16x16x32_bf16 v[126:129], v[156:159], v[200:203], v[126:129]
	v_mfma_f32_16x16x32_bf16 v[122:125], v[176:179], v[200:203], v[122:125]
	v_mfma_f32_16x16x32_bf16 v[110:113], v[156:159], v[208:211], v[110:113]
	v_mfma_f32_16x16x32_bf16 v[106:109], v[176:179], v[208:211], v[106:109]
	v_mfma_f32_16x16x32_bf16 v[94:97], v[156:159], v[216:219], v[94:97]
	v_mfma_f32_16x16x32_bf16 v[90:93], v[176:179], v[216:219], v[90:93]
	v_mfma_f32_16x16x32_bf16 v[78:81], v[156:159], v[224:227], v[78:81]
	v_mfma_f32_16x16x32_bf16 v[74:77], v[176:179], v[224:227], v[74:77]
	s_setprio 0
	s_setprio 1
	v_mfma_f32_16x16x32_bf16 v[118:121], v[180:183], v[196:199], v[118:121]
	v_mfma_f32_16x16x32_bf16 v[114:117], v[188:191], v[196:199], v[114:117]
	v_mfma_f32_16x16x32_bf16 v[102:105], v[180:183], v[204:207], v[102:105]
	v_mfma_f32_16x16x32_bf16 v[98:101], v[188:191], v[204:207], v[98:101]
	v_mfma_f32_16x16x32_bf16 v[86:89], v[180:183], v[212:215], v[86:89]
	v_mfma_f32_16x16x32_bf16 v[82:85], v[188:191], v[212:215], v[82:85]
	v_mfma_f32_16x16x32_bf16 v[70:73], v[180:183], v[220:223], v[70:73]
	v_mfma_f32_16x16x32_bf16 v[66:69], v[188:191], v[220:223], v[66:69]
	v_mfma_f32_16x16x32_bf16 v[118:121], v[184:187], v[200:203], v[118:121]
	v_mfma_f32_16x16x32_bf16 v[114:117], v[192:195], v[200:203], v[114:117]
	v_mfma_f32_16x16x32_bf16 v[102:105], v[184:187], v[208:211], v[102:105]
	v_mfma_f32_16x16x32_bf16 v[98:101], v[192:195], v[208:211], v[98:101]
	v_mfma_f32_16x16x32_bf16 v[86:89], v[184:187], v[216:219], v[86:89]
	v_mfma_f32_16x16x32_bf16 v[82:85], v[192:195], v[216:219], v[82:85]
	v_mfma_f32_16x16x32_bf16 v[70:73], v[184:187], v[224:227], v[70:73]
	v_mfma_f32_16x16x32_bf16 v[66:69], v[192:195], v[224:227], v[66:69]
	s_setprio 0
	s_barrier
	s_add_i32 s66, s60, s38
	v_lshl_add_u64 v[164:165], s[34:35], 0, v[132:133]
	s_mov_b32 m0, s66
	ds_read_b128 v[196:199], v169 offset:16384
	ds_read_b128 v[200:203], v169 offset:17408
	ds_read_b128 v[204:207], v169 offset:18432
	ds_read_b128 v[208:211], v169 offset:19456
	ds_read_b128 v[212:215], v169 offset:20480
	ds_read_b128 v[216:219], v169 offset:21504
	ds_read_b128 v[220:223], v169 offset:22528
	ds_read_b128 v[224:227], v169 offset:23552
	global_load_lds_dwordx4 v[164:165], off
	s_add_i32 m0, s66, 0x2000
	s_add_u32 s66, s34, 0xb0000
	v_lshl_add_u64 v[228:229], s[34:35], 0, v[136:137]
	s_addc_u32 s67, s35, 0
	s_add_i32 s68, s61, s38
	global_load_lds_dwordx4 v[228:229], off
	s_waitcnt vmcnt(4)
	s_waitcnt lgkmcnt(0)
	s_barrier
	s_setprio 1
	s_waitcnt lgkmcnt(0)
	v_mfma_f32_16x16x32_bf16 v[62:65], v[150:153], v[196:199], v[62:65]
	v_mfma_f32_16x16x32_bf16 v[58:61], v[160:163], v[196:199], v[58:61]
	v_lshl_add_u64 v[230:231], s[66:67], 0, v[132:133]
	s_mov_b32 m0, s68
	v_lshl_add_u64 v[232:233], s[36:37], 0, v[134:135]
	global_load_lds_dwordx4 v[230:231], off
	v_mfma_f32_16x16x32_bf16 v[46:49], v[150:153], v[204:207], v[46:49]
	v_mfma_f32_16x16x32_bf16 v[42:45], v[160:163], v[204:207], v[42:45]
	v_mfma_f32_16x16x32_bf16 v[30:33], v[150:153], v[212:215], v[30:33]
	v_mfma_f32_16x16x32_bf16 v[26:29], v[160:163], v[212:215], v[26:29]
	v_mfma_f32_16x16x32_bf16 v[14:17], v[150:153], v[220:223], v[14:17]
	v_mfma_f32_16x16x32_bf16 v[10:13], v[160:163], v[220:223], v[10:13]
	v_mfma_f32_16x16x32_bf16 v[62:65], v[156:159], v[200:203], v[62:65]
	v_mfma_f32_16x16x32_bf16 v[58:61], v[176:179], v[200:203], v[58:61]
	v_lshl_add_u64 v[230:231], s[66:67], 0, v[136:137]
	s_add_i32 m0, s68, 0x2000
	s_nop 0
	global_load_lds_dwordx4 v[230:231], off
	v_mfma_f32_16x16x32_bf16 v[46:49], v[156:159], v[208:211], v[46:49]
	v_mfma_f32_16x16x32_bf16 v[42:45], v[176:179], v[208:211], v[42:45]
	v_mfma_f32_16x16x32_bf16 v[30:33], v[156:159], v[216:219], v[30:33]
	v_mfma_f32_16x16x32_bf16 v[26:29], v[176:179], v[216:219], v[26:29]
	v_mfma_f32_16x16x32_bf16 v[14:17], v[156:159], v[224:227], v[14:17]
	v_mfma_f32_16x16x32_bf16 v[10:13], v[176:179], v[224:227], v[10:13]
	s_setprio 0
	s_setprio 1
	v_mfma_f32_16x16x32_bf16 v[54:57], v[180:183], v[196:199], v[54:57]
	v_mfma_f32_16x16x32_bf16 v[50:53], v[188:191], v[196:199], v[50:53]
	v_lshl_add_u64 v[230:231], s[36:37], 0, v[130:131]
	s_mov_b32 m0, s39
	s_nop 0
	global_load_lds_dwordx4 v[230:231], off
	v_mfma_f32_16x16x32_bf16 v[38:41], v[180:183], v[204:207], v[38:41]
	v_mfma_f32_16x16x32_bf16 v[34:37], v[188:191], v[204:207], v[34:37]
	v_mfma_f32_16x16x32_bf16 v[22:25], v[180:183], v[212:215], v[22:25]
	v_mfma_f32_16x16x32_bf16 v[18:21], v[188:191], v[212:215], v[18:21]
	v_mfma_f32_16x16x32_bf16 v[6:9], v[180:183], v[220:223], v[6:9]
	v_mfma_f32_16x16x32_bf16 v[2:5], v[188:191], v[220:223], v[2:5]
	v_mfma_f32_16x16x32_bf16 v[54:57], v[184:187], v[200:203], v[54:57]
	v_mfma_f32_16x16x32_bf16 v[50:53], v[192:195], v[200:203], v[50:53]
	s_mov_b32 m0, s40
	s_nop 0
	global_load_lds_dwordx4 v[232:233], off
	v_mfma_f32_16x16x32_bf16 v[38:41], v[184:187], v[208:211], v[38:41]
	v_mfma_f32_16x16x32_bf16 v[34:37], v[192:195], v[208:211], v[34:37]
	v_mfma_f32_16x16x32_bf16 v[22:25], v[184:187], v[216:219], v[22:25]
	v_mfma_f32_16x16x32_bf16 v[18:21], v[192:195], v[216:219], v[18:21]
	v_mfma_f32_16x16x32_bf16 v[6:9], v[184:187], v[224:227], v[6:9]
	v_mfma_f32_16x16x32_bf16 v[2:5], v[192:195], v[224:227], v[2:5]
	s_setprio 0
	s_barrier
; #define PG8_STAGE(bufoff, gbase, voff) do { _Pragma("unroll") for (int _i = 0; _i < 2; ++_i) \
;         __builtin_amdgcn_global_load_lds((const unsigned*)((const char*)(gbase) + (voff)[_i]), (PG8_LAS unsigned*)(lds + (bufoff) + ldsw + _i * 8192), 16, 0, 0); } while (0)
; #define PG8_LDA(dst, b, h) do { _Pragma("unroll") for (int m = 0; m < 4; ++m) _Pragma("unroll") for (int k = 0; k < 2; ++k) dst[m][k] = *(const PG8_LAS bf16x8*)(lds + PG8_SA(b, h) + aoff + m * 2048 + k * 1024); } while (0)
; #define PG8_LDB(dst, b, h) do { _Pragma("unroll") for (int n = 0; n < 2; ++n) _Pragma("unroll") for (int k = 0; k < 2; ++k) dst[n][k] = *(const PG8_LAS bf16x8*)(lds + PG8_SB(b, h) + boff + n * 2048 + k * 1024); } while (0)
; #define PG8_MMA(ai, bj, At, Bt) do { __builtin_amdgcn_s_setprio(1); _Pragma("unroll") for (int m = 0; m < 4; ++m) _Pragma("unroll") for (int n = 0; n < 2; ++n) _Pragma("unroll") for (int k = 0; k < 2; ++k) \
;         acc[ai][bj][m][n] = __builtin_amdgcn_mfma_f32_16x16x32_bf16(Bt[n][k], At[m][k], acc[ai][bj][m][n], 0, 0, 0); __builtin_amdgcn_s_setprio(0); } while (0)
; #define PG8_WAIT_V(n) asm volatile("s_waitcnt vmcnt(" #n ")" ::: "memory")
; #define PG8_WAIT_L(n) asm volatile("s_waitcnt lgkmcnt(" #n ")" ::: "memory")
; #define PG8_BAR __builtin_amdgcn_s_barrier()
; #define PG8_SCHED __builtin_amdgcn_sched_barrier(0)
; template <class Epi, class Sched, bool ALIGN_EPI = false, bool SP2 = false, bool AGM = false  >
; __device__ __forceinline__ void gemm_phase(PG8_LAS unsigned char* lds, const Gemm g, const Sched& S, const Epi& E) {
;     ...
;             PG8_LDB(B0, 1, 0); PG8_LDB(B1, 1, 1); PG8_SCHED; PG8_LDA(At, 1, 0); PG8_STAGE(PG8_SA(0, 1), a2 + hstepA, voffA);
;             PG8_WAIT_V(8); PG8_WAIT_L(0); PG8_BAR; PG8_MMA(0, 0, At, B0); PG8_MMA(0, 1, At, B1); PG8_BAR; PG8_SCHED;
	s_add_i32 s66, 0, 0x18000
	s_add_i32 s67, 0, 0x1c000
	v_add_u32_e32 v176, s66, v1
	v_add_u32_e32 v192, s67, v1
	ds_read_b128 v[150:153], v176
	ds_read_b128 v[156:159], v176 offset:1024
	ds_read_b128 v[160:163], v176 offset:2048
	ds_read_b128 v[176:179], v176 offset:3072
	ds_read_b128 v[180:183], v192
	ds_read_b128 v[184:187], v192 offset:1024
	ds_read_b128 v[188:191], v192 offset:2048
	ds_read_b128 v[192:195], v192 offset:3072
	s_add_u32 s36, s36, 0xb0000
	s_addc_u32 s37, s37, 0
	s_mov_b32 m0, s41
	v_lshl_add_u64 v[234:235], s[36:37], 0, v[130:131]
	ds_read_b128 v[196:199], v169 offset:32768
	ds_read_b128 v[200:203], v169 offset:33792
	ds_read_b128 v[204:207], v169 offset:34816
	ds_read_b128 v[208:211], v169 offset:35840
	ds_read_b128 v[212:215], v169 offset:36864
	ds_read_b128 v[216:219], v169 offset:37888
	ds_read_b128 v[220:223], v169 offset:38912
	ds_read_b128 v[224:227], v169 offset:39936
	global_load_lds_dwordx4 v[234:235], off
	v_lshl_add_u64 v[234:235], s[36:37], 0, v[134:135]
	s_mov_b32 m0, s42
	s_nop 0
	global_load_lds_dwordx4 v[234:235], off
	s_waitcnt vmcnt(8)
	s_waitcnt lgkmcnt(0)
	s_barrier
	s_setprio 1
	s_waitcnt lgkmcnt(0)
	v_mfma_f32_16x16x32_bf16 v[126:129], v[150:153], v[196:199], v[126:129]
	v_mfma_f32_16x16x32_bf16 v[122:125], v[160:163], v[196:199], v[122:125]
	v_mfma_f32_16x16x32_bf16 v[110:113], v[150:153], v[204:207], v[110:113]
	v_mfma_f32_16x16x32_bf16 v[106:109], v[160:163], v[204:207], v[106:109]
	v_mfma_f32_16x16x32_bf16 v[94:97], v[150:153], v[212:215], v[94:97]
	v_mfma_f32_16x16x32_bf16 v[90:93], v[160:163], v[212:215], v[90:93]
	v_mfma_f32_16x16x32_bf16 v[78:81], v[150:153], v[220:223], v[78:81]
	v_mfma_f32_16x16x32_bf16 v[74:77], v[160:163], v[220:223], v[74:77]
	v_mfma_f32_16x16x32_bf16 v[126:129], v[156:159], v[200:203], v[126:129]
	v_mfma_f32_16x16x32_bf16 v[122:125], v[176:179], v[200:203], v[122:125]
	v_mfma_f32_16x16x32_bf16 v[110:113], v[156:159], v[208:211], v[110:113]
	v_mfma_f32_16x16x32_bf16 v[106:109], v[176:179], v[208:211], v[106:109]
	v_mfma_f32_16x16x32_bf16 v[94:97], v[156:159], v[216:219], v[94:97]
	v_mfma_f32_16x16x32_bf16 v[90:93], v[176:179], v[216:219], v[90:93]
	v_mfma_f32_16x16x32_bf16 v[78:81], v[156:159], v[224:227], v[78:81]
	v_mfma_f32_16x16x32_bf16 v[74:77], v[176:179], v[224:227], v[74:77]
	s_setprio 0
	s_setprio 1
	v_mfma_f32_16x16x32_bf16 v[118:121], v[180:183], v[196:199], v[118:121]
	v_mfma_f32_16x16x32_bf16 v[114:117], v[188:191], v[196:199], v[114:117]
	v_mfma_f32_16x16x32_bf16 v[102:105], v[180:183], v[204:207], v[102:105]
	v_mfma_f32_16x16x32_bf16 v[98:101], v[188:191], v[204:207], v[98:101]
	v_mfma_f32_16x16x32_bf16 v[86:89], v[180:183], v[212:215], v[86:89]
	v_mfma_f32_16x16x32_bf16 v[82:85], v[188:191], v[212:215], v[82:85]
	v_mfma_f32_16x16x32_bf16 v[70:73], v[180:183], v[220:223], v[70:73]
	v_mfma_f32_16x16x32_bf16 v[66:69], v[188:191], v[220:223], v[66:69]
	v_mfma_f32_16x16x32_bf16 v[118:121], v[184:187], v[200:203], v[118:121]
	v_mfma_f32_16x16x32_bf16 v[114:117], v[192:195], v[200:203], v[114:117]
	v_mfma_f32_16x16x32_bf16 v[102:105], v[184:187], v[208:211], v[102:105]
	v_mfma_f32_16x16x32_bf16 v[98:101], v[192:195], v[208:211], v[98:101]
	v_mfma_f32_16x16x32_bf16 v[86:89], v[184:187], v[216:219], v[86:89]
	v_mfma_f32_16x16x32_bf16 v[82:85], v[192:195], v[216:219], v[82:85]
	v_mfma_f32_16x16x32_bf16 v[70:73], v[184:187], v[224:227], v[70:73]
	v_mfma_f32_16x16x32_bf16 v[66:69], v[192:195], v[224:227], v[66:69]
	s_setprio 0
	s_barrier
; #define PG8_STAGE(bufoff, gbase, voff) do { _Pragma("unroll") for (int _i = 0; _i < 2; ++_i) \
;         __builtin_amdgcn_global_load_lds((const unsigned*)((const char*)(gbase) + (voff)[_i]), (PG8_LAS unsigned*)(lds + (bufoff) + ldsw + _i * 8192), 16, 0, 0); } while (0)
; #define PG8_LDA(dst, b, h) do { _Pragma("unroll") for (int m = 0; m < 4; ++m) _Pragma("unroll") for (int k = 0; k < 2; ++k) dst[m][k] = *(const PG8_LAS bf16x8*)(lds + PG8_SA(b, h) + aoff + m * 2048 + k * 1024); } while (0)
; #define PG8_MMA(ai, bj, At, Bt) do { __builtin_amdgcn_s_setprio(1); _Pragma("unroll") for (int m = 0; m < 4; ++m) _Pragma("unroll") for (int n = 0; n < 2; ++n) _Pragma("unroll") for (int k = 0; k < 2; ++k) \
;         acc[ai][bj][m][n] = __builtin_amdgcn_mfma_f32_16x16x32_bf16(Bt[n][k], At[m][k], acc[ai][bj][m][n], 0, 0, 0); __builtin_amdgcn_s_setprio(0); } while (0)
; #define PG8_WAIT_V(n) asm volatile("s_waitcnt vmcnt(" #n ")" ::: "memory")
; #define PG8_WAIT_L(n) asm volatile("s_waitcnt lgkmcnt(" #n ")" ::: "memory")
; #define PG8_BAR __builtin_amdgcn_s_barrier()
; #define PG8_SCHED __builtin_amdgcn_sched_barrier(0)
; template <class Epi, class Sched, bool ALIGN_EPI = false, bool SP2 = false, bool AGM = false  >
; __device__ __forceinline__ void gemm_phase(PG8_LAS unsigned char* lds, const Gemm g, const Sched& S, const Epi& E) {
;     ...
;             PG8_LDA(At, 1, 1); PG8_STAGE(PG8_SB(1, 0), b3, voffB); PG8_STAGE(PG8_SB(1, 1), b3 + hstep, voffB); PG8_STAGE(PG8_SA(1, 0), a3, voffA);
;             PG8_WAIT_V(8); PG8_WAIT_L(0); PG8_BAR; PG8_MMA(1, 0, At, B0); PG8_MMA(1, 1, At, B1); PG8_BAR; PG8_SCHED;
	s_add_i32 s36, s66, s38
	v_lshl_add_u64 v[164:165], v[164:165], 0, s[24:25]
	s_mov_b32 m0, s36
	ds_read_b128 v[196:199], v169 offset:49152
	ds_read_b128 v[200:203], v169 offset:50176
	ds_read_b128 v[204:207], v169 offset:51200
	ds_read_b128 v[208:211], v169 offset:52224
	ds_read_b128 v[212:215], v169 offset:53248
	ds_read_b128 v[216:219], v169 offset:54272
	ds_read_b128 v[220:223], v169 offset:55296
	ds_read_b128 v[224:227], v169 offset:56320
	global_load_lds_dwordx4 v[164:165], off
	s_add_i32 m0, s36, 0x2000
	s_add_u32 s34, s34, 0xb0080
	v_lshl_add_u64 v[164:165], v[228:229], 0, s[24:25]
	s_addc_u32 s35, s35, 0
	s_add_i32 s36, s67, s38
	global_load_lds_dwordx4 v[164:165], off
	s_waitcnt vmcnt(4)
	s_waitcnt lgkmcnt(0)
	s_barrier
	s_setprio 1
	s_waitcnt lgkmcnt(0)
	v_mfma_f32_16x16x32_bf16 v[62:65], v[150:153], v[196:199], v[62:65]
	v_mfma_f32_16x16x32_bf16 v[58:61], v[160:163], v[196:199], v[58:61]
	v_lshl_add_u64 v[164:165], s[34:35], 0, v[132:133]
	s_mov_b32 m0, s36
	s_nop 0
	global_load_lds_dwordx4 v[164:165], off
	v_mfma_f32_16x16x32_bf16 v[46:49], v[150:153], v[204:207], v[46:49]
	v_mfma_f32_16x16x32_bf16 v[42:45], v[160:163], v[204:207], v[42:45]
	v_mfma_f32_16x16x32_bf16 v[30:33], v[150:153], v[212:215], v[30:33]
	v_mfma_f32_16x16x32_bf16 v[26:29], v[160:163], v[212:215], v[26:29]
	v_mfma_f32_16x16x32_bf16 v[14:17], v[150:153], v[220:223], v[14:17]
	v_mfma_f32_16x16x32_bf16 v[10:13], v[160:163], v[220:223], v[10:13]
	v_mfma_f32_16x16x32_bf16 v[62:65], v[156:159], v[200:203], v[62:65]
	v_mfma_f32_16x16x32_bf16 v[58:61], v[176:179], v[200:203], v[58:61]
	v_lshl_add_u64 v[164:165], s[34:35], 0, v[136:137]
	s_add_i32 m0, s36, 0x2000
	s_nop 0
	global_load_lds_dwordx4 v[164:165], off
	v_mfma_f32_16x16x32_bf16 v[46:49], v[156:159], v[208:211], v[46:49]
	v_mfma_f32_16x16x32_bf16 v[42:45], v[176:179], v[208:211], v[42:45]
	v_mfma_f32_16x16x32_bf16 v[30:33], v[156:159], v[216:219], v[30:33]
	v_mfma_f32_16x16x32_bf16 v[26:29], v[176:179], v[216:219], v[26:29]
	v_mfma_f32_16x16x32_bf16 v[14:17], v[156:159], v[224:227], v[14:17]
	v_mfma_f32_16x16x32_bf16 v[10:13], v[176:179], v[224:227], v[10:13]
	s_setprio 0
	s_setprio 1
	v_mfma_f32_16x16x32_bf16 v[54:57], v[180:183], v[196:199], v[54:57]
	v_mfma_f32_16x16x32_bf16 v[50:53], v[188:191], v[196:199], v[50:53]
	v_lshl_add_u64 v[164:165], v[230:231], 0, s[24:25]
	s_mov_b32 m0, s55
	s_nop 0
	global_load_lds_dwordx4 v[164:165], off
	v_mfma_f32_16x16x32_bf16 v[38:41], v[180:183], v[204:207], v[38:41]
	v_mfma_f32_16x16x32_bf16 v[34:37], v[188:191], v[204:207], v[34:37]
	v_mfma_f32_16x16x32_bf16 v[22:25], v[180:183], v[212:215], v[22:25]
	v_mfma_f32_16x16x32_bf16 v[18:21], v[188:191], v[212:215], v[18:21]
	v_mfma_f32_16x16x32_bf16 v[6:9], v[180:183], v[220:223], v[6:9]
	v_mfma_f32_16x16x32_bf16 v[2:5], v[188:191], v[220:223], v[2:5]
	v_mfma_f32_16x16x32_bf16 v[54:57], v[184:187], v[200:203], v[54:57]
	v_mfma_f32_16x16x32_bf16 v[50:53], v[192:195], v[200:203], v[50:53]
	v_lshl_add_u64 v[164:165], v[232:233], 0, s[24:25]
	s_mov_b32 m0, s58
	s_nop 0
	global_load_lds_dwordx4 v[164:165], off
	v_mfma_f32_16x16x32_bf16 v[38:41], v[184:187], v[208:211], v[38:41]
	v_mfma_f32_16x16x32_bf16 v[34:37], v[192:195], v[208:211], v[34:37]
	v_mfma_f32_16x16x32_bf16 v[22:25], v[184:187], v[216:219], v[22:25]
	v_mfma_f32_16x16x32_bf16 v[18:21], v[192:195], v[216:219], v[18:21]
	v_mfma_f32_16x16x32_bf16 v[6:9], v[184:187], v[224:227], v[6:9]
	v_mfma_f32_16x16x32_bf16 v[2:5], v[192:195], v[224:227], v[2:5]
	s_setprio 0
	s_barrier
	s_add_i32 s65, s65, 2
	s_add_u32 s30, s30, 0x100
	s_addc_u32 s31, s31, 0
	s_add_u32 s5, s5, 0x100
	s_addc_u32 s33, s33, 0
	s_cmp_gt_u32 s65, 41
	s_cbranch_scc0 .LBB0_1068
	s_and_b64 vcc, exec, s[26:27]
	s_cbranch_vccz .LBB0_1071
	s_barrier
